# wout epilogue batched loads; sgemm16 K-loops pipelined; IEEE f32 division expansions replaced by v_rcp_f32 in activation epilogues
# speedup vs baseline: 1.0420x; 1.0123x over previous
.LBB0_41:
	s_and_b64 vcc, exec, s[8:9]
	s_cbranch_vccnz .Lwo1_srcout
	v_readlane_b32 s12, v254, 7
	v_readlane_b32 s13, v254, 8
	s_nop 3
	s_load_dwordx2 s[12:13], s[12:13], 0x0
	s_waitcnt lgkmcnt(0)
	v_lshl_add_u64 v[88:89], v[132:133], 2, s[12:13]
	s_branch .Lwo1_go
.Lwo1_srcout:
	v_mov_b32_e32 v88, v134
	v_mov_b32_e32 v89, v135
.Lwo1_go:
	v_ashrrev_i32_e32 v0, 6, v131
	v_add_u32_e32 v87, s14, v0
	v_lshlrev_b32_e32 v92, 12, v87
	v_mov_b32_e32 v93, 0
	v_mad_u32_u24 v91, v0, s33, v130
	v_lshl_add_u64 v[66:67], v[92:93], 0, v[88:89]
	global_load_dwordx4 v[140:143], v[66:67], off
	v_add_u32_e32 v92, 0x8000, v92
	v_lshl_add_u64 v[66:67], v[92:93], 0, v[88:89]
	global_load_dwordx4 v[144:147], v[66:67], off
	v_add_u32_e32 v92, 0x8000, v92
	v_lshl_add_u64 v[66:67], v[92:93], 0, v[88:89]
	global_load_dwordx4 v[148:151], v[66:67], off
	v_add_u32_e32 v92, 0x8000, v92
	v_lshl_add_u64 v[66:67], v[92:93], 0, v[88:89]
	global_load_dwordx4 v[152:155], v[66:67], off
	v_add_u32_e32 v92, 0x8000, v92
	v_lshl_add_u64 v[66:67], v[92:93], 0, v[88:89]
	global_load_dwordx4 v[156:159], v[66:67], off
	v_add_u32_e32 v92, 0x8000, v92
	v_lshl_add_u64 v[66:67], v[92:93], 0, v[88:89]
	global_load_dwordx4 v[160:163], v[66:67], off
	v_add_u32_e32 v92, 0x8000, v92
	v_lshl_add_u64 v[66:67], v[92:93], 0, v[88:89]
	global_load_dwordx4 v[164:167], v[66:67], off
	v_add_u32_e32 v92, 0x8000, v92
	v_lshl_add_u64 v[66:67], v[92:93], 0, v[88:89]
	global_load_dwordx4 v[172:175], v[66:67], off
	v_add_u32_e32 v92, 0x8000, v92
	v_lshl_add_u64 v[66:67], v[92:93], 0, v[88:89]
	global_load_dwordx4 v[176:179], v[66:67], off
	v_add_u32_e32 v92, 0x8000, v92
	v_lshl_add_u64 v[66:67], v[92:93], 0, v[88:89]
	global_load_dwordx4 v[180:183], v[66:67], off
	v_add_u32_e32 v92, 0x8000, v92
	v_lshl_add_u64 v[66:67], v[92:93], 0, v[88:89]
	global_load_dwordx4 v[184:187], v[66:67], off
	v_add_u32_e32 v92, 0x8000, v92
	v_lshl_add_u64 v[66:67], v[92:93], 0, v[88:89]
	global_load_dwordx4 v[188:191], v[66:67], off
	v_add_u32_e32 v92, 0x8000, v92
	v_lshl_add_u64 v[66:67], v[92:93], 0, v[88:89]
	global_load_dwordx4 v[192:195], v[66:67], off
	v_add_u32_e32 v92, 0x8000, v92
	v_lshl_add_u64 v[66:67], v[92:93], 0, v[88:89]
	global_load_dwordx4 v[196:199], v[66:67], off
	v_add_u32_e32 v92, 0x8000, v92
	v_lshl_add_u64 v[66:67], v[92:93], 0, v[88:89]
	global_load_dwordx4 v[220:223], v[66:67], off
	v_add_u32_e32 v92, 0x8000, v92
	v_lshl_add_u64 v[66:67], v[92:93], 0, v[88:89]
	global_load_dwordx4 v[224:227], v[66:67], off
	v_add_u32_e32 v92, 0x8000, v92
	v_add_u32_e32 v92, 0xfff80000, v92
	ds_read_b128 v[96:99], v91
	ds_read_b128 v[100:103], v91 offset:8320
	ds_read_b128 v[104:107], v91 offset:16640
	ds_read_b128 v[108:111], v91 offset:24960
	v_add_u32_e32 v91, 0x8200, v91
	s_waitcnt vmcnt(15) lgkmcnt(3)
	v_pk_add_f32 v[140:141], v[96:97], v[140:141]
	v_pk_add_f32 v[142:143], v[98:99], v[142:143]
	v_lshl_add_u64 v[70:71], v[92:93], 0, v[134:135]
	global_store_dwordx4 v[70:71], v[140:143], off
	v_add_u32_e32 v92, 0x8000, v92
	s_waitcnt vmcnt(15) lgkmcnt(2)
	v_pk_add_f32 v[144:145], v[100:101], v[144:145]
	v_pk_add_f32 v[146:147], v[102:103], v[146:147]
	v_lshl_add_u64 v[70:71], v[92:93], 0, v[134:135]
	global_store_dwordx4 v[70:71], v[144:147], off
	v_add_u32_e32 v92, 0x8000, v92
	s_waitcnt vmcnt(15) lgkmcnt(1)
	v_pk_add_f32 v[148:149], v[104:105], v[148:149]
	v_pk_add_f32 v[150:151], v[106:107], v[150:151]
	v_lshl_add_u64 v[70:71], v[92:93], 0, v[134:135]
	global_store_dwordx4 v[70:71], v[148:151], off
	v_add_u32_e32 v92, 0x8000, v92
	s_waitcnt vmcnt(15) lgkmcnt(0)
	v_pk_add_f32 v[152:153], v[108:109], v[152:153]
	v_pk_add_f32 v[154:155], v[110:111], v[154:155]
	v_lshl_add_u64 v[70:71], v[92:93], 0, v[134:135]
	global_store_dwordx4 v[70:71], v[152:155], off
	v_add_u32_e32 v92, 0x8000, v92
	ds_read_b128 v[96:99], v91
	ds_read_b128 v[100:103], v91 offset:8320
	ds_read_b128 v[104:107], v91 offset:16640
	ds_read_b128 v[108:111], v91 offset:24960
	v_add_u32_e32 v91, 0x8200, v91
	s_waitcnt vmcnt(15) lgkmcnt(3)
	v_pk_add_f32 v[156:157], v[96:97], v[156:157]
	v_pk_add_f32 v[158:159], v[98:99], v[158:159]
	v_lshl_add_u64 v[70:71], v[92:93], 0, v[134:135]
	global_store_dwordx4 v[70:71], v[156:159], off
	v_add_u32_e32 v92, 0x8000, v92
	s_waitcnt vmcnt(15) lgkmcnt(2)
	v_pk_add_f32 v[160:161], v[100:101], v[160:161]
	v_pk_add_f32 v[162:163], v[102:103], v[162:163]
	v_lshl_add_u64 v[70:71], v[92:93], 0, v[134:135]
	global_store_dwordx4 v[70:71], v[160:163], off
	v_add_u32_e32 v92, 0x8000, v92
	s_waitcnt vmcnt(15) lgkmcnt(1)
	v_pk_add_f32 v[164:165], v[104:105], v[164:165]
	v_pk_add_f32 v[166:167], v[106:107], v[166:167]
	v_lshl_add_u64 v[70:71], v[92:93], 0, v[134:135]
	global_store_dwordx4 v[70:71], v[164:167], off
	v_add_u32_e32 v92, 0x8000, v92
	s_waitcnt vmcnt(15) lgkmcnt(0)
	v_pk_add_f32 v[172:173], v[108:109], v[172:173]
	v_pk_add_f32 v[174:175], v[110:111], v[174:175]
	v_lshl_add_u64 v[70:71], v[92:93], 0, v[134:135]
	global_store_dwordx4 v[70:71], v[172:175], off
	v_add_u32_e32 v92, 0x8000, v92
	ds_read_b128 v[96:99], v91
	ds_read_b128 v[100:103], v91 offset:8320
	ds_read_b128 v[104:107], v91 offset:16640
	ds_read_b128 v[108:111], v91 offset:24960
	v_add_u32_e32 v91, 0x8200, v91
	s_waitcnt vmcnt(15) lgkmcnt(3)
	v_pk_add_f32 v[176:177], v[96:97], v[176:177]
	v_pk_add_f32 v[178:179], v[98:99], v[178:179]
	v_lshl_add_u64 v[70:71], v[92:93], 0, v[134:135]
	global_store_dwordx4 v[70:71], v[176:179], off
	v_add_u32_e32 v92, 0x8000, v92
	s_waitcnt vmcnt(15) lgkmcnt(2)
	v_pk_add_f32 v[180:181], v[100:101], v[180:181]
	v_pk_add_f32 v[182:183], v[102:103], v[182:183]
	v_lshl_add_u64 v[70:71], v[92:93], 0, v[134:135]
	global_store_dwordx4 v[70:71], v[180:183], off
	v_add_u32_e32 v92, 0x8000, v92
	s_waitcnt vmcnt(15) lgkmcnt(1)
	v_pk_add_f32 v[184:185], v[104:105], v[184:185]
	v_pk_add_f32 v[186:187], v[106:107], v[186:187]
	v_lshl_add_u64 v[70:71], v[92:93], 0, v[134:135]
	global_store_dwordx4 v[70:71], v[184:187], off
	v_add_u32_e32 v92, 0x8000, v92
	s_waitcnt vmcnt(15) lgkmcnt(0)
	v_pk_add_f32 v[188:189], v[108:109], v[188:189]
	v_pk_add_f32 v[190:191], v[110:111], v[190:191]
	v_lshl_add_u64 v[70:71], v[92:93], 0, v[134:135]
	global_store_dwordx4 v[70:71], v[188:191], off
	v_add_u32_e32 v92, 0x8000, v92
	ds_read_b128 v[96:99], v91
	ds_read_b128 v[100:103], v91 offset:8320
	ds_read_b128 v[104:107], v91 offset:16640
	ds_read_b128 v[108:111], v91 offset:24960
	v_add_u32_e32 v91, 0x8200, v91
	s_waitcnt vmcnt(15) lgkmcnt(3)
	v_pk_add_f32 v[192:193], v[96:97], v[192:193]
	v_pk_add_f32 v[194:195], v[98:99], v[194:195]
	v_lshl_add_u64 v[70:71], v[92:93], 0, v[134:135]
	global_store_dwordx4 v[70:71], v[192:195], off
	v_add_u32_e32 v92, 0x8000, v92
	s_waitcnt vmcnt(15) lgkmcnt(2)
	v_pk_add_f32 v[196:197], v[100:101], v[196:197]
	v_pk_add_f32 v[198:199], v[102:103], v[198:199]
	v_lshl_add_u64 v[70:71], v[92:93], 0, v[134:135]
	global_store_dwordx4 v[70:71], v[196:199], off
	v_add_u32_e32 v92, 0x8000, v92
	s_waitcnt vmcnt(15) lgkmcnt(1)
	v_pk_add_f32 v[220:221], v[104:105], v[220:221]
	v_pk_add_f32 v[222:223], v[106:107], v[222:223]
	v_lshl_add_u64 v[70:71], v[92:93], 0, v[134:135]
	global_store_dwordx4 v[70:71], v[220:223], off
	v_add_u32_e32 v92, 0x8000, v92
	s_waitcnt vmcnt(15) lgkmcnt(0)
	v_pk_add_f32 v[224:225], v[108:109], v[224:225]
	v_pk_add_f32 v[226:227], v[110:111], v[226:227]
	v_lshl_add_u64 v[70:71], v[92:93], 0, v[134:135]
	global_store_dwordx4 v[70:71], v[224:227], off
	v_add_u32_e32 v92, 0x8000, v92

.Lwo2_go:
	v_ashrrev_i32_e32 v0, 6, v131
	v_add_u32_e32 v87, s14, v0
	v_lshlrev_b32_e32 v92, 12, v87
	v_mov_b32_e32 v93, 0
	v_mad_u32_u24 v91, v0, s33, v130
	v_lshl_add_u64 v[66:67], v[92:93], 0, v[88:89]
	global_load_dwordx4 v[140:143], v[66:67], off
	v_add_u32_e32 v92, 0x8000, v92
	v_lshl_add_u64 v[66:67], v[92:93], 0, v[88:89]
	global_load_dwordx4 v[144:147], v[66:67], off
	v_add_u32_e32 v92, 0x8000, v92
	v_lshl_add_u64 v[66:67], v[92:93], 0, v[88:89]
	global_load_dwordx4 v[148:151], v[66:67], off
	v_add_u32_e32 v92, 0x8000, v92
	v_lshl_add_u64 v[66:67], v[92:93], 0, v[88:89]
	global_load_dwordx4 v[152:155], v[66:67], off
	v_add_u32_e32 v92, 0x8000, v92
	v_lshl_add_u64 v[66:67], v[92:93], 0, v[88:89]
	global_load_dwordx4 v[156:159], v[66:67], off
	v_add_u32_e32 v92, 0x8000, v92
	v_lshl_add_u64 v[66:67], v[92:93], 0, v[88:89]
	global_load_dwordx4 v[160:163], v[66:67], off
	v_add_u32_e32 v92, 0x8000, v92
	v_lshl_add_u64 v[66:67], v[92:93], 0, v[88:89]
	global_load_dwordx4 v[164:167], v[66:67], off
	v_add_u32_e32 v92, 0x8000, v92
	v_lshl_add_u64 v[66:67], v[92:93], 0, v[88:89]
	global_load_dwordx4 v[172:175], v[66:67], off
	v_add_u32_e32 v92, 0x8000, v92
	v_lshl_add_u64 v[66:67], v[92:93], 0, v[88:89]
	global_load_dwordx4 v[176:179], v[66:67], off
	v_add_u32_e32 v92, 0x8000, v92
	v_lshl_add_u64 v[66:67], v[92:93], 0, v[88:89]
	global_load_dwordx4 v[180:183], v[66:67], off
	v_add_u32_e32 v92, 0x8000, v92
	v_lshl_add_u64 v[66:67], v[92:93], 0, v[88:89]
	global_load_dwordx4 v[184:187], v[66:67], off
	v_add_u32_e32 v92, 0x8000, v92
	v_lshl_add_u64 v[66:67], v[92:93], 0, v[88:89]
	global_load_dwordx4 v[188:191], v[66:67], off
	v_add_u32_e32 v92, 0x8000, v92
	v_lshl_add_u64 v[66:67], v[92:93], 0, v[88:89]
	global_load_dwordx4 v[192:195], v[66:67], off
	v_add_u32_e32 v92, 0x8000, v92
	v_lshl_add_u64 v[66:67], v[92:93], 0, v[88:89]
	global_load_dwordx4 v[196:199], v[66:67], off
	v_add_u32_e32 v92, 0x8000, v92
	v_lshl_add_u64 v[66:67], v[92:93], 0, v[88:89]
	global_load_dwordx4 v[220:223], v[66:67], off
	v_add_u32_e32 v92, 0x8000, v92
	v_lshl_add_u64 v[66:67], v[92:93], 0, v[88:89]
	global_load_dwordx4 v[224:227], v[66:67], off
	v_add_u32_e32 v92, 0x8000, v92
	v_add_u32_e32 v92, 0xfff80000, v92
	ds_read_b128 v[96:99], v91
	ds_read_b128 v[100:103], v91 offset:8320
	ds_read_b128 v[104:107], v91 offset:16640
	ds_read_b128 v[108:111], v91 offset:24960
	v_add_u32_e32 v91, 0x8200, v91
	s_waitcnt vmcnt(15) lgkmcnt(3)
	v_pk_add_f32 v[140:141], v[96:97], v[140:141]
	v_pk_add_f32 v[142:143], v[98:99], v[142:143]
	v_lshl_add_u64 v[70:71], v[92:93], 0, v[134:135]
	global_store_dwordx4 v[70:71], v[140:143], off
	v_add_u32_e32 v92, 0x8000, v92
	s_waitcnt vmcnt(15) lgkmcnt(2)
	v_pk_add_f32 v[144:145], v[100:101], v[144:145]
	v_pk_add_f32 v[146:147], v[102:103], v[146:147]
	v_lshl_add_u64 v[70:71], v[92:93], 0, v[134:135]
	global_store_dwordx4 v[70:71], v[144:147], off
	v_add_u32_e32 v92, 0x8000, v92
	s_waitcnt vmcnt(15) lgkmcnt(1)
	v_pk_add_f32 v[148:149], v[104:105], v[148:149]
	v_pk_add_f32 v[150:151], v[106:107], v[150:151]
	v_lshl_add_u64 v[70:71], v[92:93], 0, v[134:135]
	global_store_dwordx4 v[70:71], v[148:151], off
	v_add_u32_e32 v92, 0x8000, v92
	s_waitcnt vmcnt(15) lgkmcnt(0)
	v_pk_add_f32 v[152:153], v[108:109], v[152:153]
	v_pk_add_f32 v[154:155], v[110:111], v[154:155]
	v_lshl_add_u64 v[70:71], v[92:93], 0, v[134:135]
	global_store_dwordx4 v[70:71], v[152:155], off
	v_add_u32_e32 v92, 0x8000, v92
	ds_read_b128 v[96:99], v91
	ds_read_b128 v[100:103], v91 offset:8320
	ds_read_b128 v[104:107], v91 offset:16640
	ds_read_b128 v[108:111], v91 offset:24960
	v_add_u32_e32 v91, 0x8200, v91
	s_waitcnt vmcnt(15) lgkmcnt(3)
	v_pk_add_f32 v[156:157], v[96:97], v[156:157]
	v_pk_add_f32 v[158:159], v[98:99], v[158:159]
	v_lshl_add_u64 v[70:71], v[92:93], 0, v[134:135]
	global_store_dwordx4 v[70:71], v[156:159], off
	v_add_u32_e32 v92, 0x8000, v92
	s_waitcnt vmcnt(15) lgkmcnt(2)
	v_pk_add_f32 v[160:161], v[100:101], v[160:161]
	v_pk_add_f32 v[162:163], v[102:103], v[162:163]
	v_lshl_add_u64 v[70:71], v[92:93], 0, v[134:135]
	global_store_dwordx4 v[70:71], v[160:163], off
	v_add_u32_e32 v92, 0x8000, v92
	s_waitcnt vmcnt(15) lgkmcnt(1)
	v_pk_add_f32 v[164:165], v[104:105], v[164:165]
	v_pk_add_f32 v[166:167], v[106:107], v[166:167]
	v_lshl_add_u64 v[70:71], v[92:93], 0, v[134:135]
	global_store_dwordx4 v[70:71], v[164:167], off
	v_add_u32_e32 v92, 0x8000, v92
	s_waitcnt vmcnt(15) lgkmcnt(0)
	v_pk_add_f32 v[172:173], v[108:109], v[172:173]
	v_pk_add_f32 v[174:175], v[110:111], v[174:175]
	v_lshl_add_u64 v[70:71], v[92:93], 0, v[134:135]
	global_store_dwordx4 v[70:71], v[172:175], off
	v_add_u32_e32 v92, 0x8000, v92
	ds_read_b128 v[96:99], v91
	ds_read_b128 v[100:103], v91 offset:8320
	ds_read_b128 v[104:107], v91 offset:16640
	ds_read_b128 v[108:111], v91 offset:24960
	v_add_u32_e32 v91, 0x8200, v91
	s_waitcnt vmcnt(15) lgkmcnt(3)
	v_pk_add_f32 v[176:177], v[96:97], v[176:177]
	v_pk_add_f32 v[178:179], v[98:99], v[178:179]
	v_lshl_add_u64 v[70:71], v[92:93], 0, v[134:135]
	global_store_dwordx4 v[70:71], v[176:179], off
	v_add_u32_e32 v92, 0x8000, v92
	s_waitcnt vmcnt(15) lgkmcnt(2)
	v_pk_add_f32 v[180:181], v[100:101], v[180:181]
	v_pk_add_f32 v[182:183], v[102:103], v[182:183]
	v_lshl_add_u64 v[70:71], v[92:93], 0, v[134:135]
	global_store_dwordx4 v[70:71], v[180:183], off
	v_add_u32_e32 v92, 0x8000, v92
	s_waitcnt vmcnt(15) lgkmcnt(1)
	v_pk_add_f32 v[184:185], v[104:105], v[184:185]
	v_pk_add_f32 v[186:187], v[106:107], v[186:187]
	v_lshl_add_u64 v[70:71], v[92:93], 0, v[134:135]
	global_store_dwordx4 v[70:71], v[184:187], off
	v_add_u32_e32 v92, 0x8000, v92
	s_waitcnt vmcnt(15) lgkmcnt(0)
	v_pk_add_f32 v[188:189], v[108:109], v[188:189]
	v_pk_add_f32 v[190:191], v[110:111], v[190:191]
	v_lshl_add_u64 v[70:71], v[92:93], 0, v[134:135]
	global_store_dwordx4 v[70:71], v[188:191], off
	v_add_u32_e32 v92, 0x8000, v92
	ds_read_b128 v[96:99], v91
	ds_read_b128 v[100:103], v91 offset:8320
	ds_read_b128 v[104:107], v91 offset:16640
	ds_read_b128 v[108:111], v91 offset:24960
	v_add_u32_e32 v91, 0x8200, v91
	s_waitcnt vmcnt(15) lgkmcnt(3)
	v_pk_add_f32 v[192:193], v[96:97], v[192:193]
	v_pk_add_f32 v[194:195], v[98:99], v[194:195]
	v_lshl_add_u64 v[70:71], v[92:93], 0, v[134:135]
	global_store_dwordx4 v[70:71], v[192:195], off
	v_add_u32_e32 v92, 0x8000, v92
	s_waitcnt vmcnt(15) lgkmcnt(2)
	v_pk_add_f32 v[196:197], v[100:101], v[196:197]
	v_pk_add_f32 v[198:199], v[102:103], v[198:199]
	v_lshl_add_u64 v[70:71], v[92:93], 0, v[134:135]
	global_store_dwordx4 v[70:71], v[196:199], off
	v_add_u32_e32 v92, 0x8000, v92
	s_waitcnt vmcnt(15) lgkmcnt(1)
	v_pk_add_f32 v[220:221], v[104:105], v[220:221]
	v_pk_add_f32 v[222:223], v[106:107], v[222:223]
	v_lshl_add_u64 v[70:71], v[92:93], 0, v[134:135]
	global_store_dwordx4 v[70:71], v[220:223], off
	v_add_u32_e32 v92, 0x8000, v92
	s_waitcnt vmcnt(15) lgkmcnt(0)
	v_pk_add_f32 v[224:225], v[108:109], v[224:225]
	v_pk_add_f32 v[226:227], v[110:111], v[226:227]
	v_lshl_add_u64 v[70:71], v[92:93], 0, v[134:135]
	global_store_dwordx4 v[70:71], v[224:227], off
	v_add_u32_e32 v92, 0x8000, v92
	s_branch .LBB0_30

.LBB0_126:
	s_and_b32 s4, s16, 0xffffff00
	s_lshl_b32 s0, s14, 11
	s_ashr_i32 s5, s4, 31
	s_and_b32 s0, s0, 0x38000
	s_lshl_b64 s[4:5], s[4:5], 11
	v_mov_b32_e32 v2, 0
	v_lshl_add_u64 v[18:19], v[12:13], 0, s[0:1]
	v_lshl_add_u64 v[20:21], v[14:15], 0, s[4:5]
	v_lshl_add_u64 v[22:23], v[16:17], 0, s[4:5]
	s_movk_i32 s0, 0xffe0
	v_mov_b32_e32 v3, v2
	v_mov_b32_e32 v4, v2
	v_mov_b32_e32 v5, v2
	s_waitcnt vmcnt(0)
	v_mov_b32_e32 v6, v2
	v_mov_b32_e32 v7, v2
	v_mov_b32_e32 v8, v2
	v_mov_b32_e32 v9, v2
	global_load_dwordx4 v[28:31], v[18:19], off offset:-256
	global_load_dwordx4 v[32:35], v[20:21], off offset:-256
	global_load_dwordx4 v[36:39], v[22:23], off offset:-256
	global_load_dwordx4 v[96:99], v[18:19], off offset:-192
	global_load_dwordx4 v[100:103], v[20:21], off offset:-192
	global_load_dwordx4 v[104:107], v[22:23], off offset:-192
	global_load_dwordx4 v[108:111], v[18:19], off offset:-128
	global_load_dwordx4 v[112:115], v[20:21], off offset:-128
	global_load_dwordx4 v[116:119], v[22:23], off offset:-128
	global_load_dwordx4 v[120:123], v[18:19], off offset:-64
	global_load_dwordx4 v[124:127], v[20:21], off offset:-64
	global_load_dwordx4 v[128:131], v[22:23], off offset:-64
	global_load_dwordx4 v[132:135], v[18:19], off
	global_load_dwordx4 v[136:139], v[20:21], off
	global_load_dwordx4 v[140:143], v[22:23], off
	global_load_dwordx4 v[144:147], v[18:19], off offset:64
	global_load_dwordx4 v[148:151], v[20:21], off offset:64
	global_load_dwordx4 v[152:155], v[22:23], off offset:64
	global_load_dwordx4 v[156:159], v[18:19], off offset:128
	global_load_dwordx4 v[160:163], v[20:21], off offset:128
	global_load_dwordx4 v[164:167], v[22:23], off offset:128
	global_load_dwordx4 v[172:175], v[18:19], off offset:192
	global_load_dwordx4 v[176:179], v[20:21], off offset:192
	global_load_dwordx4 v[180:183], v[22:23], off offset:192
	v_lshl_add_u64 v[18:19], v[18:19], 0, s[22:23]
	v_lshl_add_u64 v[20:21], v[20:21], 0, s[22:23]
	v_lshl_add_u64 v[22:23], v[22:23], 0, s[22:23]
.Lsg0_loop:
	s_addk_i32 s0, 0x100
	s_cmpk_lt_u32 s0, 0x3e0
	s_cbranch_scc0 .Lsg0_tail
	s_waitcnt vmcnt(21)
	v_mfma_f32_16x16x32_bf16 v[2:5], v[28:31], v[32:35], v[2:5]
	v_mfma_f32_16x16x32_bf16 v[6:9], v[28:31], v[36:39], v[6:9]
	global_load_dwordx4 v[28:31], v[18:19], off offset:-256
	global_load_dwordx4 v[32:35], v[20:21], off offset:-256
	global_load_dwordx4 v[36:39], v[22:23], off offset:-256
	s_waitcnt vmcnt(21)
	v_mfma_f32_16x16x32_bf16 v[2:5], v[96:99], v[100:103], v[2:5]
	v_mfma_f32_16x16x32_bf16 v[6:9], v[96:99], v[104:107], v[6:9]
	global_load_dwordx4 v[96:99], v[18:19], off offset:-192
	global_load_dwordx4 v[100:103], v[20:21], off offset:-192
	global_load_dwordx4 v[104:107], v[22:23], off offset:-192
	s_waitcnt vmcnt(21)
	v_mfma_f32_16x16x32_bf16 v[2:5], v[108:111], v[112:115], v[2:5]
	v_mfma_f32_16x16x32_bf16 v[6:9], v[108:111], v[116:119], v[6:9]
	global_load_dwordx4 v[108:111], v[18:19], off offset:-128
	global_load_dwordx4 v[112:115], v[20:21], off offset:-128
	global_load_dwordx4 v[116:119], v[22:23], off offset:-128
	s_waitcnt vmcnt(21)
	v_mfma_f32_16x16x32_bf16 v[2:5], v[120:123], v[124:127], v[2:5]
	v_mfma_f32_16x16x32_bf16 v[6:9], v[120:123], v[128:131], v[6:9]
	global_load_dwordx4 v[120:123], v[18:19], off offset:-64
	global_load_dwordx4 v[124:127], v[20:21], off offset:-64
	global_load_dwordx4 v[128:131], v[22:23], off offset:-64
	s_waitcnt vmcnt(21)
	v_mfma_f32_16x16x32_bf16 v[2:5], v[132:135], v[136:139], v[2:5]
	v_mfma_f32_16x16x32_bf16 v[6:9], v[132:135], v[140:143], v[6:9]
	global_load_dwordx4 v[132:135], v[18:19], off
	global_load_dwordx4 v[136:139], v[20:21], off
	global_load_dwordx4 v[140:143], v[22:23], off
	s_waitcnt vmcnt(21)
	v_mfma_f32_16x16x32_bf16 v[2:5], v[144:147], v[148:151], v[2:5]
	v_mfma_f32_16x16x32_bf16 v[6:9], v[144:147], v[152:155], v[6:9]
	global_load_dwordx4 v[144:147], v[18:19], off offset:64
	global_load_dwordx4 v[148:151], v[20:21], off offset:64
	global_load_dwordx4 v[152:155], v[22:23], off offset:64
	s_waitcnt vmcnt(21)
	v_mfma_f32_16x16x32_bf16 v[2:5], v[156:159], v[160:163], v[2:5]
	v_mfma_f32_16x16x32_bf16 v[6:9], v[156:159], v[164:167], v[6:9]
	global_load_dwordx4 v[156:159], v[18:19], off offset:128
	global_load_dwordx4 v[160:163], v[20:21], off offset:128
	global_load_dwordx4 v[164:167], v[22:23], off offset:128
	s_waitcnt vmcnt(21)
	v_mfma_f32_16x16x32_bf16 v[2:5], v[172:175], v[176:179], v[2:5]
	v_mfma_f32_16x16x32_bf16 v[6:9], v[172:175], v[180:183], v[6:9]
	global_load_dwordx4 v[172:175], v[18:19], off offset:192
	global_load_dwordx4 v[176:179], v[20:21], off offset:192
	global_load_dwordx4 v[180:183], v[22:23], off offset:192
	v_lshl_add_u64 v[18:19], v[18:19], 0, s[22:23]
	v_lshl_add_u64 v[20:21], v[20:21], 0, s[22:23]
	v_lshl_add_u64 v[22:23], v[22:23], 0, s[22:23]
	s_branch .Lsg0_loop
.Lsg0_tail:
	s_waitcnt vmcnt(21)
	v_mfma_f32_16x16x32_bf16 v[2:5], v[28:31], v[32:35], v[2:5]
	v_mfma_f32_16x16x32_bf16 v[6:9], v[28:31], v[36:39], v[6:9]
	s_waitcnt vmcnt(18)
	v_mfma_f32_16x16x32_bf16 v[2:5], v[96:99], v[100:103], v[2:5]
	v_mfma_f32_16x16x32_bf16 v[6:9], v[96:99], v[104:107], v[6:9]
	s_waitcnt vmcnt(15)
	v_mfma_f32_16x16x32_bf16 v[2:5], v[108:111], v[112:115], v[2:5]
	v_mfma_f32_16x16x32_bf16 v[6:9], v[108:111], v[116:119], v[6:9]
	s_waitcnt vmcnt(12)
	v_mfma_f32_16x16x32_bf16 v[2:5], v[120:123], v[124:127], v[2:5]
	v_mfma_f32_16x16x32_bf16 v[6:9], v[120:123], v[128:131], v[6:9]
	s_waitcnt vmcnt(9)
	v_mfma_f32_16x16x32_bf16 v[2:5], v[132:135], v[136:139], v[2:5]
	v_mfma_f32_16x16x32_bf16 v[6:9], v[132:135], v[140:143], v[6:9]
	s_waitcnt vmcnt(6)
	v_mfma_f32_16x16x32_bf16 v[2:5], v[144:147], v[148:151], v[2:5]
	v_mfma_f32_16x16x32_bf16 v[6:9], v[144:147], v[152:155], v[6:9]
	s_waitcnt vmcnt(3)
	v_mfma_f32_16x16x32_bf16 v[2:5], v[156:159], v[160:163], v[2:5]
	v_mfma_f32_16x16x32_bf16 v[6:9], v[156:159], v[164:167], v[6:9]
	s_waitcnt vmcnt(0)
	v_mfma_f32_16x16x32_bf16 v[2:5], v[172:175], v[176:179], v[2:5]
	v_mfma_f32_16x16x32_bf16 v[6:9], v[172:175], v[180:183], v[6:9]
	s_lshl_b32 s0, s13, 4
	s_lshl_b32 s4, s13, 5
	s_and_b32 s0, s0, 0x70
	s_and_b32 s4, s4, 0xffffff00
	v_or_b32_e32 v0, s0, v26
	v_add_u32_e32 v20, s4, v10
	v_or_b32_e32 v11, 0x4000, v0
	v_ashrrev_i32_e32 v21, 31, v20
	v_lshl_add_u64 v[18:19], v[20:21], 2, s[6:7]
	s_mov_b64 s[4:5], -1
	s_and_b64 vcc, exec, s[8:9]
	v_lshlrev_b32_e32 v0, 10, v11
	v_lshlrev_b32_e32 v22, 12, v11
	s_cbranch_vccz .LBB0_130
	v_mov_b32_e32 v23, v1
	v_lshl_add_u64 v[24:25], v[18:19], 0, v[22:23]
	s_mov_b64 s[4:5], 0

.LBB0_164:
	s_cmp_eq_u32 s16, 1
	s_movk_i32 s0, 0x800
	s_cselect_b32 s0, s0, 0x600
	s_cmp_lg_u32 s16, 0
	s_cselect_b32 s0, s0, 0x400
	s_lshl_b32 s0, s0, 1
	v_lshl_add_u64 v[44:45], v[42:43], 0, s[0:1]
	s_movk_i32 s0, 0xffe0
	v_mov_b64_e32 v[46:47], v[24:25]
	v_mov_b64_e32 v[48:49], v[22:23]
	v_mov_b32_e32 v6, 0
	v_mov_b32_e32 v7, v0
	v_mov_b32_e32 v8, v0
	v_mov_b32_e32 v9, v0
	v_mov_b32_e32 v2, 0
	v_mov_b32_e32 v3, v0
	v_mov_b32_e32 v4, v0
	v_mov_b32_e32 v5, v0
	global_load_dwordx4 v[52:55], v[44:45], off offset:-256
	global_load_dwordx4 v[56:59], v[46:47], off offset:-256
	global_load_dwordx4 v[60:63], v[48:49], off offset:-256
	global_load_dwordx4 v[96:99], v[44:45], off offset:-192
	global_load_dwordx4 v[100:103], v[46:47], off offset:-192
	global_load_dwordx4 v[104:107], v[48:49], off offset:-192
	global_load_dwordx4 v[108:111], v[44:45], off offset:-128
	global_load_dwordx4 v[112:115], v[46:47], off offset:-128
	global_load_dwordx4 v[116:119], v[48:49], off offset:-128
	global_load_dwordx4 v[120:123], v[44:45], off offset:-64
	global_load_dwordx4 v[124:127], v[46:47], off offset:-64
	global_load_dwordx4 v[128:131], v[48:49], off offset:-64
	global_load_dwordx4 v[132:135], v[44:45], off
	global_load_dwordx4 v[136:139], v[46:47], off
	global_load_dwordx4 v[140:143], v[48:49], off
	global_load_dwordx4 v[144:147], v[44:45], off offset:64
	global_load_dwordx4 v[148:151], v[46:47], off offset:64
	global_load_dwordx4 v[152:155], v[48:49], off offset:64
	global_load_dwordx4 v[156:159], v[44:45], off offset:128
	global_load_dwordx4 v[160:163], v[46:47], off offset:128
	global_load_dwordx4 v[164:167], v[48:49], off offset:128
	global_load_dwordx4 v[172:175], v[44:45], off offset:192
	global_load_dwordx4 v[176:179], v[46:47], off offset:192
	global_load_dwordx4 v[180:183], v[48:49], off offset:192
	v_lshl_add_u64 v[48:49], v[48:49], 0, s[22:23]
	v_lshl_add_u64 v[46:47], v[46:47], 0, s[22:23]
	v_lshl_add_u64 v[44:45], v[44:45], 0, s[22:23]
.Lsg1_loop:
	s_addk_i32 s0, 0x100
	s_cmpk_lt_u32 s0, 0x1e0
	s_cbranch_scc0 .Lsg1_tail
	s_waitcnt vmcnt(21)
	v_mfma_f32_16x16x32_bf16 v[6:9], v[52:55], v[56:59], v[6:9]
	v_mfma_f32_16x16x32_bf16 v[2:5], v[52:55], v[60:63], v[2:5]
	global_load_dwordx4 v[52:55], v[44:45], off offset:-256
	global_load_dwordx4 v[56:59], v[46:47], off offset:-256
	global_load_dwordx4 v[60:63], v[48:49], off offset:-256
	s_waitcnt vmcnt(21)
	v_mfma_f32_16x16x32_bf16 v[6:9], v[96:99], v[100:103], v[6:9]
	v_mfma_f32_16x16x32_bf16 v[2:5], v[96:99], v[104:107], v[2:5]
	global_load_dwordx4 v[96:99], v[44:45], off offset:-192
	global_load_dwordx4 v[100:103], v[46:47], off offset:-192
	global_load_dwordx4 v[104:107], v[48:49], off offset:-192
	s_waitcnt vmcnt(21)
	v_mfma_f32_16x16x32_bf16 v[6:9], v[108:111], v[112:115], v[6:9]
	v_mfma_f32_16x16x32_bf16 v[2:5], v[108:111], v[116:119], v[2:5]
	global_load_dwordx4 v[108:111], v[44:45], off offset:-128
	global_load_dwordx4 v[112:115], v[46:47], off offset:-128
	global_load_dwordx4 v[116:119], v[48:49], off offset:-128
	s_waitcnt vmcnt(21)
	v_mfma_f32_16x16x32_bf16 v[6:9], v[120:123], v[124:127], v[6:9]
	v_mfma_f32_16x16x32_bf16 v[2:5], v[120:123], v[128:131], v[2:5]
	global_load_dwordx4 v[120:123], v[44:45], off offset:-64
	global_load_dwordx4 v[124:127], v[46:47], off offset:-64
	global_load_dwordx4 v[128:131], v[48:49], off offset:-64
	s_waitcnt vmcnt(21)
	v_mfma_f32_16x16x32_bf16 v[6:9], v[132:135], v[136:139], v[6:9]
	v_mfma_f32_16x16x32_bf16 v[2:5], v[132:135], v[140:143], v[2:5]
	global_load_dwordx4 v[132:135], v[44:45], off
	global_load_dwordx4 v[136:139], v[46:47], off
	global_load_dwordx4 v[140:143], v[48:49], off
	s_waitcnt vmcnt(21)
	v_mfma_f32_16x16x32_bf16 v[6:9], v[144:147], v[148:151], v[6:9]
	v_mfma_f32_16x16x32_bf16 v[2:5], v[144:147], v[152:155], v[2:5]
	global_load_dwordx4 v[144:147], v[44:45], off offset:64
	global_load_dwordx4 v[148:151], v[46:47], off offset:64
	global_load_dwordx4 v[152:155], v[48:49], off offset:64
	s_waitcnt vmcnt(21)
	v_mfma_f32_16x16x32_bf16 v[6:9], v[156:159], v[160:163], v[6:9]
	v_mfma_f32_16x16x32_bf16 v[2:5], v[156:159], v[164:167], v[2:5]
	global_load_dwordx4 v[156:159], v[44:45], off offset:128
	global_load_dwordx4 v[160:163], v[46:47], off offset:128
	global_load_dwordx4 v[164:167], v[48:49], off offset:128
	s_waitcnt vmcnt(21)
	v_mfma_f32_16x16x32_bf16 v[6:9], v[172:175], v[176:179], v[6:9]
	v_mfma_f32_16x16x32_bf16 v[2:5], v[172:175], v[180:183], v[2:5]
	global_load_dwordx4 v[172:175], v[44:45], off offset:192
	global_load_dwordx4 v[176:179], v[46:47], off offset:192
	global_load_dwordx4 v[180:183], v[48:49], off offset:192
	v_lshl_add_u64 v[48:49], v[48:49], 0, s[22:23]
	v_lshl_add_u64 v[46:47], v[46:47], 0, s[22:23]
	v_lshl_add_u64 v[44:45], v[44:45], 0, s[22:23]
	s_branch .Lsg1_loop
.Lsg1_tail:
	s_waitcnt vmcnt(21)
	v_mfma_f32_16x16x32_bf16 v[6:9], v[52:55], v[56:59], v[6:9]
	v_mfma_f32_16x16x32_bf16 v[2:5], v[52:55], v[60:63], v[2:5]
	s_waitcnt vmcnt(18)
	v_mfma_f32_16x16x32_bf16 v[6:9], v[96:99], v[100:103], v[6:9]
	v_mfma_f32_16x16x32_bf16 v[2:5], v[96:99], v[104:107], v[2:5]
	s_waitcnt vmcnt(15)
	v_mfma_f32_16x16x32_bf16 v[6:9], v[108:111], v[112:115], v[6:9]
	v_mfma_f32_16x16x32_bf16 v[2:5], v[108:111], v[116:119], v[2:5]
	s_waitcnt vmcnt(12)
	v_mfma_f32_16x16x32_bf16 v[6:9], v[120:123], v[124:127], v[6:9]
	v_mfma_f32_16x16x32_bf16 v[2:5], v[120:123], v[128:131], v[2:5]
	s_waitcnt vmcnt(9)
	v_mfma_f32_16x16x32_bf16 v[6:9], v[132:135], v[136:139], v[6:9]
	v_mfma_f32_16x16x32_bf16 v[2:5], v[132:135], v[140:143], v[2:5]
	s_waitcnt vmcnt(6)
	v_mfma_f32_16x16x32_bf16 v[6:9], v[144:147], v[148:151], v[6:9]
	v_mfma_f32_16x16x32_bf16 v[2:5], v[144:147], v[152:155], v[2:5]
	s_waitcnt vmcnt(3)
	v_mfma_f32_16x16x32_bf16 v[6:9], v[156:159], v[160:163], v[6:9]
	v_mfma_f32_16x16x32_bf16 v[2:5], v[156:159], v[164:167], v[2:5]
	s_waitcnt vmcnt(0)
	v_mfma_f32_16x16x32_bf16 v[6:9], v[172:175], v[176:179], v[6:9]
	v_mfma_f32_16x16x32_bf16 v[2:5], v[172:175], v[180:183], v[2:5]
	s_lshl_b32 s0, s16, 11
	v_lshl_add_u64 v[44:45], v[26:27], 0, s[0:1]
	v_lshl_add_u64 v[46:47], v[32:33], 0, s[0:1]
	global_load_ushort v21, v[44:45], off
	global_load_ushort v48, v[46:47], off
	s_add_i32 s16, s16, 1
	s_mov_b64 s[18:19], 0x100000
	v_lshl_add_u64 v[22:23], v[22:23], 0, s[18:19]
	v_lshl_add_u64 v[24:25], v[24:25], 0, s[18:19]
	s_cmp_eq_u32 s16, 3
	s_waitcnt vmcnt(0)
	v_lshlrev_b32_e32 v49, 16, v48
	v_lshlrev_b32_e32 v48, 16, v21
	v_pk_fma_f32 v[36:37], v[6:7], v[48:49], v[36:37]
	global_load_ushort v6, v[44:45], off offset:32
	global_load_ushort v7, v[46:47], off offset:32
	s_waitcnt vmcnt(1)
	v_lshlrev_b32_e32 v6, 16, v6
	s_waitcnt vmcnt(0)
	v_lshlrev_b32_e32 v7, 16, v7
	v_pk_fma_f32 v[38:39], v[2:3], v[6:7], v[38:39]
	v_lshl_add_u64 v[2:3], v[34:35], 0, s[0:1]
	v_lshl_add_u64 v[6:7], v[40:41], 0, s[0:1]
	global_load_ushort v21, v[2:3], off
	global_load_ushort v44, v[6:7], off
	s_nop 0
	global_load_ushort v2, v[2:3], off offset:32
	s_nop 0
	global_load_ushort v3, v[6:7], off offset:32
	s_waitcnt vmcnt(1)
	v_lshlrev_b32_e32 v2, 16, v2
	v_lshlrev_b32_e32 v45, 16, v44
	v_lshlrev_b32_e32 v44, 16, v21
	s_waitcnt vmcnt(0)
	v_lshlrev_b32_e32 v3, 16, v3
	v_pk_fma_f32 v[28:29], v[8:9], v[44:45], v[28:29]
	v_pk_fma_f32 v[30:31], v[4:5], v[2:3], v[30:31]
	s_cbranch_scc0 .LBB0_164
	v_lshlrev_b32_e32 v0, 11, v50
	v_lshl_add_u64 v[2:3], s[8:9], 1, v[10:11]
	v_lshl_add_u64 v[4:5], v[2:3], 0, v[0:1]
	v_cvt_pk_bf16_f32 v6, v36, s0
	global_store_short v[4:5], v6, off
	v_cvt_pk_bf16_f32 v6, v38, s0
	global_store_short v[4:5], v6, off offset:32
	v_or_b32_e32 v4, 0x800, v0
	v_mov_b32_e32 v5, v1
	v_lshl_add_u64 v[4:5], v[2:3], 0, v[4:5]
	v_cvt_pk_bf16_f32 v6, v37, s0
	global_store_short v[4:5], v6, off
	v_cvt_pk_bf16_f32 v6, v39, s0
	global_store_short v[4:5], v6, off offset:32
	v_or_b32_e32 v4, 0x1000, v0
	v_mov_b32_e32 v5, v1
	v_or_b32_e32 v0, 0x1800, v0
	v_lshl_add_u64 v[4:5], v[2:3], 0, v[4:5]
	v_cvt_pk_bf16_f32 v6, v28, s0
	v_lshl_add_u64 v[2:3], v[2:3], 0, v[0:1]
	v_cvt_pk_bf16_f32 v0, v29, s0
	s_add_i32 s11, s11, s10
	s_add_i32 s12, s12, s13
	s_add_i32 s14, s14, s15
	global_store_short v[4:5], v6, off
	v_cvt_pk_bf16_f32 v6, v30, s0
	global_store_short v[2:3], v0, off
	v_cvt_pk_bf16_f32 v0, v31, s0
	s_cmp_gt_i32 s11, 31
	global_store_short v[4:5], v6, off offset:32
	global_store_short v[2:3], v0, off offset:32
	s_cbranch_scc0 .LBB0_163

.LBB0_178:
	s_ashr_i32 s25, s24, 31
	s_lshl_b64 s[26:27], s[24:25], 11
	v_lshl_add_u64 v[14:15], v[4:5], 0, s[26:27]
	v_add_co_u32_e32 v16, vcc, s40, v14
	v_lshl_add_u64 v[24:25], v[6:7], 0, s[26:27]
	s_nop 0
	v_addc_co_u32_e32 v17, vcc, 0, v15, vcc
	v_add_co_u32_e32 v18, vcc, s42, v14
	v_lshl_add_u64 v[12:13], v[10:11], 0, s[18:19]
	s_nop 0
	v_addc_co_u32_e32 v19, vcc, 0, v15, vcc
	v_add_co_u32_e32 v20, vcc, s40, v24
	global_load_dword v31, v[12:13], off
	s_nop 0
	v_addc_co_u32_e32 v21, vcc, 0, v25, vcc
	v_add_co_u32_e32 v22, vcc, s42, v24
	global_load_dword v38, v[14:15], off
	global_load_dword v39, v[24:25], off
	global_load_dword v40, v[14:15], off offset:2048
	global_load_dword v41, v[24:25], off offset:2048
	v_addc_co_u32_e32 v23, vcc, 0, v25, vcc
	global_load_dword v42, v[18:19], off offset:-4096
	global_load_dword v43, v[22:23], off offset:-4096
	global_load_dword v44, v[16:17], off offset:2048
	global_load_dword v45, v[20:21], off offset:2048
	global_load_dword v46, v[18:19], off
	global_load_dword v47, v[22:23], off
	global_load_dword v48, v[18:19], off offset:2048
	global_load_dword v49, v[22:23], off offset:2048
	v_add_co_u32_e32 v16, vcc, s64, v14
	s_mul_i32 s17, s24, 0x3800
	s_nop 0
	v_addc_co_u32_e32 v17, vcc, 0, v15, vcc
	v_add_co_u32_e32 v18, vcc, s44, v14
	s_mul_hi_i32 s0, s24, 0x3800
	s_nop 0
	v_addc_co_u32_e32 v19, vcc, 0, v15, vcc
	v_add_co_u32_e32 v20, vcc, s64, v24
	global_load_dword v50, v[18:19], off offset:-4096
	s_nop 0
	v_addc_co_u32_e32 v21, vcc, 0, v25, vcc
	v_add_co_u32_e32 v22, vcc, s44, v24
	s_add_u32 s26, s4, s17
	s_nop 0
	v_addc_co_u32_e32 v23, vcc, 0, v25, vcc
	global_load_dword v51, v[22:23], off offset:-4096
	global_load_dword v52, v[16:17], off offset:2048
	global_load_dword v32, v[20:21], off offset:2048
	global_load_dword v33, v[18:19], off
	global_load_dword v28, v[22:23], off
	global_load_dword v29, v[18:19], off offset:2048
	global_load_dword v26, v[22:23], off offset:2048
	v_add_co_u32_e32 v16, vcc, s69, v14
	s_addc_u32 s27, s5, s0
	s_nop 0
	v_addc_co_u32_e32 v17, vcc, 0, v15, vcc
	v_add_co_u32_e32 v34, vcc, s45, v14
	v_lshl_add_u64 v[12:13], v[2:3], 1, s[26:27]
	s_nop 0
	v_addc_co_u32_e32 v35, vcc, 0, v15, vcc
	v_add_co_u32_e32 v18, vcc, s69, v24
	global_load_dword v27, v[34:35], off offset:-4096
	s_nop 0
	v_addc_co_u32_e32 v19, vcc, 0, v25, vcc
	v_add_co_u32_e32 v36, vcc, s45, v24
	s_waitcnt vmcnt(19)
	v_fmac_f32_e32 v39, v31, v38
	v_addc_co_u32_e32 v37, vcc, 0, v25, vcc
	global_load_dword v22, v[36:37], off offset:-4096
	global_load_dword v23, v[16:17], off offset:2048
	global_load_dword v20, v[18:19], off offset:2048
	global_load_dword v21, v[34:35], off
	s_nop 0
	global_load_dword v18, v[36:37], off
	global_load_dword v19, v[34:35], off offset:2048
	global_load_dword v16, v[36:37], off offset:2048
	v_add_co_u32_e32 v34, vcc, s68, v14
	s_waitcnt vmcnt(24)
	v_fmac_f32_e32 v41, v39, v40
	v_addc_co_u32_e32 v35, vcc, 0, v15, vcc
	v_add_co_u32_e32 v24, vcc, s68, v24
	global_load_dword v17, v[34:35], off
	s_nop 0
	v_addc_co_u32_e32 v25, vcc, 0, v25, vcc
	global_load_dword v14, v[24:25], off
	global_load_dword v15, v[34:35], off offset:2048
	global_load_dword v0, v[24:25], off offset:2048
	v_add_co_u32_e32 v24, vcc, s40, v12
	s_waitcnt vmcnt(26)
	v_fmac_f32_e32 v43, v41, v42
	v_addc_co_u32_e32 v25, vcc, 0, v13, vcc
	global_load_ushort v24, v[24:25], off offset:3072
	s_waitcnt vmcnt(25)
	v_fmac_f32_e32 v45, v43, v44
	s_waitcnt vmcnt(23)
	v_fmac_f32_e32 v47, v45, v46
	s_waitcnt vmcnt(21)
	v_fmac_f32_e32 v49, v47, v48
	s_waitcnt vmcnt(19)
	v_fmac_f32_e32 v51, v49, v50
	s_waitcnt vmcnt(17)
	v_fmac_f32_e32 v32, v51, v52
	s_waitcnt vmcnt(15)
	v_fmac_f32_e32 v28, v32, v33
	s_waitcnt vmcnt(13)
	v_fmac_f32_e32 v26, v28, v29
	s_waitcnt vmcnt(11)
	v_fmac_f32_e32 v22, v26, v27
	s_waitcnt vmcnt(9)
	v_fmac_f32_e32 v20, v22, v23
	s_waitcnt vmcnt(7)
	v_fmac_f32_e32 v18, v20, v21
	s_waitcnt vmcnt(5)
	v_fmac_f32_e32 v16, v18, v19
	s_waitcnt vmcnt(3)
	v_fmac_f32_e32 v14, v16, v17
	s_waitcnt vmcnt(1)
	v_fmac_f32_e32 v0, v14, v15
	s_waitcnt vmcnt(0)
	v_lshlrev_b32_e32 v24, 16, v24
	v_mul_f32_e32 v25, 0xbfb8aa3b, v24
	v_exp_f32_e32 v25, v25
	s_nop 0
	v_add_f32_e32 v25, 1.0, v25
	v_rcp_f32_e32 v34, v25
	s_nop 0
	v_mul_f32_e32 v24, v24, v34
	v_mul_f32_e32 v24, v39, v24
	v_cvt_pk_bf16_f32 v35, v24, s0
	v_add_co_u32_e32 v24, vcc, s69, v12
	s_mov_b32 s0, 0x1d000
	s_nop 0
	v_addc_co_u32_e32 v25, vcc, 0, v13, vcc
	global_load_ushort v38, v[24:25], off offset:1024
	v_add_co_u32_e32 v24, vcc, s63, v12
	global_store_short v[12:13], v35, off offset:3072
	s_nop 0
	v_addc_co_u32_e32 v25, vcc, 0, v13, vcc
	global_load_ushort v53, v[24:25], off offset:3072
	v_add_co_u32_e32 v24, vcc, s65, v12
	s_waitcnt vmcnt(2)
	v_lshlrev_b32_e32 v35, 16, v38
	v_addc_co_u32_e32 v25, vcc, 0, v13, vcc
	global_load_ushort v54, v[24:25], off offset:1024
	v_add_co_u32_e32 v24, vcc, s70, v12
	s_nop 1
	v_addc_co_u32_e32 v25, vcc, 0, v13, vcc
	global_load_ushort v55, v[24:25], off offset:3072
	v_add_co_u32_e32 v24, vcc, s71, v12
	s_nop 1
	v_addc_co_u32_e32 v25, vcc, 0, v13, vcc
	global_load_ushort v56, v[24:25], off offset:1024
	v_add_co_u32_e32 v24, vcc, s43, v12
	s_nop 1
	v_addc_co_u32_e32 v25, vcc, 0, v13, vcc
	global_load_ushort v57, v[24:25], off offset:3072
	v_add_co_u32_e32 v24, vcc, s67, v12
	s_nop 1
	v_addc_co_u32_e32 v25, vcc, 0, v13, vcc
	global_load_ushort v58, v[24:25], off offset:1024
	v_add_co_u32_e32 v24, vcc, s0, v12
	s_mov_b32 s0, 0x24000
	s_nop 0
	v_addc_co_u32_e32 v25, vcc, 0, v13, vcc
	global_load_ushort v59, v[24:25], off offset:3072
	v_add_co_u32_e32 v24, vcc, s72, v12
	s_nop 1
	v_addc_co_u32_e32 v25, vcc, 0, v13, vcc
	global_load_ushort v60, v[24:25], off offset:1024
	v_add_co_u32_e32 v24, vcc, s0, v12
	s_mov_b32 s0, 0x28000
	s_nop 0
	v_addc_co_u32_e32 v25, vcc, 0, v13, vcc
	global_load_ushort v61, v[24:25], off offset:3072
	v_add_co_u32_e32 v24, vcc, s0, v12
	s_mov_b32 s0, 0x2b000
	s_nop 0
	v_addc_co_u32_e32 v25, vcc, 0, v13, vcc
	global_load_ushort v62, v[24:25], off offset:1024
	v_add_co_u32_e32 v24, vcc, s0, v12
	s_mov_b32 s0, 0x2f000
	s_nop 0
	v_addc_co_u32_e32 v25, vcc, 0, v13, vcc
	global_load_ushort v34, v[24:25], off offset:3072
	v_add_co_u32_e32 v24, vcc, s0, v12
	s_mov_b32 s0, 0x32000
	s_nop 0
	v_addc_co_u32_e32 v25, vcc, 0, v13, vcc
	global_load_ushort v31, v[24:25], off offset:1024
	v_add_co_u32_e32 v24, vcc, s0, v12
	s_mov_b32 s0, 0x36000
	s_nop 0
	v_addc_co_u32_e32 v25, vcc, 0, v13, vcc
	v_add_co_u32_e32 v36, vcc, s0, v12
	global_load_ushort v25, v[24:25], off offset:3072
	s_nop 0
	v_addc_co_u32_e32 v37, vcc, 0, v13, vcc
	global_load_ushort v24, v[36:37], off offset:1024
	v_mul_f32_e32 v36, 0xbfb8aa3b, v35
	v_exp_f32_e32 v36, v36
	s_nop 0
	v_add_f32_e32 v36, 1.0, v36
	v_rcp_f32_e32 v38, v36
	s_nop 0
	v_mul_f32_e32 v35, v35, v38
	v_mul_f32_e32 v35, v41, v35
	v_add_co_u32_e32 v36, vcc, s44, v12
	v_cvt_pk_bf16_f32 v35, v35, s0
	s_nop 0
	v_addc_co_u32_e32 v37, vcc, 0, v13, vcc
	global_store_short v[36:37], v35, off offset:1024
	s_waitcnt vmcnt(14)
	v_lshlrev_b32_e32 v35, 16, v53
	v_mul_f32_e32 v36, 0xbfb8aa3b, v35
	v_exp_f32_e32 v36, v36
	s_nop 0
	v_add_f32_e32 v36, 1.0, v36
	v_rcp_f32_e32 v38, v36
	s_nop 0
	v_mul_f32_e32 v35, v35, v38
	v_mul_f32_e32 v35, v43, v35
	v_add_co_u32_e32 v36, vcc, s68, v12
	v_cvt_pk_bf16_f32 v35, v35, s0
	s_nop 0
	v_addc_co_u32_e32 v37, vcc, 0, v13, vcc
	global_store_short v[36:37], v35, off offset:3072
	s_waitcnt vmcnt(14)
	v_lshlrev_b32_e32 v35, 16, v54
	v_mul_f32_e32 v36, 0xbfb8aa3b, v35
	v_exp_f32_e32 v36, v36
	s_nop 0
	v_add_f32_e32 v36, 1.0, v36
	v_rcp_f32_e32 v38, v36
	s_nop 0
	v_mul_f32_e32 v35, v35, v38
	v_mul_f32_e32 v35, v45, v35
	v_cvt_pk_bf16_f32 v35, v35, s0
	s_mov_b32 s0, 0xb000
	v_add_co_u32_e32 v36, vcc, s0, v12
	s_nop 1
	v_addc_co_u32_e32 v37, vcc, 0, v13, vcc
	global_store_short v[36:37], v35, off offset:1024
	s_waitcnt vmcnt(14)
	v_lshlrev_b32_e32 v35, 16, v55
	v_mul_f32_e32 v36, 0xbfb8aa3b, v35
	v_exp_f32_e32 v36, v36
	s_nop 0
	v_add_f32_e32 v36, 1.0, v36
	v_rcp_f32_e32 v38, v36
	s_nop 0
	v_mul_f32_e32 v35, v35, v38
	v_mul_f32_e32 v35, v47, v35
	v_add_co_u32_e32 v36, vcc, s66, v12
	v_cvt_pk_bf16_f32 v35, v35, s0
	s_nop 0
	v_addc_co_u32_e32 v37, vcc, 0, v13, vcc
	global_store_short v[36:37], v35, off offset:3072
	s_waitcnt vmcnt(14)
	v_lshlrev_b32_e32 v35, 16, v56
	v_mul_f32_e32 v36, 0xbfb8aa3b, v35
	v_exp_f32_e32 v36, v36
	s_nop 0
	v_add_f32_e32 v36, 1.0, v36
	v_rcp_f32_e32 v38, v36
	s_nop 0
	v_mul_f32_e32 v35, v35, v38
	v_mul_f32_e32 v35, v49, v35
	v_cvt_pk_bf16_f32 v35, v35, s0
	s_mov_b32 s0, 0x12000
	v_add_co_u32_e32 v36, vcc, s0, v12
	s_nop 1
	v_addc_co_u32_e32 v37, vcc, 0, v13, vcc
	global_store_short v[36:37], v35, off offset:1024
	s_waitcnt vmcnt(14)
	v_lshlrev_b32_e32 v35, 16, v57
	v_mul_f32_e32 v36, 0xbfb8aa3b, v35
	v_exp_f32_e32 v36, v36
	s_nop 0
	v_add_f32_e32 v36, 1.0, v36
	v_rcp_f32_e32 v38, v36
	s_nop 0
	v_mul_f32_e32 v35, v35, v38
	v_mul_f32_e32 v35, v51, v35
	v_add_co_u32_e32 v36, vcc, s73, v12
	v_cvt_pk_bf16_f32 v35, v35, s0
	s_nop 0
	v_addc_co_u32_e32 v37, vcc, 0, v13, vcc
	global_store_short v[36:37], v35, off offset:3072
	s_waitcnt vmcnt(14)
	v_lshlrev_b32_e32 v35, 16, v58
	v_mul_f32_e32 v36, 0xbfb8aa3b, v35
	v_exp_f32_e32 v36, v36
	s_nop 0
	v_add_f32_e32 v36, 1.0, v36
	v_rcp_f32_e32 v38, v36
	s_nop 0
	v_mul_f32_e32 v35, v35, v38
	v_mul_f32_e32 v35, v32, v35
	s_waitcnt vmcnt(13)
	v_lshlrev_b32_e32 v32, 16, v59
	v_mul_f32_e32 v33, 0xbfb8aa3b, v32
	v_exp_f32_e32 v33, v33
	v_cvt_pk_bf16_f32 v35, v35, s0
	s_mov_b32 s0, 0x19000
	v_add_co_u32_e32 v36, vcc, s0, v12
	v_add_f32_e32 v33, 1.0, v33
	s_nop 0
	v_addc_co_u32_e32 v37, vcc, 0, v13, vcc
	global_store_short v[36:37], v35, off offset:1024
	v_rcp_f32_e32 v36, v33
	s_nop 0
	v_mul_f32_e32 v32, v32, v36
	v_mul_f32_e32 v32, v28, v32
	s_waitcnt vmcnt(13)
	v_lshlrev_b32_e32 v28, 16, v60
	v_mul_f32_e32 v29, 0xbfb8aa3b, v28
	v_exp_f32_e32 v29, v29
	v_cvt_pk_bf16_f32 v35, v32, s0
	v_add_co_u32_e32 v32, vcc, s41, v12
	v_add_f32_e32 v29, 1.0, v29
	s_nop 0
	v_addc_co_u32_e32 v33, vcc, 0, v13, vcc
	global_store_short v[32:33], v35, off offset:3072
	v_rcp_f32_e32 v33, v29
	s_nop 0
	v_mul_f32_e32 v28, v28, v33
	v_mul_f32_e32 v28, v26, v28
	s_waitcnt vmcnt(13)
	v_lshlrev_b32_e32 v26, 16, v61
	v_mul_f32_e32 v27, 0xbfb8aa3b, v26
	v_exp_f32_e32 v27, v27
	v_cvt_pk_bf16_f32 v32, v28, s0
	v_add_co_u32_e32 v28, vcc, s74, v12
	v_add_f32_e32 v27, 1.0, v27
	s_nop 0
	v_addc_co_u32_e32 v29, vcc, 0, v13, vcc
	global_store_short v[28:29], v32, off offset:1024
	v_rcp_f32_e32 v29, v27
	s_nop 0
	v_mul_f32_e32 v26, v26, v29
	v_mul_f32_e32 v26, v22, v26
	s_waitcnt vmcnt(13)
	v_lshlrev_b32_e32 v22, 16, v62
	v_mul_f32_e32 v23, 0xbfb8aa3b, v22
	v_exp_f32_e32 v23, v23
	v_cvt_pk_bf16_f32 v28, v26, s0
	s_mov_b32 s0, 0x23000
	v_add_co_u32_e32 v26, vcc, s0, v12
	v_add_f32_e32 v23, 1.0, v23
	s_nop 0
	v_addc_co_u32_e32 v27, vcc, 0, v13, vcc
	global_store_short v[26:27], v28, off offset:3072
	v_rcp_f32_e32 v27, v23
	s_nop 0
	v_mul_f32_e32 v22, v22, v27
	v_mul_f32_e32 v22, v20, v22
	s_waitcnt vmcnt(13)
	v_lshlrev_b32_e32 v20, 16, v34
	v_mul_f32_e32 v21, 0xbfb8aa3b, v20
	v_exp_f32_e32 v21, v21
	v_cvt_pk_bf16_f32 v26, v22, s0
	s_mov_b32 s0, 0x27000
	v_add_co_u32_e32 v22, vcc, s0, v12
	v_add_f32_e32 v21, 1.0, v21
	s_nop 0
	v_addc_co_u32_e32 v23, vcc, 0, v13, vcc
	global_store_short v[22:23], v26, off offset:1024
	v_rcp_f32_e32 v23, v21
	s_nop 0
	v_mul_f32_e32 v20, v20, v23
	v_mul_f32_e32 v20, v18, v20
	s_waitcnt vmcnt(13)
	v_lshlrev_b32_e32 v18, 16, v31
	v_mul_f32_e32 v19, 0xbfb8aa3b, v18
	v_exp_f32_e32 v19, v19
	v_cvt_pk_bf16_f32 v22, v20, s0
	s_mov_b32 s0, 0x2a000
	v_add_co_u32_e32 v20, vcc, s0, v12
	v_add_f32_e32 v19, 1.0, v19
	s_nop 0
	v_addc_co_u32_e32 v21, vcc, 0, v13, vcc
	global_store_short v[20:21], v22, off offset:3072
	v_rcp_f32_e32 v21, v19
	s_nop 0
	v_mul_f32_e32 v18, v18, v21
	v_mul_f32_e32 v18, v16, v18
	s_waitcnt vmcnt(13)
	v_lshlrev_b32_e32 v16, 16, v25
	v_mul_f32_e32 v17, 0xbfb8aa3b, v16
	v_exp_f32_e32 v17, v17
	v_cvt_pk_bf16_f32 v20, v18, s0
	s_mov_b32 s0, 0x2e000
	v_add_co_u32_e32 v18, vcc, s0, v12
	v_add_f32_e32 v17, 1.0, v17
	s_nop 0
	v_addc_co_u32_e32 v19, vcc, 0, v13, vcc
	global_store_short v[18:19], v20, off offset:1024
	v_rcp_f32_e32 v19, v17
	s_nop 0
	v_mul_f32_e32 v16, v16, v19
	v_mul_f32_e32 v16, v14, v16
	s_waitcnt vmcnt(13)
	v_lshlrev_b32_e32 v14, 16, v24
	v_mul_f32_e32 v15, 0xbfb8aa3b, v14
	v_exp_f32_e32 v15, v15
	v_cvt_pk_bf16_f32 v18, v16, s0
	s_mov_b32 s0, 0x31000
	v_add_co_u32_e32 v16, vcc, s0, v12
	v_add_f32_e32 v15, 1.0, v15
	s_nop 0
	v_addc_co_u32_e32 v17, vcc, 0, v13, vcc
	global_store_short v[16:17], v18, off offset:3072
	v_rcp_f32_e32 v17, v15
	s_nop 0
	v_mul_f32_e32 v14, v14, v17
	v_mul_f32_e32 v14, v0, v14
	v_cvt_pk_bf16_f32 v14, v14, s0
	s_mov_b32 s0, 0x35000
	v_add_co_u32_e32 v12, vcc, s0, v12
	s_nop 1
	v_addc_co_u32_e32 v13, vcc, 0, v13, vcc
	global_store_short v[12:13], v14, off offset:1024
	v_lshl_add_u64 v[12:13], v[8:9], 0, s[18:19]
	s_add_u32 s18, s18, 0x800
	s_addc_u32 s19, s19, 0
	s_add_i32 s24, s24, 16
	s_cmpk_lg_i32 s18, 0x2000
	global_store_dword v[12:13], v0, off
	s_cbranch_scc1 .LBB0_178
	s_mov_b64 s[18:19], 0

.LBB0_191:
	s_waitcnt lgkmcnt(0)
	v_lshl_add_u64 v[34:35], s[26:27], 0, v[8:9]
	v_add_co_u32_e32 v14, vcc, 0x15205000, v34
	v_lshl_add_u64 v[12:13], s[26:27], 0, v[6:7]
	s_nop 0
	v_addc_co_u32_e32 v15, vcc, 0, v35, vcc
	v_add_co_u32_e32 v16, vcc, 0x17245000, v34
	global_load_dword v24, v[14:15], off
	s_nop 0
	v_addc_co_u32_e32 v17, vcc, 0, v35, vcc
	global_load_dword v38, v[16:17], off
	global_load_dword v39, v[14:15], off offset:2048
	global_load_dword v40, v[16:17], off offset:2048
	v_add_co_u32_e32 v14, vcc, 0x15206000, v34
	s_mov_b32 s17, 0x35a5000
	s_nop 0
	v_addc_co_u32_e32 v15, vcc, 0, v35, vcc
	v_add_co_u32_e32 v16, vcc, 0x17246000, v34
	global_load_dword v41, v[14:15], off
	s_nop 0
	v_addc_co_u32_e32 v17, vcc, 0, v35, vcc
	global_load_dword v42, v[16:17], off
	global_load_dword v43, v[14:15], off offset:2048
	global_load_dword v44, v[16:17], off offset:2048
	v_add_co_u32_e32 v14, vcc, 0x15207000, v34
	v_lshl_add_u64 v[8:9], v[8:9], 0, s[24:25]
	s_nop 0
	v_addc_co_u32_e32 v15, vcc, 0, v35, vcc
	v_add_co_u32_e32 v16, vcc, 0x17247000, v34
	global_load_dword v45, v[14:15], off
	s_nop 0
	v_addc_co_u32_e32 v17, vcc, 0, v35, vcc
	global_load_dword v46, v[16:17], off
	global_load_dword v47, v[14:15], off offset:2048
	global_load_dword v48, v[16:17], off offset:2048
	v_add_co_u32_e32 v14, vcc, 0x15208000, v34
	s_waitcnt vmcnt(10)
	v_fmac_f32_e32 v38, v11, v24
	v_addc_co_u32_e32 v15, vcc, 0, v35, vcc
	v_add_co_u32_e32 v16, vcc, 0x17248000, v34
	global_load_dword v49, v[14:15], off
	s_nop 0
	v_addc_co_u32_e32 v17, vcc, 0, v35, vcc
	global_load_dword v31, v[16:17], off
	global_load_dword v32, v[14:15], off offset:2048
	global_load_dword v27, v[16:17], off offset:2048
	v_add_co_u32_e32 v14, vcc, 0x15209000, v34
	s_waitcnt vmcnt(12)
	v_fmac_f32_e32 v40, v38, v39
	v_addc_co_u32_e32 v15, vcc, 0, v35, vcc
	v_add_co_u32_e32 v16, vcc, 0x17249000, v34
	global_load_dword v28, v[14:15], off
	s_nop 0
	v_addc_co_u32_e32 v17, vcc, 0, v35, vcc
	global_load_dword v25, v[16:17], off
	global_load_dword v26, v[14:15], off offset:2048
	global_load_dword v22, v[16:17], off offset:2048
	v_add_co_u32_e32 v14, vcc, 0x1520a000, v34
	s_waitcnt vmcnt(14)
	v_fmac_f32_e32 v42, v40, v41
	v_addc_co_u32_e32 v15, vcc, 0, v35, vcc
	v_add_co_u32_e32 v16, vcc, 0x1724a000, v34
	global_load_dword v23, v[14:15], off
	s_nop 0
	v_addc_co_u32_e32 v17, vcc, 0, v35, vcc
	global_load_dword v20, v[16:17], off
	global_load_dword v21, v[14:15], off offset:2048
	global_load_dword v18, v[16:17], off offset:2048
	v_add_co_u32_e32 v14, vcc, 0x1520b000, v34
	s_waitcnt vmcnt(16)
	v_fmac_f32_e32 v44, v42, v43
	v_addc_co_u32_e32 v15, vcc, 0, v35, vcc
	v_add_co_u32_e32 v36, vcc, 0x1724b000, v34
	global_load_dword v19, v[14:15], off
	s_nop 0
	v_addc_co_u32_e32 v37, vcc, 0, v35, vcc
	global_load_dword v16, v[36:37], off
	global_load_dword v17, v[14:15], off offset:2048
	s_nop 0
	global_load_dword v14, v[36:37], off offset:2048
	v_add_co_u32_e32 v36, vcc, 0x1520c000, v34
	s_waitcnt vmcnt(18)
	v_fmac_f32_e32 v46, v44, v45
	v_addc_co_u32_e32 v37, vcc, 0, v35, vcc
	v_add_co_u32_e32 v34, vcc, 0x1724c000, v34
	global_load_dword v15, v[36:37], off
	s_nop 0
	v_addc_co_u32_e32 v35, vcc, 0, v35, vcc
	global_load_dword v0, v[34:35], off
	global_load_dword v3, v[36:37], off offset:2048
	global_load_dword v10, v[34:35], off offset:2048
	v_add_co_u32_e32 v34, vcc, 0x35a6000, v12
	s_waitcnt vmcnt(20)
	v_fmac_f32_e32 v48, v46, v47
	v_addc_co_u32_e32 v35, vcc, 0, v13, vcc
	global_load_ushort v11, v[34:35], off offset:3072
	s_waitcnt vmcnt(19)
	v_fmac_f32_e32 v31, v48, v49
	s_waitcnt vmcnt(17)
	v_fmac_f32_e32 v27, v31, v32
	s_waitcnt vmcnt(15)
	v_fmac_f32_e32 v25, v27, v28
	s_waitcnt vmcnt(13)
	v_fmac_f32_e32 v22, v25, v26
	s_waitcnt vmcnt(11)
	v_fmac_f32_e32 v20, v22, v23
	s_waitcnt vmcnt(9)
	v_fmac_f32_e32 v18, v20, v21
	s_waitcnt vmcnt(7)
	v_fmac_f32_e32 v16, v18, v19
	s_waitcnt vmcnt(5)
	v_fmac_f32_e32 v14, v16, v17
	s_waitcnt vmcnt(3)
	v_fmac_f32_e32 v0, v14, v15
	s_waitcnt vmcnt(0)
	v_lshlrev_b32_e32 v11, 16, v11
	v_mul_f32_e32 v24, 0xbfb8aa3b, v11
	v_exp_f32_e32 v24, v24
	s_nop 0
	v_add_f32_e32 v24, 1.0, v24
	v_div_scale_f32 v29, s[18:19], v24, v24, v11
	v_rcp_f32_e32 v33, v29
	s_nop 0
	v_fma_f32 v34, -v29, v33, 1.0
	v_fmac_f32_e32 v33, v34, v33
	v_div_scale_f32 v34, vcc, v11, v24, v11
	v_mul_f32_e32 v35, v34, v33
	v_fma_f32 v36, -v29, v35, v34
	v_fmac_f32_e32 v35, v36, v33
	v_fma_f32 v29, -v29, v35, v34
	v_div_fmas_f32 v29, v29, v33, v35
	v_add_co_u32_e32 v34, vcc, s17, v12
	s_mov_b32 s17, 0x35aa000
	s_nop 0
	v_addc_co_u32_e32 v35, vcc, 0, v13, vcc
	v_add_co_u32_e32 v36, vcc, s17, v12
	s_mov_b32 s17, 0x35ad000
	s_nop 0
	v_addc_co_u32_e32 v37, vcc, 0, v13, vcc
	global_load_ushort v51, v[36:37], off offset:1024
	v_add_co_u32_e32 v36, vcc, s17, v12
	s_mov_b32 s17, 0x35b1000
	s_nop 0
	v_addc_co_u32_e32 v37, vcc, 0, v13, vcc
	global_load_ushort v52, v[36:37], off offset:3072
	v_add_co_u32_e32 v36, vcc, s17, v12
	s_mov_b32 s17, 0x35b4000
	s_nop 0
	v_addc_co_u32_e32 v37, vcc, 0, v13, vcc
	global_load_ushort v53, v[36:37], off offset:1024
	v_add_co_u32_e32 v36, vcc, s17, v12
	s_mov_b32 s17, 0x35b8000
	s_nop 0
	v_addc_co_u32_e32 v37, vcc, 0, v13, vcc
	global_load_ushort v54, v[36:37], off offset:3072
	v_add_co_u32_e32 v36, vcc, s17, v12
	s_mov_b32 s17, 0x35bb000
	s_nop 0
	v_addc_co_u32_e32 v37, vcc, 0, v13, vcc
	global_load_ushort v55, v[36:37], off offset:1024
	v_add_co_u32_e32 v36, vcc, s17, v12
	s_mov_b32 s17, 0x35bf000
	s_nop 0
	v_addc_co_u32_e32 v37, vcc, 0, v13, vcc
	global_load_ushort v56, v[36:37], off offset:3072
	v_add_co_u32_e32 v36, vcc, s17, v12
	s_mov_b32 s17, 0x35c2000
	s_nop 0
	v_addc_co_u32_e32 v37, vcc, 0, v13, vcc
	global_load_ushort v57, v[36:37], off offset:1024
	v_add_co_u32_e32 v36, vcc, s17, v12
	s_mov_b32 s17, 0x35c6000
	s_nop 0
	v_addc_co_u32_e32 v37, vcc, 0, v13, vcc
	global_load_ushort v58, v[36:37], off offset:3072
	v_add_co_u32_e32 v36, vcc, s17, v12
	s_mov_b32 s17, 0x35c9000
	s_nop 0
	v_addc_co_u32_e32 v37, vcc, 0, v13, vcc
	global_load_ushort v59, v[36:37], off offset:1024
	v_add_co_u32_e32 v36, vcc, s17, v12
	s_mov_b32 s17, 0x35cd000
	s_nop 0
	v_addc_co_u32_e32 v37, vcc, 0, v13, vcc
	v_div_fixup_f32 v11, v29, v24, v11
	global_load_ushort v60, v[36:37], off offset:3072
	v_add_co_u32_e32 v36, vcc, s17, v12
	v_mul_f32_e32 v11, v38, v11
	s_nop 0
	v_addc_co_u32_e32 v37, vcc, 0, v13, vcc
	s_mov_b32 s17, 0x35d0000
	v_cvt_pk_bf16_f32 v50, v11, s0
	global_load_ushort v61, v[36:37], off offset:1024
	v_add_co_u32_e32 v36, vcc, s17, v12
	s_mov_b32 s17, 0x35d4000
	s_nop 0
	v_addc_co_u32_e32 v37, vcc, 0, v13, vcc
	global_store_short v[34:35], v50, off offset:3072
	global_load_ushort v33, v[36:37], off offset:3072
	v_add_co_u32_e32 v36, vcc, s17, v12
	s_mov_b32 s17, 0x35d7000
	s_nop 0
	v_addc_co_u32_e32 v37, vcc, 0, v13, vcc
	global_load_ushort v29, v[36:37], off offset:1024
	v_add_co_u32_e32 v36, vcc, s17, v12
	s_mov_b32 s17, 0x35db000
	s_waitcnt vmcnt(13)
	v_lshlrev_b32_e32 v34, 16, v51
	v_mul_f32_e32 v35, 0xbfb8aa3b, v34
	v_exp_f32_e32 v35, v35
	v_addc_co_u32_e32 v37, vcc, 0, v13, vcc
	global_load_ushort v11, v[36:37], off offset:3072
	v_add_co_u32_e32 v36, vcc, s17, v12
	v_add_f32_e32 v35, 1.0, v35
	s_nop 0
	v_addc_co_u32_e32 v37, vcc, 0, v13, vcc
	global_load_ushort v24, v[36:37], off offset:1024
	v_div_scale_f32 v36, s[18:19], v35, v35, v34
	v_rcp_f32_e32 v37, v36
	s_mov_b32 s17, 0x35a9000
	v_fma_f32 v38, -v36, v37, 1.0
	v_fmac_f32_e32 v37, v38, v37
	v_div_scale_f32 v38, vcc, v34, v35, v34
	v_mul_f32_e32 v39, v38, v37
	v_fma_f32 v50, -v36, v39, v38
	v_fmac_f32_e32 v39, v50, v37
	v_fma_f32 v36, -v36, v39, v38
	v_div_fmas_f32 v36, v36, v37, v39
	v_div_fixup_f32 v34, v36, v35, v34
	v_mul_f32_e32 v34, v40, v34
	v_cvt_pk_bf16_f32 v36, v34, s0
	v_add_co_u32_e32 v34, vcc, s17, v12
	s_mov_b32 s17, 0x35ac000
	s_nop 0
	v_addc_co_u32_e32 v35, vcc, 0, v13, vcc
	global_store_short v[34:35], v36, off offset:1024
	s_waitcnt vmcnt(15)
	v_lshlrev_b32_e32 v34, 16, v52
	v_mul_f32_e32 v35, 0xbfb8aa3b, v34
	v_exp_f32_e32 v35, v35
	s_waitcnt vmcnt(2)
	v_lshlrev_b32_e32 v11, 16, v11
	v_add_f32_e32 v35, 1.0, v35
	v_rcp_f32_e32 v37, v35
	s_nop 0
	v_mul_f32_e32 v34, v34, v37
	v_mul_f32_e32 v34, v42, v34
	v_cvt_pk_bf16_f32 v36, v34, s0
	v_add_co_u32_e32 v34, vcc, s17, v12
	s_mov_b32 s17, 0x35b0000
	s_nop 0
	v_addc_co_u32_e32 v35, vcc, 0, v13, vcc
	global_store_short v[34:35], v36, off offset:3072
	v_lshlrev_b32_e32 v34, 16, v53
	v_mul_f32_e32 v35, 0xbfb8aa3b, v34
	v_exp_f32_e32 v35, v35
	s_nop 0
	v_add_f32_e32 v35, 1.0, v35
	v_rcp_f32_e32 v37, v35
	s_nop 0
	v_mul_f32_e32 v34, v34, v37
	v_mul_f32_e32 v34, v44, v34
	v_cvt_pk_bf16_f32 v36, v34, s0
	v_add_co_u32_e32 v34, vcc, s17, v12
	s_mov_b32 s17, 0x35b3000
	s_nop 0
	v_addc_co_u32_e32 v35, vcc, 0, v13, vcc
	global_store_short v[34:35], v36, off offset:1024
	v_lshlrev_b32_e32 v34, 16, v54
	v_mul_f32_e32 v35, 0xbfb8aa3b, v34
	v_exp_f32_e32 v35, v35
	s_nop 0
	v_add_f32_e32 v35, 1.0, v35
	v_rcp_f32_e32 v37, v35
	s_nop 0
	v_mul_f32_e32 v34, v34, v37
	v_mul_f32_e32 v34, v46, v34
	v_cvt_pk_bf16_f32 v36, v34, s0
	v_add_co_u32_e32 v34, vcc, s17, v12
	s_mov_b32 s17, 0x35b7000
	s_nop 0
	v_addc_co_u32_e32 v35, vcc, 0, v13, vcc
	global_store_short v[34:35], v36, off offset:3072
	v_lshlrev_b32_e32 v34, 16, v55
	v_mul_f32_e32 v35, 0xbfb8aa3b, v34
	v_exp_f32_e32 v35, v35
	s_nop 0
	v_add_f32_e32 v35, 1.0, v35
	v_rcp_f32_e32 v37, v35
	s_nop 0
	v_mul_f32_e32 v34, v34, v37
	v_mul_f32_e32 v34, v48, v34
	v_cvt_pk_bf16_f32 v36, v34, s0
	v_add_co_u32_e32 v34, vcc, s17, v12
	s_mov_b32 s17, 0x35ba000
	s_nop 0
	v_addc_co_u32_e32 v35, vcc, 0, v13, vcc
	global_store_short v[34:35], v36, off offset:1024
	v_lshlrev_b32_e32 v34, 16, v56
	v_mul_f32_e32 v35, 0xbfb8aa3b, v34
	v_exp_f32_e32 v35, v35
	s_nop 0
	v_add_f32_e32 v35, 1.0, v35
	v_rcp_f32_e32 v37, v35
	s_nop 0
	v_mul_f32_e32 v34, v34, v37
	v_mul_f32_e32 v34, v31, v34
	v_lshlrev_b32_e32 v31, 16, v57
	v_mul_f32_e32 v32, 0xbfb8aa3b, v31
	v_exp_f32_e32 v32, v32
	v_cvt_pk_bf16_f32 v36, v34, s0
	v_add_co_u32_e32 v34, vcc, s17, v12
	v_add_f32_e32 v32, 1.0, v32
	s_nop 0
	v_addc_co_u32_e32 v35, vcc, 0, v13, vcc
	global_store_short v[34:35], v36, off offset:3072
	v_div_scale_f32 v34, s[18:19], v32, v32, v31
	v_rcp_f32_e32 v35, v34
	s_mov_b32 s17, 0x35be000
	v_fma_f32 v36, -v34, v35, 1.0
	v_fmac_f32_e32 v35, v36, v35
	v_div_scale_f32 v36, vcc, v31, v32, v31
	v_mul_f32_e32 v37, v36, v35
	v_fma_f32 v38, -v34, v37, v36
	v_fmac_f32_e32 v37, v38, v35
	v_fma_f32 v34, -v34, v37, v36
	v_div_fmas_f32 v34, v34, v35, v37
	v_div_fixup_f32 v31, v34, v32, v31
	v_mul_f32_e32 v31, v27, v31
	v_lshlrev_b32_e32 v27, 16, v58
	v_mul_f32_e32 v28, 0xbfb8aa3b, v27
	v_exp_f32_e32 v28, v28
	v_add_co_u32_e32 v34, vcc, s17, v12
	v_cvt_pk_bf16_f32 v31, v31, s0
	s_nop 0
	v_addc_co_u32_e32 v35, vcc, 0, v13, vcc
	v_add_f32_e32 v28, 1.0, v28
	global_store_short v[34:35], v31, off offset:1024
	v_div_scale_f32 v31, s[18:19], v28, v28, v27
	v_rcp_f32_e32 v32, v31
	s_mov_b32 s17, 0x35c1000
	v_fma_f32 v34, -v31, v32, 1.0
	v_fmac_f32_e32 v32, v34, v32
	v_div_scale_f32 v34, vcc, v27, v28, v27
	v_mul_f32_e32 v35, v34, v32
	v_fma_f32 v36, -v31, v35, v34
	v_fmac_f32_e32 v35, v36, v32
	v_fma_f32 v31, -v31, v35, v34
	v_div_fmas_f32 v31, v31, v32, v35
	v_div_fixup_f32 v27, v31, v28, v27
	v_mul_f32_e32 v27, v25, v27
	v_lshlrev_b32_e32 v25, 16, v59
	v_mul_f32_e32 v26, 0xbfb8aa3b, v25
	v_exp_f32_e32 v26, v26
	v_add_co_u32_e32 v34, vcc, s17, v12
	v_cvt_pk_bf16_f32 v27, v27, s0
	s_nop 0
	v_addc_co_u32_e32 v35, vcc, 0, v13, vcc
	v_add_f32_e32 v26, 1.0, v26
	global_store_short v[34:35], v27, off offset:3072
	v_div_scale_f32 v27, s[18:19], v26, v26, v25
	v_rcp_f32_e32 v28, v27
	s_mov_b32 s17, 0x35c5000
	v_fma_f32 v31, -v27, v28, 1.0
	v_fmac_f32_e32 v28, v31, v28
	v_div_scale_f32 v31, vcc, v25, v26, v25
	v_mul_f32_e32 v32, v31, v28
	v_fma_f32 v34, -v27, v32, v31
	v_fmac_f32_e32 v32, v34, v28
	v_fma_f32 v27, -v27, v32, v31
	v_div_fmas_f32 v27, v27, v28, v32
	v_div_fixup_f32 v25, v27, v26, v25
	v_mul_f32_e32 v25, v22, v25
	v_lshlrev_b32_e32 v22, 16, v60
	v_mul_f32_e32 v23, 0xbfb8aa3b, v22
	v_exp_f32_e32 v23, v23
	v_add_co_u32_e32 v26, vcc, s17, v12
	v_cvt_pk_bf16_f32 v25, v25, s0
	s_nop 0
	v_addc_co_u32_e32 v27, vcc, 0, v13, vcc
	v_add_f32_e32 v23, 1.0, v23
	global_store_short v[26:27], v25, off offset:1024
	v_div_scale_f32 v25, s[18:19], v23, v23, v22
	v_rcp_f32_e32 v26, v25
	s_mov_b32 s17, 0x35c8000
	v_fma_f32 v27, -v25, v26, 1.0
	v_fmac_f32_e32 v26, v27, v26
	v_div_scale_f32 v27, vcc, v22, v23, v22
	v_mul_f32_e32 v28, v27, v26
	v_fma_f32 v31, -v25, v28, v27
	v_fmac_f32_e32 v28, v31, v26
	v_fma_f32 v25, -v25, v28, v27
	v_div_fmas_f32 v25, v25, v26, v28
	v_div_fixup_f32 v22, v25, v23, v22
	v_mul_f32_e32 v22, v20, v22
	v_lshlrev_b32_e32 v20, 16, v61
	v_mul_f32_e32 v21, 0xbfb8aa3b, v20
	v_exp_f32_e32 v21, v21
	v_cvt_pk_bf16_f32 v25, v22, s0
	v_add_co_u32_e32 v22, vcc, s17, v12
	v_add_f32_e32 v21, 1.0, v21
	s_nop 0
	v_addc_co_u32_e32 v23, vcc, 0, v13, vcc
	global_store_short v[22:23], v25, off offset:3072
	v_div_scale_f32 v22, s[18:19], v21, v21, v20
	v_rcp_f32_e32 v23, v22
	s_mov_b32 s17, 0x35cc000
	v_fma_f32 v25, -v22, v23, 1.0
	v_fmac_f32_e32 v23, v25, v23
	v_div_scale_f32 v25, vcc, v20, v21, v20
	v_mul_f32_e32 v26, v25, v23
	v_fma_f32 v27, -v22, v26, v25
	v_fmac_f32_e32 v26, v27, v23
	v_fma_f32 v22, -v22, v26, v25
	v_div_fmas_f32 v22, v22, v23, v26
	v_div_fixup_f32 v20, v22, v21, v20
	v_mul_f32_e32 v20, v18, v20
	v_lshlrev_b32_e32 v18, 16, v33
	v_mul_f32_e32 v19, 0xbfb8aa3b, v18
	v_exp_f32_e32 v19, v19
	v_cvt_pk_bf16_f32 v22, v20, s0
	v_add_co_u32_e32 v20, vcc, s17, v12
	v_add_f32_e32 v19, 1.0, v19
	s_nop 0
	v_addc_co_u32_e32 v21, vcc, 0, v13, vcc
	global_store_short v[20:21], v22, off offset:1024
	v_div_scale_f32 v20, s[18:19], v19, v19, v18
	v_rcp_f32_e32 v21, v20
	s_mov_b32 s17, 0x35cf000
	v_fma_f32 v22, -v20, v21, 1.0
	v_fmac_f32_e32 v21, v22, v21
	v_div_scale_f32 v22, vcc, v18, v19, v18
	v_mul_f32_e32 v23, v22, v21
	v_fma_f32 v25, -v20, v23, v22
	v_fmac_f32_e32 v23, v25, v21
	v_fma_f32 v20, -v20, v23, v22
	v_div_fmas_f32 v20, v20, v21, v23
	v_div_fixup_f32 v18, v20, v19, v18
	v_mul_f32_e32 v18, v16, v18
	v_lshlrev_b32_e32 v16, 16, v29
	v_mul_f32_e32 v17, 0xbfb8aa3b, v16
	v_exp_f32_e32 v17, v17
	v_cvt_pk_bf16_f32 v20, v18, s0
	v_add_co_u32_e32 v18, vcc, s17, v12
	v_add_f32_e32 v17, 1.0, v17
	s_nop 0
	v_addc_co_u32_e32 v19, vcc, 0, v13, vcc
	global_store_short v[18:19], v20, off offset:3072
	v_div_scale_f32 v18, s[18:19], v17, v17, v16
	v_rcp_f32_e32 v19, v18
	s_mov_b32 s17, 0x35d3000
	v_fma_f32 v20, -v18, v19, 1.0
	v_fmac_f32_e32 v19, v20, v19
	v_div_scale_f32 v20, vcc, v16, v17, v16
	v_mul_f32_e32 v21, v20, v19
	v_fma_f32 v22, -v18, v21, v20
	v_fmac_f32_e32 v21, v22, v19
	v_fma_f32 v18, -v18, v21, v20
	v_div_fmas_f32 v18, v18, v19, v21
	v_div_fixup_f32 v16, v18, v17, v16
	v_mul_f32_e32 v16, v14, v16
	v_mul_f32_e32 v14, 0xbfb8aa3b, v11
	v_exp_f32_e32 v14, v14
	v_cvt_pk_bf16_f32 v18, v16, s0
	v_add_co_u32_e32 v16, vcc, s17, v12
	v_add_f32_e32 v14, 1.0, v14
	s_nop 0
	v_addc_co_u32_e32 v17, vcc, 0, v13, vcc
	v_div_scale_f32 v15, s[18:19], v14, v14, v11
	global_store_short v[16:17], v18, off offset:1024
	v_rcp_f32_e32 v16, v15
	s_mov_b32 s17, 0x35d6000
	v_fma_f32 v17, -v15, v16, 1.0
	v_fmac_f32_e32 v16, v17, v16
	v_div_scale_f32 v17, vcc, v11, v14, v11
	v_mul_f32_e32 v18, v17, v16
	v_fma_f32 v19, -v15, v18, v17
	v_fmac_f32_e32 v18, v19, v16
	v_fma_f32 v15, -v15, v18, v17
	v_div_fmas_f32 v15, v15, v16, v18
	v_div_fixup_f32 v11, v15, v14, v11
	v_mul_f32_e32 v11, v0, v11
	v_add_co_u32_e32 v14, vcc, s17, v12
	v_cvt_pk_bf16_f32 v11, v11, s0
	s_nop 0
	v_addc_co_u32_e32 v15, vcc, 0, v13, vcc
	global_store_short v[14:15], v11, off offset:3072
	v_mov_b32_e32 v11, v10
	v_fmac_f32_e32 v11, v0, v3
	s_waitcnt vmcnt(14)
	v_lshlrev_b32_e32 v0, 16, v24
	v_mul_f32_e32 v3, 0xbfb8aa3b, v0
	v_exp_f32_e32 v3, v3
	s_nop 0
	v_add_f32_e32 v3, 1.0, v3
	v_div_scale_f32 v10, s[18:19], v3, v3, v0
	v_rcp_f32_e32 v14, v10
	s_mov_b64 s[18:19], 0x38000
	v_lshl_add_u64 v[6:7], v[6:7], 0, s[18:19]
	v_fma_f32 v15, -v10, v14, 1.0
	v_fmac_f32_e32 v14, v15, v14
	v_div_scale_f32 v15, vcc, v0, v3, v0
	v_mul_f32_e32 v16, v15, v14
	v_fma_f32 v17, -v10, v16, v15
	v_fmac_f32_e32 v16, v17, v14
	v_fma_f32 v10, -v10, v16, v15
	v_div_fmas_f32 v10, v10, v14, v16
	v_div_fixup_f32 v0, v10, v3, v0
	v_mul_f32_e32 v0, v11, v0
	v_cvt_pk_bf16_f32 v0, v0, s0
	v_add_co_u32_e32 v12, vcc, 0x35da000, v12
	s_add_i32 s0, s0, 16
	s_nop 0
	v_addc_co_u32_e32 v13, vcc, 0, v13, vcc
	s_cmp_gt_u32 s0, 47
	global_store_short v[12:13], v0, off offset:1024
	s_cbranch_scc0 .LBB0_191
	v_cmp_ne_u64_e32 vcc, 0, v[4:5]
	s_and_saveexec_b64 s[18:19], vcc
	s_cbranch_execz .LBB0_194
	global_store_dword v[4:5], v11, off

.LBB0_196:
	s_andn2_b64 vcc, exec, s[18:19]
	s_cbranch_vccnz .LBB0_200
	v_ashrrev_i32_e32 v0, 1, v2
	v_and_b32_e32 v18, 15, v30
	v_and_b32_e32 v10, 0xffffffe0, v0
	v_or_b32_e32 v2, v10, v18
	s_lshl_b32 s0, s58, 11
	s_lshr_b32 s24, s57, 3
	v_ashrrev_i32_e32 v3, 31, v2
	s_and_b32 s17, s0, 0x38000
	s_lshl_b32 s0, s24, 9
	v_lshlrev_b64 v[4:5], 10, v[2:3]
	v_or_b32_e32 v2, 16, v2
	s_lshl_b64 s[18:19], s[0:1], 1
	s_lshl_b32 s0, s24, 8
	v_ashrrev_i32_e32 v3, 31, v2
	s_lshl_b64 s[24:25], s[0:1], 10
	v_lshlrev_b64 v[2:3], 10, v[2:3]
	v_lshlrev_b32_e32 v0, 11, v18
	s_waitcnt vmcnt(0)
	v_and_b32_e32 v6, 48, v30
	s_add_u32 s18, s55, s18
	v_lshl_add_u64 v[4:5], v[4:5], 0, s[24:25]
	v_lshl_add_u64 v[2:3], v[2:3], 0, s[24:25]
	v_or3_b32 v0, s17, v0, v6
	s_addc_u32 s19, s56, s19
	v_or_b32_e32 v4, v4, v6
	v_or_b32_e32 v2, v2, v6
	v_mov_b32_e32 v6, 0
	s_movk_i32 s0, 0xffe0
	v_lshl_add_u64 v[12:13], s[18:19], 0, v[0:1]
	v_lshl_add_u64 v[14:15], s[14:15], 0, v[4:5]
	v_lshl_add_u64 v[16:17], s[14:15], 0, v[2:3]
	v_mov_b32_e32 v7, v6
	v_mov_b32_e32 v8, v6
	v_mov_b32_e32 v9, v6
	v_mov_b32_e32 v2, v6
	v_mov_b32_e32 v3, v6
	v_mov_b32_e32 v4, v6
	v_mov_b32_e32 v5, v6
	global_load_dwordx4 v[20:23], v[12:13], off offset:-256
	global_load_dwordx4 v[24:27], v[14:15], off offset:-256
	global_load_dwordx4 v[32:35], v[16:17], off offset:-256
	global_load_dwordx4 v[96:99], v[12:13], off offset:-192
	global_load_dwordx4 v[100:103], v[14:15], off offset:-192
	global_load_dwordx4 v[104:107], v[16:17], off offset:-192
	global_load_dwordx4 v[108:111], v[12:13], off offset:-128
	global_load_dwordx4 v[112:115], v[14:15], off offset:-128
	global_load_dwordx4 v[116:119], v[16:17], off offset:-128
	global_load_dwordx4 v[120:123], v[12:13], off offset:-64
	global_load_dwordx4 v[124:127], v[14:15], off offset:-64
	global_load_dwordx4 v[128:131], v[16:17], off offset:-64
	global_load_dwordx4 v[132:135], v[12:13], off
	global_load_dwordx4 v[136:139], v[14:15], off
	global_load_dwordx4 v[140:143], v[16:17], off
	global_load_dwordx4 v[144:147], v[12:13], off offset:64
	global_load_dwordx4 v[148:151], v[14:15], off offset:64
	global_load_dwordx4 v[152:155], v[16:17], off offset:64
	global_load_dwordx4 v[156:159], v[12:13], off offset:128
	global_load_dwordx4 v[160:163], v[14:15], off offset:128
	global_load_dwordx4 v[164:167], v[16:17], off offset:128
	global_load_dwordx4 v[172:175], v[12:13], off offset:192
	global_load_dwordx4 v[176:179], v[14:15], off offset:192
	global_load_dwordx4 v[180:183], v[16:17], off offset:192
	v_lshl_add_u64 v[12:13], v[12:13], 0, s[22:23]
	v_lshl_add_u64 v[14:15], v[14:15], 0, s[22:23]
	v_lshl_add_u64 v[16:17], v[16:17], 0, s[22:23]
.Lsg2_loop:
	s_addk_i32 s0, 0x100
	s_cmpk_lt_u32 s0, 0x1e0
	s_cbranch_scc0 .Lsg2_tail
	s_waitcnt vmcnt(21)
	v_mfma_f32_16x16x32_bf16 v[6:9], v[20:23], v[24:27], v[6:9]
	v_mfma_f32_16x16x32_bf16 v[2:5], v[20:23], v[32:35], v[2:5]
	global_load_dwordx4 v[20:23], v[12:13], off offset:-256
	global_load_dwordx4 v[24:27], v[14:15], off offset:-256
	global_load_dwordx4 v[32:35], v[16:17], off offset:-256
	s_waitcnt vmcnt(21)
	v_mfma_f32_16x16x32_bf16 v[6:9], v[96:99], v[100:103], v[6:9]
	v_mfma_f32_16x16x32_bf16 v[2:5], v[96:99], v[104:107], v[2:5]
	global_load_dwordx4 v[96:99], v[12:13], off offset:-192
	global_load_dwordx4 v[100:103], v[14:15], off offset:-192
	global_load_dwordx4 v[104:107], v[16:17], off offset:-192
	s_waitcnt vmcnt(21)
	v_mfma_f32_16x16x32_bf16 v[6:9], v[108:111], v[112:115], v[6:9]
	v_mfma_f32_16x16x32_bf16 v[2:5], v[108:111], v[116:119], v[2:5]
	global_load_dwordx4 v[108:111], v[12:13], off offset:-128
	global_load_dwordx4 v[112:115], v[14:15], off offset:-128
	global_load_dwordx4 v[116:119], v[16:17], off offset:-128
	s_waitcnt vmcnt(21)
	v_mfma_f32_16x16x32_bf16 v[6:9], v[120:123], v[124:127], v[6:9]
	v_mfma_f32_16x16x32_bf16 v[2:5], v[120:123], v[128:131], v[2:5]
	global_load_dwordx4 v[120:123], v[12:13], off offset:-64
	global_load_dwordx4 v[124:127], v[14:15], off offset:-64
	global_load_dwordx4 v[128:131], v[16:17], off offset:-64
	s_waitcnt vmcnt(21)
	v_mfma_f32_16x16x32_bf16 v[6:9], v[132:135], v[136:139], v[6:9]
	v_mfma_f32_16x16x32_bf16 v[2:5], v[132:135], v[140:143], v[2:5]
	global_load_dwordx4 v[132:135], v[12:13], off
	global_load_dwordx4 v[136:139], v[14:15], off
	global_load_dwordx4 v[140:143], v[16:17], off
	s_waitcnt vmcnt(21)
	v_mfma_f32_16x16x32_bf16 v[6:9], v[144:147], v[148:151], v[6:9]
	v_mfma_f32_16x16x32_bf16 v[2:5], v[144:147], v[152:155], v[2:5]
	global_load_dwordx4 v[144:147], v[12:13], off offset:64
	global_load_dwordx4 v[148:151], v[14:15], off offset:64
	global_load_dwordx4 v[152:155], v[16:17], off offset:64
	s_waitcnt vmcnt(21)
	v_mfma_f32_16x16x32_bf16 v[6:9], v[156:159], v[160:163], v[6:9]
	v_mfma_f32_16x16x32_bf16 v[2:5], v[156:159], v[164:167], v[2:5]
	global_load_dwordx4 v[156:159], v[12:13], off offset:128
	global_load_dwordx4 v[160:163], v[14:15], off offset:128
	global_load_dwordx4 v[164:167], v[16:17], off offset:128
	s_waitcnt vmcnt(21)
	v_mfma_f32_16x16x32_bf16 v[6:9], v[172:175], v[176:179], v[6:9]
	v_mfma_f32_16x16x32_bf16 v[2:5], v[172:175], v[180:183], v[2:5]
	global_load_dwordx4 v[172:175], v[12:13], off offset:192
	global_load_dwordx4 v[176:179], v[14:15], off offset:192
	global_load_dwordx4 v[180:183], v[16:17], off offset:192
	v_lshl_add_u64 v[12:13], v[12:13], 0, s[22:23]
	v_lshl_add_u64 v[14:15], v[14:15], 0, s[22:23]
	v_lshl_add_u64 v[16:17], v[16:17], 0, s[22:23]
	s_branch .Lsg2_loop
.Lsg2_tail:
	s_waitcnt vmcnt(21)
	v_mfma_f32_16x16x32_bf16 v[6:9], v[20:23], v[24:27], v[6:9]
	v_mfma_f32_16x16x32_bf16 v[2:5], v[20:23], v[32:35], v[2:5]
	s_waitcnt vmcnt(18)
	v_mfma_f32_16x16x32_bf16 v[6:9], v[96:99], v[100:103], v[6:9]
	v_mfma_f32_16x16x32_bf16 v[2:5], v[96:99], v[104:107], v[2:5]
	s_waitcnt vmcnt(15)
	v_mfma_f32_16x16x32_bf16 v[6:9], v[108:111], v[112:115], v[6:9]
	v_mfma_f32_16x16x32_bf16 v[2:5], v[108:111], v[116:119], v[2:5]
	s_waitcnt vmcnt(12)
	v_mfma_f32_16x16x32_bf16 v[6:9], v[120:123], v[124:127], v[6:9]
	v_mfma_f32_16x16x32_bf16 v[2:5], v[120:123], v[128:131], v[2:5]
	s_waitcnt vmcnt(9)
	v_mfma_f32_16x16x32_bf16 v[6:9], v[132:135], v[136:139], v[6:9]
	v_mfma_f32_16x16x32_bf16 v[2:5], v[132:135], v[140:143], v[2:5]
	s_waitcnt vmcnt(6)
	v_mfma_f32_16x16x32_bf16 v[6:9], v[144:147], v[148:151], v[6:9]
	v_mfma_f32_16x16x32_bf16 v[2:5], v[144:147], v[152:155], v[2:5]
	s_waitcnt vmcnt(3)
	v_mfma_f32_16x16x32_bf16 v[6:9], v[156:159], v[160:163], v[6:9]
	v_mfma_f32_16x16x32_bf16 v[2:5], v[156:159], v[164:167], v[2:5]
	s_waitcnt vmcnt(0)
	v_mfma_f32_16x16x32_bf16 v[6:9], v[172:175], v[176:179], v[6:9]
	v_mfma_f32_16x16x32_bf16 v[2:5], v[172:175], v[180:183], v[2:5]
	s_add_i32 s0, s62, 0xfffffe7e
	s_lshl_b32 s17, s0, 4
	s_and_b32 s17, s17, 0x70
	v_lshrrev_b32_e32 v0, 2, v30
	v_and_or_b32 v0, v0, 12, s17
	v_or_b32_e32 v0, 0x4000, v0
	v_mul_u32_u24_e32 v0, 0x1c00, v0
	s_lshl_b32 s0, s0, 5
	v_lshlrev_b32_e32 v0, 1, v0
	s_and_b32 s0, s0, 0xffffff00
	v_lshl_add_u64 v[12:13], s[4:5], 0, v[0:1]
	v_ashrrev_i32_e32 v11, 31, v10
	v_lshl_add_u64 v[12:13], s[0:1], 1, v[12:13]
	v_lshl_add_u64 v[10:11], v[10:11], 1, v[12:13]
	v_lshlrev_b32_e32 v0, 1, v18
	v_lshl_add_u64 v[10:11], v[10:11], 0, v[0:1]
	global_load_ushort v0, v[10:11], off offset:1024
	s_waitcnt vmcnt(0)
	v_lshlrev_b32_e32 v0, 16, v0
	v_mul_f32_e32 v12, 0xbfb8aa3b, v0
	v_exp_f32_e32 v12, v12
	s_nop 0
	v_add_f32_e32 v12, 1.0, v12
	v_rcp_f32_e32 v14, v12
	s_nop 0
	v_mul_f32_e32 v0, v0, v14
	v_mul_f32_e32 v0, v6, v0
	v_cvt_pk_bf16_f32 v0, v0, s0
	global_store_short v[10:11], v0, off offset:2048
	global_load_ushort v0, v[10:11], off offset:1056
	s_waitcnt vmcnt(0)
	v_lshlrev_b32_e32 v0, 16, v0
	v_mul_f32_e32 v6, 0xbfb8aa3b, v0
	v_exp_f32_e32 v6, v6
	s_nop 0
	v_add_f32_e32 v6, 1.0, v6
	v_div_scale_f32 v12, s[18:19], v6, v6, v0
	v_rcp_f32_e32 v13, v12
	s_mov_b64 s[18:19], 0x3c00
	v_fma_f32 v14, -v12, v13, 1.0
	v_fmac_f32_e32 v13, v14, v13
	v_div_scale_f32 v14, vcc, v0, v6, v0
	v_mul_f32_e32 v15, v14, v13
	v_fma_f32 v16, -v12, v15, v14
	v_fmac_f32_e32 v15, v16, v13
	v_fma_f32 v12, -v12, v15, v14
	v_div_fmas_f32 v12, v12, v13, v15
	v_div_fixup_f32 v0, v12, v6, v0
	v_mul_f32_e32 v0, v2, v0
	v_cvt_pk_bf16_f32 v0, v0, s0
	s_movk_i32 s0, 0x3000
	v_add_co_u32_e32 v14, vcc, s0, v10
	global_store_short v[10:11], v0, off offset:2080
	s_nop 0
	v_addc_co_u32_e32 v15, vcc, 0, v11, vcc
	global_load_ushort v0, v[14:15], off offset:3072
	v_lshl_add_u64 v[12:13], v[10:11], 0, s[18:19]
	s_waitcnt vmcnt(0)
	v_lshlrev_b32_e32 v0, 16, v0
	v_mul_f32_e32 v2, 0xbfb8aa3b, v0
	v_exp_f32_e32 v2, v2
	s_nop 0
	v_add_f32_e32 v2, 1.0, v2
	v_rcp_f32_e32 v14, v2
	s_nop 0
	v_mul_f32_e32 v0, v0, v14
	v_mul_f32_e32 v0, v7, v0
	v_cvt_pk_bf16_f32 v0, v0, s0
	global_store_short v[12:13], v0, off offset:1024
	global_load_ushort v0, v[12:13], off offset:32
	s_waitcnt vmcnt(0)
	v_lshlrev_b32_e32 v0, 16, v0
	v_mul_f32_e32 v2, 0xbfb8aa3b, v0
	v_exp_f32_e32 v2, v2
	s_nop 0
	v_add_f32_e32 v2, 1.0, v2
	v_div_scale_f32 v6, s[18:19], v2, v2, v0
	v_rcp_f32_e32 v7, v6
	s_mov_b64 s[18:19], 0x7400
	v_fma_f32 v14, -v6, v7, 1.0
	v_fmac_f32_e32 v7, v14, v7
	v_div_scale_f32 v14, vcc, v0, v2, v0
	v_mul_f32_e32 v15, v14, v7
	v_fma_f32 v16, -v6, v15, v14
	v_fmac_f32_e32 v15, v16, v7
	v_fma_f32 v6, -v6, v15, v14
	v_div_fmas_f32 v6, v6, v7, v15
	v_div_fixup_f32 v0, v6, v2, v0
	v_mul_f32_e32 v0, v3, v0
	v_cvt_pk_bf16_f32 v0, v0, s0
	s_movk_i32 s0, 0x7000
	v_add_co_u32_e32 v6, vcc, s0, v10
	global_store_short v[12:13], v0, off offset:1056
	s_nop 0
	v_addc_co_u32_e32 v7, vcc, 0, v11, vcc
	global_load_ushort v0, v[6:7], off offset:1024
	v_lshl_add_u64 v[2:3], v[10:11], 0, s[18:19]
	s_waitcnt vmcnt(0)
	v_lshlrev_b32_e32 v0, 16, v0
	v_mul_f32_e32 v6, 0xbfb8aa3b, v0
	v_exp_f32_e32 v6, v6
	s_nop 0
	v_add_f32_e32 v6, 1.0, v6
	v_rcp_f32_e32 v12, v6
	s_nop 0
	v_mul_f32_e32 v0, v0, v12
	v_mul_f32_e32 v0, v8, v0
	v_cvt_pk_bf16_f32 v0, v0, s0
	global_store_short v[2:3], v0, off offset:1024
	global_load_ushort v0, v[2:3], off offset:32
	s_waitcnt vmcnt(0)
	v_lshlrev_b32_e32 v0, 16, v0
	v_mul_f32_e32 v6, 0xbfb8aa3b, v0
	v_exp_f32_e32 v6, v6
	s_nop 0
	v_add_f32_e32 v6, 1.0, v6
	v_div_scale_f32 v7, s[18:19], v6, v6, v0
	v_rcp_f32_e32 v8, v7
	s_mov_b64 s[18:19], 0xac00
	v_fma_f32 v12, -v7, v8, 1.0
	v_fmac_f32_e32 v8, v12, v8
	v_div_scale_f32 v12, vcc, v0, v6, v0
	v_mul_f32_e32 v13, v12, v8
	v_fma_f32 v14, -v7, v13, v12
	v_fmac_f32_e32 v13, v14, v8
	v_fma_f32 v7, -v7, v13, v12
	v_div_fmas_f32 v7, v7, v8, v13
	v_div_fixup_f32 v0, v7, v6, v0
	v_mul_f32_e32 v0, v4, v0
	v_cvt_pk_bf16_f32 v0, v0, s0
	s_mov_b32 s0, 0xa000
	v_add_co_u32_e32 v6, vcc, s0, v10
	global_store_short v[2:3], v0, off offset:1056
	s_nop 0
	v_addc_co_u32_e32 v7, vcc, 0, v11, vcc
	global_load_ushort v0, v[6:7], off offset:3072
	v_lshl_add_u64 v[2:3], v[10:11], 0, s[18:19]
	s_waitcnt vmcnt(0)
	v_lshlrev_b32_e32 v0, 16, v0
	v_mul_f32_e32 v4, 0xbfb8aa3b, v0
	v_exp_f32_e32 v4, v4
	s_nop 0
	v_add_f32_e32 v4, 1.0, v4
	v_rcp_f32_e32 v7, v4
	s_nop 0
	v_mul_f32_e32 v0, v0, v7
	v_mul_f32_e32 v0, v9, v0
	v_cvt_pk_bf16_f32 v0, v0, s0
	global_store_short v[2:3], v0, off offset:1024
	global_load_ushort v0, v[2:3], off offset:32
	s_waitcnt vmcnt(0)
	v_lshlrev_b32_e32 v0, 16, v0
	v_mul_f32_e32 v4, 0xbfb8aa3b, v0
	v_exp_f32_e32 v4, v4
	s_nop 0
	v_add_f32_e32 v4, 1.0, v4
	v_rcp_f32_e32 v7, v4
	s_nop 0
	v_mul_f32_e32 v0, v0, v7
	v_mul_f32_e32 v0, v5, v0
	v_cvt_pk_bf16_f32 v0, v0, s0
	global_store_short v[2:3], v0, off offset:1056

.LBB0_209:
	v_add_u32_e32 v73, s17, v130
	v_ashrrev_i32_e32 v80, 6, v73
	v_mad_u64_u32 v[78:79], s[18:19], v80, s33, v[0:1]
	v_add_u32_e32 v79, s0, v80
	v_mad_i64_i32 v[86:87], s[18:19], v79, s96, v[66:67]
	global_load_dwordx2 v[88:89], v[86:87], off offset:1024
	ds_read_b128 v[78:81], v78
	s_addk_i32 s17, 0x800
	s_cmpk_eq_i32 s17, 0x2000
	s_waitcnt vmcnt(0)
	v_lshlrev_b32_e32 v92, 16, v88
	v_and_b32_e32 v88, 0xffff0000, v88
	v_mul_f32_e32 v90, 0xbfb8aa3b, v92
	v_mul_f32_e32 v91, 0xbfb8aa3b, v88
	v_exp_f32_e32 v90, v90
	v_exp_f32_e32 v91, v91
	s_nop 0
	v_pk_add_f32 v[90:91], v[90:91], 1.0 op_sel_hi:[1,0]
	s_nop 0
	v_rcp_f32_e32 v94, v91
	s_nop 0
	v_mul_f32_e32 v91, v88, v94
	v_rcp_f32_e32 v93, v90
	s_nop 0
	v_mul_f32_e32 v90, v92, v93
	s_waitcnt lgkmcnt(0)
	v_pk_mul_f32 v[78:79], v[78:79], v[90:91]
	v_lshlrev_b32_e32 v90, 16, v89
	v_and_b32_e32 v91, 0xffff0000, v89
	v_mul_f32_e32 v88, 0xbfb8aa3b, v90
	v_mul_f32_e32 v89, 0xbfb8aa3b, v91
	v_exp_f32_e32 v88, v88
	v_exp_f32_e32 v89, v89
	v_cvt_pk_bf16_f32 v78, v78, v79
	v_pk_add_f32 v[88:89], v[88:89], 1.0 op_sel_hi:[1,0]
	s_nop 0
	v_rcp_f32_e32 v93, v89
	s_nop 0
	v_mul_f32_e32 v89, v91, v93
	v_rcp_f32_e32 v92, v88
	s_nop 0
	v_mul_f32_e32 v88, v90, v92
	v_pk_mul_f32 v[80:81], v[80:81], v[88:89]
	s_nop 0
	v_cvt_pk_bf16_f32 v79, v80, v81
	global_store_dwordx2 v[86:87], v[78:79], off offset:2048
	v_add_u32_e32 v78, 0x200, v73
	v_ashrrev_i32_e32 v80, 6, v78
	v_mad_u64_u32 v[78:79], s[18:19], v80, s33, v[0:1]
	v_add_u32_e32 v79, s0, v80
	v_mad_i64_i32 v[86:87], s[18:19], v79, s96, v[66:67]
	global_load_dwordx2 v[88:89], v[86:87], off offset:1024
	ds_read_b128 v[78:81], v78
	s_waitcnt vmcnt(0)
	v_lshlrev_b32_e32 v92, 16, v88
	v_and_b32_e32 v88, 0xffff0000, v88
	v_mul_f32_e32 v90, 0xbfb8aa3b, v92
	v_mul_f32_e32 v91, 0xbfb8aa3b, v88
	v_exp_f32_e32 v90, v90
	v_exp_f32_e32 v91, v91
	s_nop 0
	v_pk_add_f32 v[90:91], v[90:91], 1.0 op_sel_hi:[1,0]
	s_nop 0
	v_rcp_f32_e32 v94, v91
	s_nop 0
	v_mul_f32_e32 v91, v88, v94
	v_rcp_f32_e32 v93, v90
	s_nop 0
	v_mul_f32_e32 v90, v92, v93
	s_waitcnt lgkmcnt(0)
	v_pk_mul_f32 v[78:79], v[78:79], v[90:91]
	v_lshlrev_b32_e32 v90, 16, v89
	v_and_b32_e32 v91, 0xffff0000, v89
	v_mul_f32_e32 v88, 0xbfb8aa3b, v90
	v_mul_f32_e32 v89, 0xbfb8aa3b, v91
	v_exp_f32_e32 v88, v88
	v_exp_f32_e32 v89, v89
	v_cvt_pk_bf16_f32 v78, v78, v79
	v_pk_add_f32 v[88:89], v[88:89], 1.0 op_sel_hi:[1,0]
	s_nop 0
	v_rcp_f32_e32 v93, v89
	s_nop 0
	v_mul_f32_e32 v89, v91, v93
	v_rcp_f32_e32 v92, v88
	s_nop 0
	v_mul_f32_e32 v88, v90, v92
	v_pk_mul_f32 v[80:81], v[80:81], v[88:89]
	s_nop 0
	v_cvt_pk_bf16_f32 v79, v80, v81
	global_store_dwordx2 v[86:87], v[78:79], off offset:2048
	v_add_u32_e32 v78, 0x400, v73
	v_ashrrev_i32_e32 v80, 6, v78
	v_mad_u64_u32 v[78:79], s[18:19], v80, s33, v[0:1]
	v_add_u32_e32 v79, s0, v80
	v_mad_i64_i32 v[86:87], s[18:19], v79, s96, v[66:67]
	global_load_dwordx2 v[88:89], v[86:87], off offset:1024
	ds_read_b128 v[78:81], v78
	v_add_u32_e32 v73, 0x600, v73
	v_ashrrev_i32_e32 v73, 6, v73
	s_waitcnt vmcnt(0)
	v_lshlrev_b32_e32 v92, 16, v88
	v_and_b32_e32 v88, 0xffff0000, v88
	v_mul_f32_e32 v90, 0xbfb8aa3b, v92
	v_mul_f32_e32 v91, 0xbfb8aa3b, v88
	v_exp_f32_e32 v90, v90
	v_exp_f32_e32 v91, v91
	s_nop 0
	v_pk_add_f32 v[90:91], v[90:91], 1.0 op_sel_hi:[1,0]
	s_nop 0
	v_rcp_f32_e32 v94, v91
	s_nop 0
	v_mul_f32_e32 v91, v88, v94
	v_rcp_f32_e32 v93, v90
	s_nop 0
	v_mul_f32_e32 v90, v92, v93
	s_waitcnt lgkmcnt(0)
	v_pk_mul_f32 v[78:79], v[78:79], v[90:91]
	v_lshlrev_b32_e32 v90, 16, v89
	v_and_b32_e32 v91, 0xffff0000, v89
	v_mul_f32_e32 v88, 0xbfb8aa3b, v90
	v_mul_f32_e32 v89, 0xbfb8aa3b, v91
	v_exp_f32_e32 v88, v88
	v_exp_f32_e32 v89, v89
	v_cvt_pk_bf16_f32 v78, v78, v79
	v_pk_add_f32 v[88:89], v[88:89], 1.0 op_sel_hi:[1,0]
	s_nop 0
	v_rcp_f32_e32 v93, v89
	s_nop 0
	v_mul_f32_e32 v89, v91, v93
	v_rcp_f32_e32 v92, v88
	s_nop 0
	v_mul_f32_e32 v88, v90, v92
	v_pk_mul_f32 v[80:81], v[80:81], v[88:89]
	s_nop 0
	v_cvt_pk_bf16_f32 v79, v80, v81
	global_store_dwordx2 v[86:87], v[78:79], off offset:2048
	v_mad_u64_u32 v[78:79], s[18:19], v73, s33, v[0:1]
	v_add_u32_e32 v73, s0, v73
	v_mad_i64_i32 v[86:87], s[18:19], v73, s96, v[66:67]
	global_load_dwordx2 v[88:89], v[86:87], off offset:1024
	ds_read_b128 v[78:81], v78
	s_waitcnt vmcnt(0)
	v_lshlrev_b32_e32 v73, 16, v88
	v_and_b32_e32 v88, 0xffff0000, v88
	v_mul_f32_e32 v90, 0xbfb8aa3b, v73
	v_mul_f32_e32 v91, 0xbfb8aa3b, v88
	v_exp_f32_e32 v90, v90
	v_exp_f32_e32 v91, v91
	s_nop 0
	v_pk_add_f32 v[90:91], v[90:91], 1.0 op_sel_hi:[1,0]
	s_nop 0
	v_rcp_f32_e32 v93, v91
	s_nop 0
	v_mul_f32_e32 v91, v88, v93
	v_rcp_f32_e32 v92, v90
	s_nop 0
	v_mul_f32_e32 v90, v73, v92
	s_waitcnt lgkmcnt(0)
	v_pk_mul_f32 v[78:79], v[78:79], v[90:91]
	v_lshlrev_b32_e32 v73, 16, v89
	v_and_b32_e32 v90, 0xffff0000, v89
	v_mul_f32_e32 v88, 0xbfb8aa3b, v73
	v_mul_f32_e32 v89, 0xbfb8aa3b, v90
	v_exp_f32_e32 v88, v88
	v_exp_f32_e32 v89, v89
	v_cvt_pk_bf16_f32 v78, v78, v79
	v_pk_add_f32 v[88:89], v[88:89], 1.0 op_sel_hi:[1,0]
	s_nop 0
	v_rcp_f32_e32 v92, v89
	s_nop 0
	v_mul_f32_e32 v89, v90, v92
	v_rcp_f32_e32 v91, v88
	s_nop 0
	v_mul_f32_e32 v88, v73, v91
	v_pk_mul_f32 v[80:81], v[80:81], v[88:89]
	s_nop 0
	v_cvt_pk_bf16_f32 v79, v80, v81
	global_store_dwordx2 v[86:87], v[78:79], off offset:2048
	s_cbranch_scc0 .LBB0_209
	s_addk_i32 s0, 0x80
	s_mov_b32 s17, 0
	s_barrier
	ds_write2_b32 v131, v2, v18 offset1:16
	ds_write2_b32 v114, v3, v19 offset0:4 offset1:20
	ds_write2_b32 v115, v4, v20 offset0:8 offset1:24
	ds_write2_b32 v116, v5, v21 offset0:12 offset1:28
	ds_write2_b32 v117, v6, v22 offset0:64 offset1:80
	ds_write2_b32 v82, v7, v23 offset0:68 offset1:84
	ds_write2_b32 v83, v8, v24 offset0:72 offset1:88
	ds_write2_b32 v84, v9, v25 offset0:76 offset1:92
	ds_write2_b32 v85, v10, v26 offset0:128 offset1:144
	ds_write2_b32 v74, v11, v27 offset0:132 offset1:148
	ds_write2_b32 v75, v12, v28 offset0:136 offset1:152
	ds_write2_b32 v76, v13, v29 offset0:140 offset1:156
	ds_write2_b32 v77, v14, v30 offset0:192 offset1:208
	ds_write2_b32 v70, v15, v31 offset0:196 offset1:212
	ds_write2_b32 v71, v16, v32 offset0:200 offset1:216
	ds_write2_b32 v68, v17, v33 offset0:204 offset1:220
	ds_write2_b32 v131, v34, v50 offset0:128 offset1:144
	ds_write2_b32 v114, v35, v51 offset0:132 offset1:148
	ds_write2_b32 v115, v36, v52 offset0:136 offset1:152
	ds_write2_b32 v116, v37, v53 offset0:140 offset1:156
	ds_write2_b32 v117, v38, v54 offset0:192 offset1:208
	ds_write2_b32 v82, v39, v55 offset0:196 offset1:212
	ds_write2_b32 v83, v40, v56 offset0:200 offset1:216
	ds_write2_b32 v84, v41, v57 offset0:204 offset1:220
	ds_write2_b32 v74, v42, v58 offset1:16
	ds_write2_b32 v75, v43, v59 offset0:4 offset1:20
	ds_write2_b32 v76, v44, v60 offset0:8 offset1:24
	ds_write2_b32 v69, v45, v61 offset0:12 offset1:28
	ds_write2_b32 v70, v46, v62 offset0:64 offset1:80
	ds_write2_b32 v71, v47, v63 offset0:68 offset1:84
	ds_write2_b32 v68, v48, v64 offset0:72 offset1:88
	ds_write2_b32 v72, v49, v65 offset0:76 offset1:92
	s_waitcnt lgkmcnt(0)
	s_barrier
.LBB0_211:
	v_add_u32_e32 v12, s17, v130
	v_ashrrev_i32_e32 v4, 6, v12
	v_mad_u64_u32 v[2:3], s[18:19], v4, s33, v[0:1]
	v_add_u32_e32 v3, s0, v4
	v_mad_i64_i32 v[6:7], s[18:19], v3, s96, v[66:67]
	global_load_dwordx2 v[8:9], v[6:7], off offset:1024
	ds_read_b128 v[2:5], v2
	s_addk_i32 s17, 0x800
	s_cmpk_lg_i32 s17, 0x2000
	s_waitcnt vmcnt(0)
	v_lshlrev_b32_e32 v13, 16, v8
	v_and_b32_e32 v8, 0xffff0000, v8
	v_mul_f32_e32 v10, 0xbfb8aa3b, v13
	v_mul_f32_e32 v11, 0xbfb8aa3b, v8
	v_exp_f32_e32 v10, v10
	v_exp_f32_e32 v11, v11
	s_nop 0
	v_pk_add_f32 v[10:11], v[10:11], 1.0 op_sel_hi:[1,0]
	s_nop 0
	v_rcp_f32_e32 v15, v11
	s_nop 0
	v_mul_f32_e32 v11, v8, v15
	v_rcp_f32_e32 v14, v10
	s_nop 0
	v_mul_f32_e32 v10, v13, v14
	s_waitcnt lgkmcnt(0)
	v_pk_mul_f32 v[2:3], v[2:3], v[10:11]
	v_lshlrev_b32_e32 v10, 16, v9
	v_and_b32_e32 v11, 0xffff0000, v9
	v_mul_f32_e32 v8, 0xbfb8aa3b, v10
	v_mul_f32_e32 v9, 0xbfb8aa3b, v11
	v_exp_f32_e32 v8, v8
	v_exp_f32_e32 v9, v9
	v_cvt_pk_bf16_f32 v2, v2, v3
	v_pk_add_f32 v[8:9], v[8:9], 1.0 op_sel_hi:[1,0]
	s_nop 0
	v_rcp_f32_e32 v14, v9
	s_nop 0
	v_mul_f32_e32 v9, v11, v14
	v_rcp_f32_e32 v13, v8
	s_nop 0
	v_mul_f32_e32 v8, v10, v13
	v_pk_mul_f32 v[4:5], v[4:5], v[8:9]
	s_nop 0
	v_cvt_pk_bf16_f32 v3, v4, v5
	global_store_dwordx2 v[6:7], v[2:3], off offset:2048
	v_add_u32_e32 v2, 0x200, v12
	v_ashrrev_i32_e32 v4, 6, v2
	v_mad_u64_u32 v[2:3], s[18:19], v4, s33, v[0:1]
	v_add_u32_e32 v3, s0, v4
	v_mad_i64_i32 v[6:7], s[18:19], v3, s96, v[66:67]
	global_load_dwordx2 v[8:9], v[6:7], off offset:1024
	ds_read_b128 v[2:5], v2
	s_waitcnt vmcnt(0)
	v_lshlrev_b32_e32 v13, 16, v8
	v_and_b32_e32 v8, 0xffff0000, v8
	v_mul_f32_e32 v10, 0xbfb8aa3b, v13
	v_mul_f32_e32 v11, 0xbfb8aa3b, v8
	v_exp_f32_e32 v10, v10
	v_exp_f32_e32 v11, v11
	s_nop 0
	v_pk_add_f32 v[10:11], v[10:11], 1.0 op_sel_hi:[1,0]
	s_nop 0
	v_rcp_f32_e32 v15, v11
	s_nop 0
	v_mul_f32_e32 v11, v8, v15
	v_rcp_f32_e32 v14, v10
	s_nop 0
	v_mul_f32_e32 v10, v13, v14
	s_waitcnt lgkmcnt(0)
	v_pk_mul_f32 v[2:3], v[2:3], v[10:11]
	v_lshlrev_b32_e32 v10, 16, v9
	v_and_b32_e32 v11, 0xffff0000, v9
	v_mul_f32_e32 v8, 0xbfb8aa3b, v10
	v_mul_f32_e32 v9, 0xbfb8aa3b, v11
	v_exp_f32_e32 v8, v8
	v_exp_f32_e32 v9, v9
	v_cvt_pk_bf16_f32 v2, v2, v3
	v_pk_add_f32 v[8:9], v[8:9], 1.0 op_sel_hi:[1,0]
	s_nop 0
	v_rcp_f32_e32 v14, v9
	s_nop 0
	v_mul_f32_e32 v9, v11, v14
	v_rcp_f32_e32 v13, v8
	s_nop 0
	v_mul_f32_e32 v8, v10, v13
	v_pk_mul_f32 v[4:5], v[4:5], v[8:9]
	s_nop 0
	v_cvt_pk_bf16_f32 v3, v4, v5
	global_store_dwordx2 v[6:7], v[2:3], off offset:2048
	v_add_u32_e32 v2, 0x400, v12
	v_ashrrev_i32_e32 v4, 6, v2
	v_mad_u64_u32 v[2:3], s[18:19], v4, s33, v[0:1]
	v_add_u32_e32 v3, s0, v4
	v_mad_i64_i32 v[6:7], s[18:19], v3, s96, v[66:67]
	global_load_dwordx2 v[8:9], v[6:7], off offset:1024
	ds_read_b128 v[2:5], v2
	s_waitcnt vmcnt(0)
	v_lshlrev_b32_e32 v13, 16, v8
	v_and_b32_e32 v8, 0xffff0000, v8
	v_mul_f32_e32 v10, 0xbfb8aa3b, v13
	v_mul_f32_e32 v11, 0xbfb8aa3b, v8
	v_exp_f32_e32 v10, v10
	v_exp_f32_e32 v11, v11
	s_nop 0
	v_pk_add_f32 v[10:11], v[10:11], 1.0 op_sel_hi:[1,0]
	s_nop 0
	v_rcp_f32_e32 v15, v11
	s_nop 0
	v_mul_f32_e32 v11, v8, v15
	v_rcp_f32_e32 v14, v10
	s_nop 0
	v_mul_f32_e32 v10, v13, v14
	s_waitcnt lgkmcnt(0)
	v_pk_mul_f32 v[2:3], v[2:3], v[10:11]
	v_lshlrev_b32_e32 v10, 16, v9
	v_and_b32_e32 v11, 0xffff0000, v9
	v_mul_f32_e32 v8, 0xbfb8aa3b, v10
	v_mul_f32_e32 v9, 0xbfb8aa3b, v11
	v_exp_f32_e32 v8, v8
	v_exp_f32_e32 v9, v9
	v_cvt_pk_bf16_f32 v2, v2, v3
	v_pk_add_f32 v[8:9], v[8:9], 1.0 op_sel_hi:[1,0]
	s_nop 0
	v_rcp_f32_e32 v14, v9
	s_nop 0
	v_mul_f32_e32 v9, v11, v14
	v_rcp_f32_e32 v13, v8
	s_nop 0
	v_mul_f32_e32 v8, v10, v13
	v_pk_mul_f32 v[4:5], v[4:5], v[8:9]
	s_nop 0
	v_cvt_pk_bf16_f32 v3, v4, v5
	global_store_dwordx2 v[6:7], v[2:3], off offset:2048
	v_add_u32_e32 v2, 0x600, v12
	v_ashrrev_i32_e32 v4, 6, v2
	v_mad_u64_u32 v[2:3], s[18:19], v4, s33, v[0:1]
	v_add_u32_e32 v3, s0, v4
	v_mad_i64_i32 v[6:7], s[18:19], v3, s96, v[66:67]
	global_load_dwordx2 v[8:9], v[6:7], off offset:1024
	ds_read_b128 v[2:5], v2
	s_waitcnt vmcnt(0)
	v_lshlrev_b32_e32 v12, 16, v8
	v_and_b32_e32 v8, 0xffff0000, v8
	v_mul_f32_e32 v10, 0xbfb8aa3b, v12
	v_mul_f32_e32 v11, 0xbfb8aa3b, v8
	v_exp_f32_e32 v10, v10
	v_exp_f32_e32 v11, v11
	s_nop 0
	v_pk_add_f32 v[10:11], v[10:11], 1.0 op_sel_hi:[1,0]
	s_nop 0
	v_rcp_f32_e32 v14, v11
	s_nop 0
	v_mul_f32_e32 v11, v8, v14
	v_rcp_f32_e32 v13, v10
	s_nop 0
	v_mul_f32_e32 v10, v12, v13
	s_waitcnt lgkmcnt(0)
	v_pk_mul_f32 v[2:3], v[2:3], v[10:11]
	v_lshlrev_b32_e32 v10, 16, v9
	v_and_b32_e32 v11, 0xffff0000, v9
	v_mul_f32_e32 v8, 0xbfb8aa3b, v10
	v_mul_f32_e32 v9, 0xbfb8aa3b, v11
	v_exp_f32_e32 v8, v8
	v_exp_f32_e32 v9, v9
	v_cvt_pk_bf16_f32 v2, v2, v3
	v_pk_add_f32 v[8:9], v[8:9], 1.0 op_sel_hi:[1,0]
	s_nop 0
	v_rcp_f32_e32 v13, v9
	s_nop 0
	v_mul_f32_e32 v9, v11, v13
	v_rcp_f32_e32 v12, v8
	s_nop 0
	v_mul_f32_e32 v8, v10, v12
	v_pk_mul_f32 v[4:5], v[4:5], v[8:9]
	s_nop 0
	v_cvt_pk_bf16_f32 v3, v4, v5
	global_store_dwordx2 v[6:7], v[2:3], off offset:2048
	s_cbranch_scc1 .LBB0_211
	s_barrier
	s_branch .LBB0_173

.LBB0_355:
	s_or_b64 exec, exec, s[10:11]
	s_and_saveexec_b64 s[4:5], s[40:41]
	s_cbranch_execz .LBB0_216
	v_and_b32_e32 v2, 64, v210
	v_xor_b32_e32 v0, 32, v210
	v_add_u32_e32 v2, 64, v2
	v_cmp_lt_i32_e32 vcc, v0, v2
	s_nop 1
	v_cndmask_b32_e32 v0, v210, v0, vcc
	v_lshlrev_b32_e32 v86, 2, v0
	ds_bpermute_b32 v0, v86, v188
	s_waitcnt lgkmcnt(0)
	v_add_f32_e32 v0, v188, v0
	v_rcp_f32_e32 v0, v0
	s_nop 0
	ds_bpermute_b32 v2, v86, v181
	s_waitcnt lgkmcnt(0)
	v_add_f32_e32 v2, v181, v2
	v_rcp_f32_e32 v4, v2
	s_nop 0
	v_mul_f32_e32 v2, v140, v4
	v_pk_mul_f32 v[4:5], v[64:65], v[2:3] op_sel_hi:[1,0]
	v_pk_mul_f32 v[8:9], v[44:45], v[2:3] op_sel_hi:[1,0]
	v_pk_fma_f32 v[82:83], v[48:49], v[0:1], v[4:5] op_sel_hi:[1,0,1] neg_lo:[0,0,1] neg_hi:[0,0,1]
	v_pk_mul_f32 v[4:5], v[66:67], v[2:3] op_sel_hi:[1,0]
	v_pk_mul_f32 v[6:7], v[82:83], v[82:83]
	v_pk_fma_f32 v[80:81], v[50:51], v[0:1], v[4:5] op_sel_hi:[1,0,1] neg_lo:[0,0,1] neg_hi:[0,0,1]
	v_pk_mul_f32 v[4:5], v[68:69], v[2:3] op_sel_hi:[1,0]
	v_pk_mul_f32 v[84:85], v[80:81], v[80:81]
	v_pk_fma_f32 v[66:67], v[52:53], v[0:1], v[4:5] op_sel_hi:[1,0,1] neg_lo:[0,0,1] neg_hi:[0,0,1]
	v_pk_mul_f32 v[4:5], v[70:71], v[2:3] op_sel_hi:[1,0]
	v_pk_fma_f32 v[10:11], v[28:29], v[0:1], v[8:9] op_sel_hi:[1,0,1] neg_lo:[0,0,1] neg_hi:[0,0,1]
	v_pk_fma_f32 v[64:65], v[54:55], v[0:1], v[4:5] op_sel_hi:[1,0,1] neg_lo:[0,0,1] neg_hi:[0,0,1]
	v_pk_mul_f32 v[4:5], v[72:73], v[2:3] op_sel_hi:[1,0]
	v_pk_mul_f32 v[68:69], v[66:67], v[66:67]
	v_pk_fma_f32 v[54:55], v[56:57], v[0:1], v[4:5] op_sel_hi:[1,0,1] neg_lo:[0,0,1] neg_hi:[0,0,1]
	v_pk_mul_f32 v[4:5], v[74:75], v[2:3] op_sel_hi:[1,0]
	v_pk_mul_f32 v[70:71], v[64:65], v[64:65]
	v_pk_fma_f32 v[52:53], v[58:59], v[0:1], v[4:5] op_sel_hi:[1,0,1] neg_lo:[0,0,1] neg_hi:[0,0,1]
	v_pk_mul_f32 v[4:5], v[76:77], v[2:3] op_sel_hi:[1,0]
	v_pk_mul_f32 v[56:57], v[54:55], v[54:55]
	v_pk_fma_f32 v[50:51], v[60:61], v[0:1], v[4:5] op_sel_hi:[1,0,1] neg_lo:[0,0,1] neg_hi:[0,0,1]
	v_pk_mul_f32 v[4:5], v[78:79], v[2:3] op_sel_hi:[1,0]
	v_pk_mul_f32 v[58:59], v[52:53], v[52:53]
	v_pk_fma_f32 v[48:49], v[62:63], v[0:1], v[4:5] op_sel_hi:[1,0,1] neg_lo:[0,0,1] neg_hi:[0,0,1]
	v_pk_mul_f32 v[4:5], v[32:33], v[2:3] op_sel_hi:[1,0]
	v_pk_mul_f32 v[60:61], v[50:51], v[50:51]
	v_pk_fma_f32 v[32:33], v[16:17], v[0:1], v[4:5] op_sel_hi:[1,0,1] neg_lo:[0,0,1] neg_hi:[0,0,1]
	v_pk_mul_f32 v[4:5], v[34:35], v[2:3] op_sel_hi:[1,0]
	v_pk_mul_f32 v[62:63], v[48:49], v[48:49]
	v_pk_fma_f32 v[18:19], v[18:19], v[0:1], v[4:5] op_sel_hi:[1,0,1] neg_lo:[0,0,1] neg_hi:[0,0,1]
	v_pk_mul_f32 v[4:5], v[36:37], v[2:3] op_sel_hi:[1,0]
	v_pk_mul_f32 v[72:73], v[32:33], v[32:33]
	v_pk_fma_f32 v[16:17], v[20:21], v[0:1], v[4:5] op_sel_hi:[1,0,1] neg_lo:[0,0,1] neg_hi:[0,0,1]
	v_pk_mul_f32 v[4:5], v[38:39], v[2:3] op_sel_hi:[1,0]
	v_pk_mul_f32 v[34:35], v[18:19], v[18:19]
	v_pk_fma_f32 v[14:15], v[22:23], v[0:1], v[4:5] op_sel_hi:[1,0,1] neg_lo:[0,0,1] neg_hi:[0,0,1]
	v_pk_mul_f32 v[4:5], v[40:41], v[2:3] op_sel_hi:[1,0]
	v_pk_mul_f32 v[20:21], v[16:17], v[16:17]
	v_pk_fma_f32 v[12:13], v[24:25], v[0:1], v[4:5] op_sel_hi:[1,0,1] neg_lo:[0,0,1] neg_hi:[0,0,1]
	v_pk_mul_f32 v[4:5], v[42:43], v[2:3] op_sel_hi:[1,0]
	v_pk_mul_f32 v[2:3], v[46:47], v[2:3] op_sel_hi:[1,0]
	v_pk_fma_f32 v[4:5], v[26:27], v[0:1], v[4:5] op_sel_hi:[1,0,1] neg_lo:[0,0,1] neg_hi:[0,0,1]
	v_pk_fma_f32 v[8:9], v[30:31], v[0:1], v[2:3] op_sel_hi:[1,0,1] neg_lo:[0,0,1] neg_hi:[0,0,1]
	v_add_f32_e32 v0, v6, v7
	v_add_f32_e32 v0, v84, v0
	v_add_f32_e32 v0, v85, v0
	v_add_f32_e32 v0, v68, v0
	v_add_f32_e32 v0, v69, v0
	v_add_f32_e32 v0, v70, v0
	v_add_f32_e32 v0, v71, v0
	v_add_f32_e32 v0, v56, v0
	v_add_f32_e32 v0, v57, v0
	v_add_f32_e32 v0, v58, v0
	v_add_f32_e32 v0, v59, v0
	v_add_f32_e32 v0, v60, v0
	v_add_f32_e32 v0, v61, v0
	v_add_f32_e32 v0, v62, v0
	v_add_f32_e32 v0, v63, v0
	v_add_f32_e32 v0, v72, v0
	v_add_f32_e32 v0, v73, v0
	v_add_f32_e32 v0, v34, v0
	v_add_f32_e32 v0, v35, v0
	v_add_f32_e32 v0, v20, v0
	v_pk_mul_f32 v[22:23], v[14:15], v[14:15]
	v_add_f32_e32 v0, v21, v0
	v_add_f32_e32 v0, v22, v0
	v_pk_mul_f32 v[24:25], v[12:13], v[12:13]
	v_add_f32_e32 v0, v23, v0
	v_add_f32_e32 v0, v24, v0
	v_pk_mul_f32 v[26:27], v[4:5], v[4:5]
	v_add_f32_e32 v0, v25, v0
	v_add_f32_e32 v0, v26, v0
	v_pk_mul_f32 v[28:29], v[10:11], v[10:11]
	v_add_f32_e32 v0, v27, v0
	v_add_f32_e32 v0, v28, v0
	v_pk_mul_f32 v[2:3], v[8:9], v[8:9]
	v_add_f32_e32 v0, v29, v0
	v_add_f32_e32 v0, v2, v0
	v_add_f32_e32 v20, v3, v0
	ds_bpermute_b32 v21, v86, v20
	s_and_b64 exec, exec, s[6:7]
	s_cbranch_execz .LBB0_216
	v_mov_b32_e32 v143, v1
	v_lshl_add_u64 v[2:3], v[144:145], 0, v[142:143]
	s_mov_b64 s[6:7], 0x1400
	v_lshl_add_u64 v[6:7], v[2:3], 0, s[6:7]
	s_mov_b64 s[6:7], 0x1000
	v_lshl_add_u64 v[2:3], v[2:3], 0, s[6:7]
	v_mad_i64_i32 v[6:7], s[6:7], v149, s96, v[6:7]
	v_mad_i64_i32 v[24:25], s[6:7], v149, s96, v[2:3]
	v_lshlrev_b32_e32 v0, 1, v147
	v_lshl_add_u64 v[2:3], v[6:7], 0, v[0:1]
	v_lshl_add_u64 v[6:7], v[24:25], 0, v[0:1]
	s_waitcnt lgkmcnt(0)
	v_add_f32_e32 v0, v20, v21
	v_fmamk_f32 v0, v0, 0x3c800000, v170
	s_mov_b32 s0, 0x800000
	v_cmp_gt_f32_e32 vcc, s0, v0
	v_mul_f32_e32 v20, 0x4b800000, v0
	v_readlane_b32 s10, v254, 22
	v_cndmask_b32_e32 v0, v0, v20, vcc
	v_rsq_f32_e32 v0, v0
	v_lshlrev_b32_e32 v22, 2, v147
	v_readlane_b32 s11, v254, 23
	v_sub_f32_e32 v23, 1.0, v141
	v_mul_f32_e32 v20, 0x45800000, v0
	v_cndmask_b32_e32 v0, v0, v20, vcc
	global_load_dwordx2 v[20:21], v[2:3], off
	v_mul_f32_e32 v0, v23, v0
	global_load_dwordx4 v[24:27], v22, s[10:11]
	v_pk_mul_f32 v[30:31], v[82:83], v[0:1] op_sel_hi:[1,0]
	v_pk_mul_f32 v[18:19], v[18:19], v[0:1] op_sel_hi:[1,0]
	v_pk_mul_f32 v[16:17], v[16:17], v[0:1] op_sel_hi:[1,0]
	v_pk_mul_f32 v[14:15], v[14:15], v[0:1] op_sel_hi:[1,0]
	v_pk_mul_f32 v[12:13], v[12:13], v[0:1] op_sel_hi:[1,0]
	v_pk_mul_f32 v[4:5], v[4:5], v[0:1] op_sel_hi:[1,0]
	v_pk_mul_f32 v[10:11], v[10:11], v[0:1] op_sel_hi:[1,0]
	v_pk_mul_f32 v[8:9], v[8:9], v[0:1] op_sel_hi:[1,0]
	s_waitcnt vmcnt(1)
	v_lshlrev_b32_e32 v23, 16, v20
	v_and_b32_e32 v20, 0xffff0000, v20
	v_mul_f32_e32 v28, 0xbfb8aa3b, v23
	v_mul_f32_e32 v29, 0xbfb8aa3b, v20
	v_exp_f32_e32 v28, v28
	v_exp_f32_e32 v29, v29
	s_waitcnt vmcnt(0)
	v_pk_mul_f32 v[24:25], v[30:31], v[24:25]
	v_pk_add_f32 v[28:29], v[28:29], 1.0 op_sel_hi:[1,0]
	s_nop 0
	v_rcp_f32_e32 v31, v29
	s_nop 0
	v_mul_f32_e32 v29, v20, v31
	v_rcp_f32_e32 v30, v28
	s_nop 0
	v_mul_f32_e32 v28, v23, v30
	v_lshlrev_b32_e32 v23, 16, v21
	v_and_b32_e32 v30, 0xffff0000, v21
	v_mul_f32_e32 v20, 0xbfb8aa3b, v23
	v_mul_f32_e32 v21, 0xbfb8aa3b, v30
	v_exp_f32_e32 v20, v20
	v_exp_f32_e32 v21, v21
	v_pk_mul_f32 v[24:25], v[24:25], v[28:29]
	v_pk_mul_f32 v[28:29], v[80:81], v[0:1] op_sel_hi:[1,0]
	v_cvt_pk_bf16_f32 v24, v24, v25
	v_pk_add_f32 v[20:21], v[20:21], 1.0 op_sel_hi:[1,0]
	v_pk_mul_f32 v[26:27], v[28:29], v[26:27]
	v_rcp_f32_e32 v29, v21
	s_nop 0
	v_mul_f32_e32 v21, v30, v29
	v_rcp_f32_e32 v29, v20
	s_nop 0
	v_mul_f32_e32 v20, v23, v29
	v_pk_mul_f32 v[20:21], v[26:27], v[20:21]
	v_pk_mul_f32 v[30:31], v[66:67], v[0:1] op_sel_hi:[1,0]
	v_cvt_pk_bf16_f32 v25, v20, v21
	global_load_dwordx2 v[20:21], v[2:3], off offset:16
	s_waitcnt vmcnt(0)
	v_lshlrev_b32_e32 v23, 16, v20
	global_store_dwordx2 v[6:7], v[24:25], off
	global_load_dwordx4 v[24:27], v22, s[10:11] offset:32
	v_and_b32_e32 v20, 0xffff0000, v20
	v_mul_f32_e32 v28, 0xbfb8aa3b, v23
	v_mul_f32_e32 v29, 0xbfb8aa3b, v20
	v_exp_f32_e32 v28, v28
	v_exp_f32_e32 v29, v29
	s_waitcnt vmcnt(0)
	v_pk_mul_f32 v[24:25], v[30:31], v[24:25]
	v_pk_add_f32 v[28:29], v[28:29], 1.0 op_sel_hi:[1,0]
	s_nop 0
	v_rcp_f32_e32 v31, v29
	s_nop 0
	v_mul_f32_e32 v29, v20, v31
	v_rcp_f32_e32 v30, v28
	s_nop 0
	v_mul_f32_e32 v28, v23, v30
	v_lshlrev_b32_e32 v23, 16, v21
	v_and_b32_e32 v30, 0xffff0000, v21
	v_mul_f32_e32 v20, 0xbfb8aa3b, v23
	v_mul_f32_e32 v21, 0xbfb8aa3b, v30
	v_exp_f32_e32 v20, v20
	v_exp_f32_e32 v21, v21
	v_pk_mul_f32 v[24:25], v[24:25], v[28:29]
	v_pk_mul_f32 v[28:29], v[64:65], v[0:1] op_sel_hi:[1,0]
	v_cvt_pk_bf16_f32 v24, v24, v25
	v_pk_add_f32 v[20:21], v[20:21], 1.0 op_sel_hi:[1,0]
	v_pk_mul_f32 v[26:27], v[28:29], v[26:27]
	v_rcp_f32_e32 v29, v21
	s_nop 0
	v_mul_f32_e32 v21, v30, v29
	v_rcp_f32_e32 v29, v20
	s_nop 0
	v_mul_f32_e32 v20, v23, v29
	v_pk_mul_f32 v[20:21], v[26:27], v[20:21]
	v_pk_mul_f32 v[30:31], v[54:55], v[0:1] op_sel_hi:[1,0]
	v_cvt_pk_bf16_f32 v25, v20, v21
	global_load_dwordx2 v[20:21], v[2:3], off offset:32
	s_waitcnt vmcnt(0)
	v_lshlrev_b32_e32 v23, 16, v20
	global_store_dwordx2 v[6:7], v[24:25], off offset:16
	global_load_dwordx4 v[24:27], v22, s[10:11] offset:64
	v_and_b32_e32 v20, 0xffff0000, v20
	v_mul_f32_e32 v28, 0xbfb8aa3b, v23
	v_mul_f32_e32 v29, 0xbfb8aa3b, v20
	v_exp_f32_e32 v28, v28
	v_exp_f32_e32 v29, v29
	s_waitcnt vmcnt(0)
	v_pk_mul_f32 v[24:25], v[30:31], v[24:25]
	v_pk_add_f32 v[28:29], v[28:29], 1.0 op_sel_hi:[1,0]
	s_nop 0
	v_rcp_f32_e32 v31, v29
	s_nop 0
	v_mul_f32_e32 v29, v20, v31
	v_rcp_f32_e32 v30, v28
	s_nop 0
	v_mul_f32_e32 v28, v23, v30
	v_lshlrev_b32_e32 v23, 16, v21
	v_and_b32_e32 v30, 0xffff0000, v21
	v_mul_f32_e32 v20, 0xbfb8aa3b, v23
	v_mul_f32_e32 v21, 0xbfb8aa3b, v30
	v_exp_f32_e32 v20, v20
	v_exp_f32_e32 v21, v21
	v_pk_mul_f32 v[24:25], v[24:25], v[28:29]
	v_pk_mul_f32 v[28:29], v[52:53], v[0:1] op_sel_hi:[1,0]
	v_cvt_pk_bf16_f32 v24, v24, v25
	v_pk_add_f32 v[20:21], v[20:21], 1.0 op_sel_hi:[1,0]
	v_pk_mul_f32 v[26:27], v[28:29], v[26:27]
	v_rcp_f32_e32 v29, v21
	s_nop 0
	v_mul_f32_e32 v21, v30, v29
	v_rcp_f32_e32 v29, v20
	s_nop 0
	v_mul_f32_e32 v20, v23, v29
	v_pk_mul_f32 v[20:21], v[26:27], v[20:21]
	v_pk_mul_f32 v[30:31], v[50:51], v[0:1] op_sel_hi:[1,0]
	v_cvt_pk_bf16_f32 v25, v20, v21
	global_load_dwordx2 v[20:21], v[2:3], off offset:48
	s_waitcnt vmcnt(0)
	v_lshlrev_b32_e32 v23, 16, v20
	global_store_dwordx2 v[6:7], v[24:25], off offset:32
	global_load_dwordx4 v[24:27], v22, s[10:11] offset:96
	v_and_b32_e32 v20, 0xffff0000, v20
	v_mul_f32_e32 v28, 0xbfb8aa3b, v23
	v_mul_f32_e32 v29, 0xbfb8aa3b, v20
	v_exp_f32_e32 v28, v28
	v_exp_f32_e32 v29, v29
	s_waitcnt vmcnt(0)
	v_pk_mul_f32 v[24:25], v[30:31], v[24:25]
	v_pk_add_f32 v[28:29], v[28:29], 1.0 op_sel_hi:[1,0]
	s_nop 0
	v_rcp_f32_e32 v31, v29
	s_nop 0
	v_mul_f32_e32 v29, v20, v31
	v_rcp_f32_e32 v30, v28
	s_nop 0
	v_mul_f32_e32 v28, v23, v30
	v_lshlrev_b32_e32 v23, 16, v21
	v_and_b32_e32 v30, 0xffff0000, v21
	v_mul_f32_e32 v20, 0xbfb8aa3b, v23
	v_mul_f32_e32 v21, 0xbfb8aa3b, v30
	v_exp_f32_e32 v20, v20
	v_exp_f32_e32 v21, v21
	v_pk_mul_f32 v[24:25], v[24:25], v[28:29]
	v_pk_mul_f32 v[28:29], v[48:49], v[0:1] op_sel_hi:[1,0]
	v_cvt_pk_bf16_f32 v24, v24, v25
	v_pk_add_f32 v[20:21], v[20:21], 1.0 op_sel_hi:[1,0]
	v_pk_mul_f32 v[26:27], v[28:29], v[26:27]
	v_rcp_f32_e32 v29, v21
	s_nop 0
	v_mul_f32_e32 v21, v30, v29
	v_rcp_f32_e32 v29, v20
	s_nop 0
	v_mul_f32_e32 v20, v23, v29
	v_pk_mul_f32 v[20:21], v[26:27], v[20:21]
	v_pk_mul_f32 v[30:31], v[32:33], v[0:1] op_sel_hi:[1,0]
	v_cvt_pk_bf16_f32 v25, v20, v21
	global_load_dwordx2 v[20:21], v[2:3], off offset:64
	s_waitcnt vmcnt(0)
	v_lshlrev_b32_e32 v23, 16, v20
	global_store_dwordx2 v[6:7], v[24:25], off offset:48
	global_load_dwordx4 v[24:27], v22, s[10:11] offset:128
	v_and_b32_e32 v20, 0xffff0000, v20
	v_mul_f32_e32 v28, 0xbfb8aa3b, v23
	v_mul_f32_e32 v29, 0xbfb8aa3b, v20
	v_exp_f32_e32 v28, v28
	v_exp_f32_e32 v29, v29
	s_waitcnt vmcnt(0)
	v_pk_mul_f32 v[24:25], v[30:31], v[24:25]
	v_pk_add_f32 v[28:29], v[28:29], 1.0 op_sel_hi:[1,0]
	v_pk_mul_f32 v[18:19], v[18:19], v[26:27]
	v_rcp_f32_e32 v31, v29
	s_nop 0
	v_mul_f32_e32 v29, v20, v31
	v_rcp_f32_e32 v30, v28
	s_nop 0
	v_mul_f32_e32 v28, v23, v30
	v_pk_mul_f32 v[24:25], v[24:25], v[28:29]
	v_lshlrev_b32_e32 v23, 16, v21
	v_and_b32_e32 v28, 0xffff0000, v21
	v_mul_f32_e32 v20, 0xbfb8aa3b, v23
	v_mul_f32_e32 v21, 0xbfb8aa3b, v28
	v_exp_f32_e32 v20, v20
	v_exp_f32_e32 v21, v21
	s_nop 0
	v_pk_add_f32 v[20:21], v[20:21], 1.0 op_sel_hi:[1,0]
	s_nop 0
	v_rcp_f32_e32 v27, v21
	s_nop 0
	v_mul_f32_e32 v21, v28, v27
	v_rcp_f32_e32 v27, v20
	s_nop 0
	v_mul_f32_e32 v20, v23, v27
	v_pk_mul_f32 v[18:19], v[18:19], v[20:21]
	v_cvt_pk_bf16_f32 v20, v24, v25
	v_cvt_pk_bf16_f32 v21, v18, v19
	global_load_dwordx2 v[24:25], v[2:3], off offset:80
	s_waitcnt vmcnt(0)
	v_lshlrev_b32_e32 v23, 16, v24
	global_store_dwordx2 v[6:7], v[20:21], off offset:64
	global_load_dwordx4 v[18:21], v22, s[10:11] offset:160
	v_and_b32_e32 v24, 0xffff0000, v24
	v_mul_f32_e32 v26, 0xbfb8aa3b, v23
	v_exp_f32_e32 v26, v26
	s_waitcnt vmcnt(0)
	v_pk_mul_f32 v[16:17], v[16:17], v[18:19]
	v_mul_f32_e32 v18, 0xbfb8aa3b, v24
	v_exp_f32_e32 v27, v18
	v_pk_mul_f32 v[14:15], v[14:15], v[20:21]
	v_pk_add_f32 v[18:19], v[26:27], 1.0 op_sel_hi:[1,0]
	s_nop 0
	v_rcp_f32_e32 v27, v19
	s_nop 0
	v_mul_f32_e32 v19, v24, v27
	v_rcp_f32_e32 v26, v18
	s_nop 0
	v_mul_f32_e32 v18, v23, v26
	v_lshlrev_b32_e32 v23, 16, v25
	v_and_b32_e32 v24, 0xffff0000, v25
	v_pk_mul_f32 v[16:17], v[16:17], v[18:19]
	v_mul_f32_e32 v18, 0xbfb8aa3b, v23
	v_mul_f32_e32 v19, 0xbfb8aa3b, v24
	v_exp_f32_e32 v18, v18
	v_exp_f32_e32 v19, v19
	v_cvt_pk_bf16_f32 v16, v16, v17
	v_pk_add_f32 v[18:19], v[18:19], 1.0 op_sel_hi:[1,0]
	s_nop 0
	v_rcp_f32_e32 v21, v19
	s_nop 0
	v_mul_f32_e32 v19, v24, v21
	v_rcp_f32_e32 v21, v18
	s_nop 0
	v_mul_f32_e32 v18, v23, v21
	v_pk_mul_f32 v[14:15], v[14:15], v[18:19]
	global_load_dwordx2 v[18:19], v[2:3], off offset:96
	v_cvt_pk_bf16_f32 v17, v14, v15
	global_store_dwordx2 v[6:7], v[16:17], off offset:80
	global_load_dwordx4 v[14:17], v22, s[10:11] offset:192
	s_waitcnt vmcnt(2)
	v_lshlrev_b32_e32 v23, 16, v18
	v_and_b32_e32 v18, 0xffff0000, v18
	v_mul_f32_e32 v20, 0xbfb8aa3b, v23
	s_waitcnt vmcnt(0)
	v_pk_mul_f32 v[12:13], v[12:13], v[14:15]
	v_mul_f32_e32 v14, 0xbfb8aa3b, v18
	v_exp_f32_e32 v20, v20
	v_exp_f32_e32 v21, v14
	v_pk_mul_f32 v[4:5], v[4:5], v[16:17]
	v_pk_add_f32 v[14:15], v[20:21], 1.0 op_sel_hi:[1,0]
	s_nop 0
	v_rcp_f32_e32 v21, v15
	s_nop 0
	v_mul_f32_e32 v15, v18, v21
	v_rcp_f32_e32 v20, v14
	s_nop 0
	v_mul_f32_e32 v14, v23, v20
	v_lshlrev_b32_e32 v18, 16, v19
	v_and_b32_e32 v19, 0xffff0000, v19
	v_pk_mul_f32 v[12:13], v[12:13], v[14:15]
	v_mul_f32_e32 v14, 0xbfb8aa3b, v18
	v_mul_f32_e32 v15, 0xbfb8aa3b, v19
	v_exp_f32_e32 v14, v14
	v_exp_f32_e32 v15, v15
	v_cvt_pk_bf16_f32 v12, v12, v13
	v_pk_add_f32 v[14:15], v[14:15], 1.0 op_sel_hi:[1,0]
	s_nop 0
	v_rcp_f32_e32 v17, v15
	s_nop 0
	v_mul_f32_e32 v15, v19, v17
	v_rcp_f32_e32 v17, v14
	s_nop 0
	v_mul_f32_e32 v14, v18, v17
	v_pk_mul_f32 v[4:5], v[4:5], v[14:15]
	s_nop 0
	v_cvt_pk_bf16_f32 v13, v4, v5
	global_store_dwordx2 v[6:7], v[12:13], off offset:96
	global_load_dwordx2 v[12:13], v[2:3], off offset:112
	s_waitcnt vmcnt(0)
	v_lshlrev_b32_e32 v14, 16, v12
	global_load_dwordx4 v[2:5], v22, s[10:11] offset:224
	v_and_b32_e32 v12, 0xffff0000, v12
	v_mul_f32_e32 v15, 0xbfb8aa3b, v14
	v_exp_f32_e32 v16, v15
	s_waitcnt vmcnt(0)
	v_pk_mul_f32 v[2:3], v[10:11], v[2:3]
	v_mul_f32_e32 v10, 0xbfb8aa3b, v12
	v_exp_f32_e32 v17, v10
	v_pk_mul_f32 v[4:5], v[8:9], v[4:5]
	v_pk_add_f32 v[10:11], v[16:17], 1.0 op_sel_hi:[1,0]
	s_nop 0
	v_rcp_f32_e32 v16, v11
	s_nop 0
	v_mul_f32_e32 v11, v12, v16
	v_rcp_f32_e32 v15, v10
	s_nop 0
	v_mul_f32_e32 v10, v14, v15
	v_lshlrev_b32_e32 v12, 16, v13
	v_and_b32_e32 v13, 0xffff0000, v13
	v_pk_mul_f32 v[2:3], v[2:3], v[10:11]
	v_mul_f32_e32 v10, 0xbfb8aa3b, v12
	v_mul_f32_e32 v0, 0xbfb8aa3b, v13
	v_exp_f32_e32 v10, v10
	v_exp_f32_e32 v11, v0
	v_cvt_pk_bf16_f32 v2, v2, v3
	v_pk_add_f32 v[8:9], v[10:11], 1.0 op_sel_hi:[1,0]
	s_nop 0
	v_rcp_f32_e32 v10, v9
	s_nop 0
	v_mul_f32_e32 v9, v13, v10
	v_rcp_f32_e32 v10, v8
	s_nop 0
	v_mul_f32_e32 v8, v12, v10
	v_pk_mul_f32 v[4:5], v[4:5], v[8:9]
	s_nop 0
	v_cvt_pk_bf16_f32 v3, v4, v5
	global_store_dwordx2 v[6:7], v[2:3], off offset:112
	s_branch .LBB0_216

.LBB0_511:
	s_and_b32 s46, s27, 0x70
	s_ashr_i32 s45, s26, 3
	s_bitset1_b32 s46, 14
	s_mov_b64 s[4:5], -1
	s_cmp_gt_i32 s45, 4
	v_or_b32_e32 v13, s46, v11
	v_lshlrev_b32_e32 v36, 1, v12
	s_cbranch_scc0 .LBB0_529
	s_add_i32 s0, s45, -5
	s_lshl_b32 s4, s46, 10
	s_add_u32 s4, s6, s4
	s_addc_u32 s5, s7, 0
	s_lshl_b32 s8, s0, 8
	s_and_b32 s8, s8, 0xfffffe00
	s_add_u32 s4, s4, s8
	s_addc_u32 s5, s5, 0
	s_lshl_b64 s[8:9], s[0:1], 17
	s_add_u32 s8, s40, s8
	v_mov_b32_e32 v33, v1
	s_addc_u32 s9, s41, s9
	v_lshl_add_u64 v[2:3], s[4:5], 0, v[32:33]
	v_mov_b32_e32 v37, v1
	v_lshl_add_u64 v[50:51], v[2:3], 0, v[36:37]
	v_lshl_add_u64 v[2:3], s[8:9], 0, v[16:17]
	v_lshl_add_u64 v[52:53], v[2:3], 0, v[36:37]
	v_lshl_add_u64 v[2:3], s[8:9], 0, v[18:19]
	v_lshl_add_u64 v[54:55], v[2:3], 0, v[36:37]
	global_load_dwordx4 v[2:5], v[50:51], off
	global_load_dwordx4 v[6:9], v[52:53], off
	global_load_dwordx4 v[38:41], v[54:55], off
	v_readlane_b32 s4, v254, 7
	v_readlane_b32 s5, v254, 8
	s_waitcnt vmcnt(1)
	v_mfma_f32_16x16x32_bf16 v[6:9], v[2:5], v[6:9], 0
	s_waitcnt vmcnt(0)
	v_mfma_f32_16x16x32_bf16 v[2:5], v[2:5], v[38:41], 0
	global_load_dwordx4 v[38:41], v[50:51], off offset:64
	global_load_dwordx4 v[42:45], v[52:53], off offset:64
	global_load_dwordx4 v[46:49], v[54:55], off offset:64
	s_waitcnt vmcnt(1)
	v_mfma_f32_16x16x32_bf16 v[6:9], v[38:41], v[42:45], v[6:9]
	s_waitcnt vmcnt(0)
	v_mfma_f32_16x16x32_bf16 v[2:5], v[38:41], v[46:49], v[2:5]
	global_load_dwordx4 v[38:41], v[50:51], off offset:128
	global_load_dwordx4 v[42:45], v[52:53], off offset:128
	global_load_dwordx4 v[46:49], v[54:55], off offset:128
	s_waitcnt vmcnt(1)
	v_mfma_f32_16x16x32_bf16 v[6:9], v[38:41], v[42:45], v[6:9]
	s_waitcnt vmcnt(0)
	v_mfma_f32_16x16x32_bf16 v[2:5], v[38:41], v[46:49], v[2:5]
	global_load_dwordx4 v[38:41], v[50:51], off offset:192
	global_load_dwordx4 v[42:45], v[52:53], off offset:192
	global_load_dwordx4 v[46:49], v[54:55], off offset:192
	s_waitcnt vmcnt(1)
	v_mfma_f32_16x16x32_bf16 v[6:9], v[38:41], v[42:45], v[6:9]
	s_waitcnt vmcnt(0)
	v_mfma_f32_16x16x32_bf16 v[2:5], v[38:41], v[46:49], v[2:5]
	global_load_dwordx4 v[38:41], v[50:51], off offset:256
	global_load_dwordx4 v[42:45], v[52:53], off offset:256
	global_load_dwordx4 v[46:49], v[54:55], off offset:256
	s_waitcnt vmcnt(1)
	v_mfma_f32_16x16x32_bf16 v[6:9], v[38:41], v[42:45], v[6:9]
	s_waitcnt vmcnt(0)
	v_mfma_f32_16x16x32_bf16 v[2:5], v[38:41], v[46:49], v[2:5]
	global_load_dwordx4 v[38:41], v[50:51], off offset:320
	global_load_dwordx4 v[42:45], v[52:53], off offset:320
	global_load_dwordx4 v[46:49], v[54:55], off offset:320
	s_waitcnt vmcnt(1)
	v_mfma_f32_16x16x32_bf16 v[6:9], v[38:41], v[42:45], v[6:9]
	s_waitcnt vmcnt(0)
	v_mfma_f32_16x16x32_bf16 v[2:5], v[38:41], v[46:49], v[2:5]
	global_load_dwordx4 v[38:41], v[50:51], off offset:384
	global_load_dwordx4 v[42:45], v[52:53], off offset:384
	global_load_dwordx4 v[46:49], v[54:55], off offset:384
	s_waitcnt vmcnt(1)
	v_mfma_f32_16x16x32_bf16 v[6:9], v[38:41], v[42:45], v[6:9]
	s_waitcnt vmcnt(0)
	v_mfma_f32_16x16x32_bf16 v[2:5], v[38:41], v[46:49], v[2:5]
	global_load_dwordx4 v[38:41], v[50:51], off offset:448
	global_load_dwordx4 v[42:45], v[52:53], off offset:448
	global_load_dwordx4 v[46:49], v[54:55], off offset:448
	s_load_dwordx2 s[24:25], s[4:5], 0xb8
	s_load_dwordx4 s[8:11], s[4:5], 0xc8
	s_waitcnt vmcnt(1)
	v_mfma_f32_16x16x32_bf16 v[6:9], v[38:41], v[42:45], v[6:9]
	s_waitcnt vmcnt(0)
	v_mfma_f32_16x16x32_bf16 v[2:5], v[38:41], v[46:49], v[2:5]
	v_lshl_add_u32 v38, s0, 7, v14
	v_add_u32_e32 v40, s16, v38
	v_ashrrev_i32_e32 v41, 31, v40
	v_lshlrev_b64 v[40:41], 2, v[40:41]
	s_waitcnt lgkmcnt(0)
	v_lshl_add_u64 v[42:43], s[10:11], 0, v[40:41]
	global_load_dword v0, v[42:43], off
	v_lshl_add_u64 v[42:43], s[24:25], 0, v[40:41]
	global_load_dword v35, v[42:43], off
	s_mov_b32 s0, 0xbfb8aa3b
	v_lshl_add_u64 v[40:41], s[8:9], 0, v[40:41]
	v_ashrrev_i32_e32 v39, 31, v38
	s_waitcnt vmcnt(1)
	v_max_f32_e64 v15, -v0, -v0
	v_mul_f32_e64 v0, |v0|, s0
	v_exp_f32_e32 v0, v0
	s_mov_b32 s0, 0x800000
	v_max_f32_e32 v15, 0, v15
	v_add_f32_e32 v0, 1.0, v0
	v_cmp_gt_f32_e32 vcc, s0, v0
	s_mov_b32 s0, 0x3f317217
	s_nop 0
	v_cndmask_b32_e64 v33, 0, 32, vcc
	v_ldexp_f32 v0, v0, v33
	v_log_f32_e32 v0, v0
	s_nop 0
	v_mul_f32_e32 v33, 0x3f317217, v0
	v_fma_f32 v33, v0, s0, -v33
	v_fmac_f32_e32 v33, 0x3377d1cf, v0
	s_mov_b32 s0, 0x7f800000
	v_fmac_f32_e32 v33, 0x3f317217, v0
	v_cmp_lt_f32_e64 s[4:5], |v0|, s0
	s_mov_b32 s0, 0xbdcccccd
	s_nop 0
	v_cndmask_b32_e64 v0, v0, v33, s[4:5]
	v_cndmask_b32_e32 v33, 0, v251, vcc
	v_sub_f32_e32 v0, v0, v33
	v_add_f32_e32 v33, v15, v0
	global_load_dword v15, v[40:41], off
	s_waitcnt vmcnt(1)
	v_add_f32_e32 v0, v6, v35
	v_mul_f32_e32 v0, 0xbfb8aa3b, v0
	v_exp_f32_e32 v0, v0
	s_nop 0
	v_add_f32_e32 v0, 1.0, v0
	v_rcp_f32_e32 v0, v0
	s_nop 0
	v_mul_f32_e32 v0, 0xc1000000, v0
	v_mul_f32_e32 v0, v33, v0
	v_mul_f32_e32 v6, 0x3fb8aa3b, v0
	v_exp_f32_e32 v6, v6
	v_lshlrev_b32_e32 v40, 9, v13
	v_mov_b32_e32 v41, v1
	v_lshl_add_u64 v[42:43], v[40:41], 0, v[38:39]
	v_lshl_add_u64 v[44:45], v[42:43], 2, s[12:13]
	global_store_dword v[44:45], v6, off
	v_add_f32_e32 v6, v0, v0
	v_cmp_nlt_f32_e32 vcc, s0, v6
	s_and_saveexec_b64 s[4:5], vcc
	s_xor_b64 s[4:5], exec, s[4:5]
	v_mul_f32_e32 v0, 0x3fb8aa3b, v6
	v_exp_f32_e32 v0, v0
	s_nop 0
	v_sub_f32_e32 v0, 1.0, v0
	s_andn2_saveexec_b64 s[4:5], s[4:5]
	v_fmamk_f32 v0, v6, 0x3d2aaaab, v171
	v_fma_f32 v0, v6, v0, 0.5
	v_fma_f32 v0, v6, v0, 1.0
	v_mul_f32_e64 v0, v6, -v0
	s_or_b64 exec, exec, s[4:5]
	s_waitcnt vmcnt(1)
	v_add_f32_e32 v2, v2, v15
	v_mul_f32_e32 v2, 0xbfb8aa3b, v2
	v_exp_f32_e32 v2, v2
	s_mov_b32 s0, 0xf800000
	v_add_f32_e32 v2, 1.0, v2
	v_rcp_f32_e32 v2, v2
	s_nop 0
	v_cmp_gt_f32_e32 vcc, s0, v0
	v_mul_f32_e32 v6, 0x4f800000, v0
	v_lshl_add_u64 v[44:45], v[42:43], 1, s[6:7]
	v_cndmask_b32_e32 v0, v0, v6, vcc
	v_sqrt_f32_e32 v6, v0
	v_lshl_add_u64 v[42:43], v[42:43], 2, s[14:15]
	s_mov_b32 s0, 0xbdcccccd
	v_add_u32_e32 v37, -1, v6
	v_fma_f32 v41, -v37, v6, v0
	v_cmp_ge_f32_e64 s[4:5], 0, v41
	v_add_u32_e32 v41, 1, v6
	s_nop 0
	v_cndmask_b32_e64 v37, v6, v37, s[4:5]
	v_fma_f32 v6, -v41, v6, v0
	v_cmp_lt_f32_e64 s[4:5], 0, v6
	s_nop 1
	v_cndmask_b32_e64 v6, v37, v41, s[4:5]
	v_mul_f32_e32 v37, 0x37800000, v6
	v_cndmask_b32_e32 v6, v6, v37, vcc
	v_cmp_class_f32_e32 vcc, v0, v200
	s_nop 1
	v_cndmask_b32_e32 v0, v6, v0, vcc
	v_mul_f32_e32 v0, v2, v0
	global_load_ushort v2, v[44:45], off
	s_waitcnt vmcnt(0)
	v_lshlrev_b32_e32 v2, 16, v2
	v_mul_f32_e32 v0, v0, v2
	global_store_dword v[42:43], v0, off
	v_add_f32_e32 v0, v7, v35
	v_mul_f32_e32 v0, 0xbfb8aa3b, v0
	v_exp_f32_e32 v0, v0
	s_nop 0
	v_add_f32_e32 v0, 1.0, v0
	v_rcp_f32_e32 v0, v0
	s_nop 0
	v_mul_f32_e32 v0, 0xc1000000, v0
	v_mul_f32_e32 v2, v33, v0
	v_mul_f32_e32 v0, 0x3fb8aa3b, v2
	v_exp_f32_e32 v37, v0
	v_or_b32_e32 v0, 0x200, v40
	v_lshl_add_u64 v[6:7], v[0:1], 0, v[38:39]
	v_add_f32_e32 v0, v2, v2
	v_lshl_add_u64 v[42:43], v[6:7], 2, s[12:13]
	v_cmp_nlt_f32_e32 vcc, s0, v0
	global_store_dword v[42:43], v37, off
	s_and_saveexec_b64 s[4:5], vcc
	s_xor_b64 s[4:5], exec, s[4:5]
	v_mul_f32_e32 v0, 0x3fb8aa3b, v0
	v_exp_f32_e32 v0, v0
	s_nop 0
	v_sub_f32_e32 v2, 1.0, v0
	s_andn2_saveexec_b64 s[4:5], s[4:5]
	v_fmamk_f32 v2, v0, 0x3d2aaaab, v171
	v_fma_f32 v2, v0, v2, 0.5
	v_fma_f32 v2, v0, v2, 1.0
	v_mul_f32_e64 v2, v0, -v2
	s_or_b64 exec, exec, s[4:5]
	v_add_f32_e32 v0, v3, v15
	v_mul_f32_e32 v0, 0xbfb8aa3b, v0
	v_exp_f32_e32 v0, v0
	s_mov_b32 s0, 0xf800000
	v_add_f32_e32 v0, 1.0, v0
	v_rcp_f32_e32 v0, v0
	s_nop 0
	v_cmp_gt_f32_e32 vcc, s0, v2
	v_mul_f32_e32 v3, 0x4f800000, v2
	s_mov_b32 s0, 0xbdcccccd
	v_cndmask_b32_e32 v2, v2, v3, vcc
	v_sqrt_f32_e32 v3, v2
	s_nop 0
	v_add_u32_e32 v37, -1, v3
	v_fma_f32 v41, -v37, v3, v2
	v_cmp_ge_f32_e64 s[4:5], 0, v41
	v_add_u32_e32 v41, 1, v3
	s_nop 0
	v_cndmask_b32_e64 v37, v3, v37, s[4:5]
	v_fma_f32 v3, -v41, v3, v2
	v_cmp_lt_f32_e64 s[4:5], 0, v3
	s_nop 1
	v_cndmask_b32_e64 v3, v37, v41, s[4:5]
	v_mul_f32_e32 v37, 0x37800000, v3
	v_cndmask_b32_e32 v3, v3, v37, vcc
	v_cmp_class_f32_e32 vcc, v2, v200
	s_nop 1
	v_cndmask_b32_e32 v2, v3, v2, vcc
	v_mul_f32_e32 v0, v0, v2
	v_lshl_add_u64 v[2:3], v[6:7], 1, s[6:7]
	global_load_ushort v2, v[2:3], off
	s_waitcnt vmcnt(0)
	v_lshlrev_b32_e32 v2, 16, v2
	v_mul_f32_e32 v0, v0, v2
	v_lshl_add_u64 v[2:3], v[6:7], 2, s[14:15]
	global_store_dword v[2:3], v0, off
	v_add_f32_e32 v0, v8, v35
	v_mul_f32_e32 v0, 0xbfb8aa3b, v0
	v_exp_f32_e32 v0, v0
	s_nop 0
	v_add_f32_e32 v0, 1.0, v0
	v_rcp_f32_e32 v0, v0
	s_nop 0
	v_mul_f32_e32 v0, 0xc1000000, v0
	v_mul_f32_e32 v8, v33, v0
	v_mul_f32_e32 v0, 0x3fb8aa3b, v8
	v_exp_f32_e32 v37, v0
	v_or_b32_e32 v0, 0x400, v40
	v_lshl_add_u64 v[2:3], v[0:1], 0, v[38:39]
	v_add_f32_e32 v0, v8, v8
	v_lshl_add_u64 v[6:7], v[2:3], 2, s[12:13]
	v_cmp_nlt_f32_e32 vcc, s0, v0
	global_store_dword v[6:7], v37, off
	s_and_saveexec_b64 s[4:5], vcc
	s_xor_b64 s[4:5], exec, s[4:5]
	v_mul_f32_e32 v0, 0x3fb8aa3b, v0
	v_exp_f32_e32 v0, v0
	s_nop 0
	v_sub_f32_e32 v6, 1.0, v0
	s_andn2_saveexec_b64 s[4:5], s[4:5]
	v_fmamk_f32 v6, v0, 0x3d2aaaab, v171
	v_fma_f32 v6, v0, v6, 0.5
	v_fma_f32 v6, v0, v6, 1.0
	v_mul_f32_e64 v6, v0, -v6
	s_or_b64 exec, exec, s[4:5]
	v_add_f32_e32 v0, v4, v15
	v_mul_f32_e32 v0, 0xbfb8aa3b, v0
	v_exp_f32_e32 v0, v0
	s_mov_b32 s0, 0xf800000
	v_add_f32_e32 v0, 1.0, v0
	v_rcp_f32_e32 v0, v0
	s_nop 0
	v_cmp_gt_f32_e32 vcc, s0, v6
	v_mul_f32_e32 v4, 0x4f800000, v6
	s_mov_b32 s0, 0xbdcccccd
	v_cndmask_b32_e32 v4, v6, v4, vcc
	v_sqrt_f32_e32 v6, v4
	s_nop 0
	v_add_u32_e32 v7, -1, v6
	v_fma_f32 v8, -v7, v6, v4
	v_cmp_ge_f32_e64 s[4:5], 0, v8
	v_add_u32_e32 v8, 1, v6
	s_nop 0
	v_cndmask_b32_e64 v7, v6, v7, s[4:5]
	v_fma_f32 v6, -v8, v6, v4
	v_cmp_lt_f32_e64 s[4:5], 0, v6
	s_nop 1
	v_cndmask_b32_e64 v6, v7, v8, s[4:5]
	v_mul_f32_e32 v7, 0x37800000, v6
	v_cndmask_b32_e32 v6, v6, v7, vcc
	v_cmp_class_f32_e32 vcc, v4, v200
	s_nop 1
	v_cndmask_b32_e32 v4, v6, v4, vcc
	v_lshl_add_u64 v[6:7], v[2:3], 1, s[6:7]
	v_mul_f32_e32 v0, v0, v4
	global_load_ushort v4, v[6:7], off
	v_lshl_add_u64 v[2:3], v[2:3], 2, s[14:15]
	s_waitcnt vmcnt(0)
	v_lshlrev_b32_e32 v4, 16, v4
	v_mul_f32_e32 v0, v0, v4
	global_store_dword v[2:3], v0, off
	v_add_f32_e32 v0, v9, v35
	v_mul_f32_e32 v0, 0xbfb8aa3b, v0
	v_exp_f32_e32 v0, v0
	s_nop 0
	v_add_f32_e32 v0, 1.0, v0
	v_rcp_f32_e32 v0, v0
	s_nop 0
	v_mul_f32_e32 v0, 0xc1000000, v0
	v_mul_f32_e32 v4, v33, v0
	v_mul_f32_e32 v0, 0x3fb8aa3b, v4
	v_exp_f32_e32 v8, v0
	v_or_b32_e32 v0, 0x600, v40
	v_lshl_add_u64 v[2:3], v[0:1], 0, v[38:39]
	v_add_f32_e32 v0, v4, v4
	v_lshl_add_u64 v[6:7], v[2:3], 2, s[12:13]
	v_cmp_nlt_f32_e32 vcc, s0, v0
	global_store_dword v[6:7], v8, off
	s_and_saveexec_b64 s[4:5], vcc
	s_xor_b64 s[4:5], exec, s[4:5]
	v_mul_f32_e32 v0, 0x3fb8aa3b, v0
	v_exp_f32_e32 v0, v0
	s_nop 0
	v_sub_f32_e32 v4, 1.0, v0
	s_andn2_saveexec_b64 s[4:5], s[4:5]
	v_fmamk_f32 v4, v0, 0x3d2aaaab, v171
	v_fma_f32 v4, v0, v4, 0.5
	v_fma_f32 v4, v0, v4, 1.0
	v_mul_f32_e64 v4, v0, -v4
	s_or_b64 exec, exec, s[4:5]
	v_add_f32_e32 v0, v5, v15
	v_mul_f32_e32 v0, 0xbfb8aa3b, v0
	v_exp_f32_e32 v0, v0
	s_mov_b32 s0, 0xf800000
	v_add_f32_e32 v0, 1.0, v0
	v_rcp_f32_e32 v0, v0
	s_nop 0
	v_cmp_gt_f32_e32 vcc, s0, v4
	v_mul_f32_e32 v5, 0x4f800000, v4
	s_nop 0
	v_cndmask_b32_e32 v4, v4, v5, vcc
	v_sqrt_f32_e32 v5, v4
	s_nop 0
	v_add_u32_e32 v6, -1, v5
	v_fma_f32 v7, -v6, v5, v4
	v_cmp_ge_f32_e64 s[4:5], 0, v7
	v_add_u32_e32 v7, 1, v5
	s_nop 0
	v_cndmask_b32_e64 v6, v5, v6, s[4:5]
	v_fma_f32 v5, -v7, v5, v4
	v_cmp_lt_f32_e64 s[4:5], 0, v5
	s_nop 1
	v_cndmask_b32_e64 v5, v6, v7, s[4:5]
	v_mul_f32_e32 v6, 0x37800000, v5
	v_cndmask_b32_e32 v5, v5, v6, vcc
	v_cmp_class_f32_e32 vcc, v4, v200
	s_mov_b64 s[4:5], 0
	s_nop 0
	v_cndmask_b32_e32 v4, v5, v4, vcc
	v_mul_f32_e32 v0, v0, v4
	v_lshl_add_u64 v[4:5], v[2:3], 1, s[6:7]
	global_load_ushort v4, v[4:5], off
	v_lshl_add_u64 v[2:3], v[2:3], 2, s[14:15]
	s_waitcnt vmcnt(0)
	v_lshlrev_b32_e32 v4, 16, v4
	v_mul_f32_e32 v0, v0, v4
	global_store_dword v[2:3], v0, off

.LBB0_988:
	v_add_u32_e32 v0, s16, v131
	v_ashrrev_i32_e32 v70, 6, v0
	v_mad_u64_u32 v[66:67], s[18:19], v70, s33, v[130:131]
	ds_read_b128 v[66:69], v66
	v_add_u32_e32 v70, s50, v70
	s_addk_i32 s16, 0x800
	s_cmpk_eq_i32 s16, 0x2000
	s_waitcnt lgkmcnt(0)
	v_mul_f32_e32 v66, 0xbfb8aa3b, v66
	v_mul_f32_e32 v67, 0xbfb8aa3b, v67
	v_exp_f32_e32 v66, v66
	v_exp_f32_e32 v67, v67
	s_nop 0
	v_pk_add_f32 v[66:67], v[66:67], 1.0 op_sel_hi:[1,0]
	s_nop 0
	v_rcp_f32_e32 v71, v67
	s_nop 0
	v_rcp_f32_e32 v72, v66
	s_nop 0
	v_mul_f32_e32 v66, 0xbfb8aa3b, v68
	v_mul_f32_e32 v67, 0xbfb8aa3b, v69
	v_exp_f32_e32 v66, v66
	v_exp_f32_e32 v67, v67
	s_nop 0
	v_pk_add_f32 v[66:67], v[66:67], 1.0 op_sel_hi:[1,0]
	s_nop 0
	v_rcp_f32_e32 v67, v67
	s_nop 0
	v_rcp_f32_e32 v68, v66
	s_nop 0
	v_cvt_pk_bf16_f32 v66, v72, v71
	v_cvt_pk_bf16_f32 v67, v68, v67
	v_mad_i64_i32 v[68:69], s[18:19], v70, s96, v[132:133]
	global_store_dwordx2 v[68:69], v[66:67], off
	v_add_u32_e32 v66, 0x200, v0
	v_ashrrev_i32_e32 v70, 6, v66
	v_mad_u64_u32 v[66:67], s[18:19], v70, s33, v[130:131]
	ds_read_b128 v[66:69], v66
	v_add_u32_e32 v70, s50, v70
	s_waitcnt lgkmcnt(0)
	v_mul_f32_e32 v66, 0xbfb8aa3b, v66
	v_mul_f32_e32 v67, 0xbfb8aa3b, v67
	v_exp_f32_e32 v66, v66
	v_exp_f32_e32 v67, v67
	s_nop 0
	v_pk_add_f32 v[66:67], v[66:67], 1.0 op_sel_hi:[1,0]
	s_nop 0
	v_rcp_f32_e32 v71, v67
	s_nop 0
	v_rcp_f32_e32 v72, v66
	s_nop 0
	v_mul_f32_e32 v66, 0xbfb8aa3b, v68
	v_mul_f32_e32 v67, 0xbfb8aa3b, v69
	v_exp_f32_e32 v66, v66
	v_exp_f32_e32 v67, v67
	s_nop 0
	v_pk_add_f32 v[66:67], v[66:67], 1.0 op_sel_hi:[1,0]
	s_nop 0
	v_rcp_f32_e32 v67, v67
	s_nop 0
	v_rcp_f32_e32 v68, v66
	s_nop 0
	v_cvt_pk_bf16_f32 v66, v72, v71
	v_cvt_pk_bf16_f32 v67, v68, v67
	v_mad_i64_i32 v[68:69], s[18:19], v70, s96, v[132:133]
	global_store_dwordx2 v[68:69], v[66:67], off
	v_add_u32_e32 v66, 0x400, v0
	v_ashrrev_i32_e32 v70, 6, v66
	v_mad_u64_u32 v[66:67], s[18:19], v70, s33, v[130:131]
	ds_read_b128 v[66:69], v66
	v_add_u32_e32 v70, s50, v70
	v_add_u32_e32 v0, 0x600, v0
	v_ashrrev_i32_e32 v0, 6, v0
	s_waitcnt lgkmcnt(0)
	v_mul_f32_e32 v66, 0xbfb8aa3b, v66
	v_mul_f32_e32 v67, 0xbfb8aa3b, v67
	v_exp_f32_e32 v66, v66
	v_exp_f32_e32 v67, v67
	s_nop 0
	v_pk_add_f32 v[66:67], v[66:67], 1.0 op_sel_hi:[1,0]
	s_nop 0
	v_rcp_f32_e32 v71, v67
	s_nop 0
	v_rcp_f32_e32 v72, v66
	s_nop 0
	v_mul_f32_e32 v66, 0xbfb8aa3b, v68
	v_mul_f32_e32 v67, 0xbfb8aa3b, v69
	v_exp_f32_e32 v66, v66
	v_exp_f32_e32 v67, v67
	s_nop 0
	v_pk_add_f32 v[66:67], v[66:67], 1.0 op_sel_hi:[1,0]
	s_nop 0
	v_rcp_f32_e32 v67, v67
	s_nop 0
	v_rcp_f32_e32 v68, v66
	s_nop 0
	v_cvt_pk_bf16_f32 v66, v72, v71
	v_cvt_pk_bf16_f32 v67, v68, v67
	v_mad_i64_i32 v[68:69], s[18:19], v70, s96, v[132:133]
	global_store_dwordx2 v[68:69], v[66:67], off
	v_mad_u64_u32 v[66:67], s[18:19], v0, s33, v[130:131]
	ds_read_b128 v[66:69], v66
	v_add_u32_e32 v0, s50, v0
	s_waitcnt lgkmcnt(0)
	v_mul_f32_e32 v66, 0xbfb8aa3b, v66
	v_mul_f32_e32 v67, 0xbfb8aa3b, v67
	v_exp_f32_e32 v66, v66
	v_exp_f32_e32 v67, v67
	s_nop 0
	v_pk_add_f32 v[66:67], v[66:67], 1.0 op_sel_hi:[1,0]
	s_nop 0
	v_rcp_f32_e32 v70, v67
	s_nop 0
	v_rcp_f32_e32 v71, v66
	s_nop 0
	v_mul_f32_e32 v66, 0xbfb8aa3b, v68
	v_mul_f32_e32 v67, 0xbfb8aa3b, v69
	v_exp_f32_e32 v66, v66
	v_exp_f32_e32 v67, v67
	s_nop 0
	v_pk_add_f32 v[66:67], v[66:67], 1.0 op_sel_hi:[1,0]
	s_nop 0
	v_rcp_f32_e32 v67, v67
	s_nop 0
	v_rcp_f32_e32 v68, v66
	s_nop 0
	v_cvt_pk_bf16_f32 v66, v71, v70
	v_cvt_pk_bf16_f32 v67, v68, v67
	v_mad_i64_i32 v[68:69], s[18:19], v0, s96, v[132:133]
	global_store_dwordx2 v[68:69], v[66:67], off
	s_cbranch_scc0 .LBB0_988

.LBB0_1097:
	v_add_u32_e32 v0, s12, v131
	v_ashrrev_i32_e32 v6, 6, v0
	v_mad_u64_u32 v[2:3], s[14:15], v6, s33, v[130:131]
	ds_read_b128 v[2:5], v2
	v_add_u32_e32 v6, s50, v6
	s_addk_i32 s12, 0x800
	s_cmpk_eq_i32 s12, 0x2000
	s_waitcnt lgkmcnt(0)
	v_mul_f32_e32 v2, 0xbfb8aa3b, v2
	v_mul_f32_e32 v3, 0xbfb8aa3b, v3
	v_exp_f32_e32 v2, v2
	v_exp_f32_e32 v3, v3
	s_nop 0
	v_pk_add_f32 v[2:3], v[2:3], 1.0 op_sel_hi:[1,0]
	s_nop 0
	v_rcp_f32_e32 v7, v3
	s_nop 0
	v_rcp_f32_e32 v8, v2
	s_nop 0
	v_mul_f32_e32 v2, 0xbfb8aa3b, v4
	v_mul_f32_e32 v3, 0xbfb8aa3b, v5
	v_exp_f32_e32 v2, v2
	v_exp_f32_e32 v3, v3
	s_nop 0
	v_pk_add_f32 v[2:3], v[2:3], 1.0 op_sel_hi:[1,0]
	s_nop 0
	v_rcp_f32_e32 v3, v3
	s_nop 0
	v_rcp_f32_e32 v4, v2
	s_nop 0
	v_cvt_pk_bf16_f32 v2, v8, v7
	v_cvt_pk_bf16_f32 v3, v4, v3
	v_mad_i64_i32 v[4:5], s[14:15], v6, s96, v[132:133]
	global_store_dwordx2 v[4:5], v[2:3], off
	v_add_u32_e32 v2, 0x200, v0
	v_ashrrev_i32_e32 v6, 6, v2
	v_mad_u64_u32 v[2:3], s[14:15], v6, s33, v[130:131]
	ds_read_b128 v[2:5], v2
	v_add_u32_e32 v6, s50, v6
	s_waitcnt lgkmcnt(0)
	v_mul_f32_e32 v2, 0xbfb8aa3b, v2
	v_mul_f32_e32 v3, 0xbfb8aa3b, v3
	v_exp_f32_e32 v2, v2
	v_exp_f32_e32 v3, v3
	s_nop 0
	v_pk_add_f32 v[2:3], v[2:3], 1.0 op_sel_hi:[1,0]
	s_nop 0
	v_rcp_f32_e32 v7, v3
	s_nop 0
	v_rcp_f32_e32 v8, v2
	s_nop 0
	v_mul_f32_e32 v2, 0xbfb8aa3b, v4
	v_mul_f32_e32 v3, 0xbfb8aa3b, v5
	v_exp_f32_e32 v2, v2
	v_exp_f32_e32 v3, v3
	s_nop 0
	v_pk_add_f32 v[2:3], v[2:3], 1.0 op_sel_hi:[1,0]
	s_nop 0
	v_rcp_f32_e32 v3, v3
	s_nop 0
	v_rcp_f32_e32 v4, v2
	s_nop 0
	v_cvt_pk_bf16_f32 v2, v8, v7
	v_cvt_pk_bf16_f32 v3, v4, v3
	v_mad_i64_i32 v[4:5], s[14:15], v6, s96, v[132:133]
	global_store_dwordx2 v[4:5], v[2:3], off
	v_add_u32_e32 v2, 0x400, v0
	v_ashrrev_i32_e32 v6, 6, v2
	v_mad_u64_u32 v[2:3], s[14:15], v6, s33, v[130:131]
	ds_read_b128 v[2:5], v2
	v_add_u32_e32 v6, s50, v6
	v_add_u32_e32 v0, 0x600, v0
	v_ashrrev_i32_e32 v0, 6, v0
	s_waitcnt lgkmcnt(0)
	v_mul_f32_e32 v2, 0xbfb8aa3b, v2
	v_mul_f32_e32 v3, 0xbfb8aa3b, v3
	v_exp_f32_e32 v2, v2
	v_exp_f32_e32 v3, v3
	s_nop 0
	v_pk_add_f32 v[2:3], v[2:3], 1.0 op_sel_hi:[1,0]
	s_nop 0
	v_rcp_f32_e32 v7, v3
	s_nop 0
	v_rcp_f32_e32 v8, v2
	s_nop 0
	v_mul_f32_e32 v2, 0xbfb8aa3b, v4
	v_mul_f32_e32 v3, 0xbfb8aa3b, v5
	v_exp_f32_e32 v2, v2
	v_exp_f32_e32 v3, v3
	s_nop 0
	v_pk_add_f32 v[2:3], v[2:3], 1.0 op_sel_hi:[1,0]
	s_nop 0
	v_rcp_f32_e32 v3, v3
	s_nop 0
	v_rcp_f32_e32 v4, v2
	s_nop 0
	v_cvt_pk_bf16_f32 v2, v8, v7
	v_cvt_pk_bf16_f32 v3, v4, v3
	v_mad_i64_i32 v[4:5], s[14:15], v6, s96, v[132:133]
	global_store_dwordx2 v[4:5], v[2:3], off
	v_mad_u64_u32 v[2:3], s[14:15], v0, s33, v[130:131]
	ds_read_b128 v[2:5], v2
	v_add_u32_e32 v0, s50, v0
	s_waitcnt lgkmcnt(0)
	v_mul_f32_e32 v2, 0xbfb8aa3b, v2
	v_mul_f32_e32 v3, 0xbfb8aa3b, v3
	v_exp_f32_e32 v2, v2
	v_exp_f32_e32 v3, v3
	s_nop 0
	v_pk_add_f32 v[2:3], v[2:3], 1.0 op_sel_hi:[1,0]
	s_nop 0
	v_rcp_f32_e32 v6, v3
	s_nop 0
	v_rcp_f32_e32 v7, v2
	s_nop 0
	v_mul_f32_e32 v2, 0xbfb8aa3b, v4
	v_mul_f32_e32 v3, 0xbfb8aa3b, v5
	v_exp_f32_e32 v2, v2
	v_exp_f32_e32 v3, v3
	s_nop 0
	v_pk_add_f32 v[2:3], v[2:3], 1.0 op_sel_hi:[1,0]
	s_nop 0
	v_rcp_f32_e32 v3, v3
	s_nop 0
	v_rcp_f32_e32 v4, v2
	s_nop 0
	v_cvt_pk_bf16_f32 v2, v7, v6
	v_cvt_pk_bf16_f32 v3, v4, v3
	v_mad_i64_i32 v[4:5], s[14:15], v0, s96, v[132:133]
	global_store_dwordx2 v[4:5], v[2:3], off
	s_cbranch_scc0 .LBB0_1097
	s_branch .LBB0_873

.LBB0_1101:
	s_and_b32 s4, s48, 0xffffff00
	s_lshl_b32 s0, s46, 11
	s_ashr_i32 s5, s4, 31
	s_and_b32 s0, s0, 0x38000
	s_lshl_b64 s[4:5], s[4:5], 11
	v_mov_b32_e32 v6, 0
	v_lshl_add_u64 v[18:19], v[12:13], 0, s[0:1]
	v_lshl_add_u64 v[20:21], v[14:15], 0, s[4:5]
	v_lshl_add_u64 v[22:23], v[16:17], 0, s[4:5]
	s_movk_i32 s0, 0xffe0
	v_mov_b32_e32 v7, v6
	v_mov_b32_e32 v8, v6
	v_mov_b32_e32 v9, v6
	v_mov_b32_e32 v2, v6
	v_mov_b32_e32 v3, v6
	v_mov_b32_e32 v4, v6
	v_mov_b32_e32 v5, v6
	global_load_dwordx4 v[24:27], v[18:19], off offset:-256
	global_load_dwordx4 v[28:31], v[20:21], off offset:-256
	global_load_dwordx4 v[32:35], v[22:23], off offset:-256
	global_load_dwordx4 v[96:99], v[18:19], off offset:-192
	global_load_dwordx4 v[100:103], v[20:21], off offset:-192
	global_load_dwordx4 v[104:107], v[22:23], off offset:-192
	global_load_dwordx4 v[108:111], v[18:19], off offset:-128
	global_load_dwordx4 v[112:115], v[20:21], off offset:-128
	global_load_dwordx4 v[116:119], v[22:23], off offset:-128
	global_load_dwordx4 v[120:123], v[18:19], off offset:-64
	global_load_dwordx4 v[124:127], v[20:21], off offset:-64
	global_load_dwordx4 v[128:131], v[22:23], off offset:-64
	global_load_dwordx4 v[132:135], v[18:19], off
	global_load_dwordx4 v[136:139], v[20:21], off
	global_load_dwordx4 v[140:143], v[22:23], off
	global_load_dwordx4 v[144:147], v[18:19], off offset:64
	global_load_dwordx4 v[148:151], v[20:21], off offset:64
	global_load_dwordx4 v[152:155], v[22:23], off offset:64
	global_load_dwordx4 v[156:159], v[18:19], off offset:128
	global_load_dwordx4 v[160:163], v[20:21], off offset:128
	global_load_dwordx4 v[164:167], v[22:23], off offset:128
	global_load_dwordx4 v[172:175], v[18:19], off offset:192
	global_load_dwordx4 v[176:179], v[20:21], off offset:192
	global_load_dwordx4 v[180:183], v[22:23], off offset:192
	v_lshl_add_u64 v[18:19], v[18:19], 0, s[22:23]
	v_lshl_add_u64 v[20:21], v[20:21], 0, s[22:23]
	v_lshl_add_u64 v[22:23], v[22:23], 0, s[22:23]
.Lsg3_loop:
	s_addk_i32 s0, 0x100
	s_cmpk_lt_u32 s0, 0x3e0
	s_cbranch_scc0 .Lsg3_tail
	s_waitcnt vmcnt(21)
	v_mfma_f32_16x16x32_bf16 v[6:9], v[24:27], v[28:31], v[6:9]
	v_mfma_f32_16x16x32_bf16 v[2:5], v[24:27], v[32:35], v[2:5]
	global_load_dwordx4 v[24:27], v[18:19], off offset:-256
	global_load_dwordx4 v[28:31], v[20:21], off offset:-256
	global_load_dwordx4 v[32:35], v[22:23], off offset:-256
	s_waitcnt vmcnt(21)
	v_mfma_f32_16x16x32_bf16 v[6:9], v[96:99], v[100:103], v[6:9]
	v_mfma_f32_16x16x32_bf16 v[2:5], v[96:99], v[104:107], v[2:5]
	global_load_dwordx4 v[96:99], v[18:19], off offset:-192
	global_load_dwordx4 v[100:103], v[20:21], off offset:-192
	global_load_dwordx4 v[104:107], v[22:23], off offset:-192
	s_waitcnt vmcnt(21)
	v_mfma_f32_16x16x32_bf16 v[6:9], v[108:111], v[112:115], v[6:9]
	v_mfma_f32_16x16x32_bf16 v[2:5], v[108:111], v[116:119], v[2:5]
	global_load_dwordx4 v[108:111], v[18:19], off offset:-128
	global_load_dwordx4 v[112:115], v[20:21], off offset:-128
	global_load_dwordx4 v[116:119], v[22:23], off offset:-128
	s_waitcnt vmcnt(21)
	v_mfma_f32_16x16x32_bf16 v[6:9], v[120:123], v[124:127], v[6:9]
	v_mfma_f32_16x16x32_bf16 v[2:5], v[120:123], v[128:131], v[2:5]
	global_load_dwordx4 v[120:123], v[18:19], off offset:-64
	global_load_dwordx4 v[124:127], v[20:21], off offset:-64
	global_load_dwordx4 v[128:131], v[22:23], off offset:-64
	s_waitcnt vmcnt(21)
	v_mfma_f32_16x16x32_bf16 v[6:9], v[132:135], v[136:139], v[6:9]
	v_mfma_f32_16x16x32_bf16 v[2:5], v[132:135], v[140:143], v[2:5]
	global_load_dwordx4 v[132:135], v[18:19], off
	global_load_dwordx4 v[136:139], v[20:21], off
	global_load_dwordx4 v[140:143], v[22:23], off
	s_waitcnt vmcnt(21)
	v_mfma_f32_16x16x32_bf16 v[6:9], v[144:147], v[148:151], v[6:9]
	v_mfma_f32_16x16x32_bf16 v[2:5], v[144:147], v[152:155], v[2:5]
	global_load_dwordx4 v[144:147], v[18:19], off offset:64
	global_load_dwordx4 v[148:151], v[20:21], off offset:64
	global_load_dwordx4 v[152:155], v[22:23], off offset:64
	s_waitcnt vmcnt(21)
	v_mfma_f32_16x16x32_bf16 v[6:9], v[156:159], v[160:163], v[6:9]
	v_mfma_f32_16x16x32_bf16 v[2:5], v[156:159], v[164:167], v[2:5]
	global_load_dwordx4 v[156:159], v[18:19], off offset:128
	global_load_dwordx4 v[160:163], v[20:21], off offset:128
	global_load_dwordx4 v[164:167], v[22:23], off offset:128
	s_waitcnt vmcnt(21)
	v_mfma_f32_16x16x32_bf16 v[6:9], v[172:175], v[176:179], v[6:9]
	v_mfma_f32_16x16x32_bf16 v[2:5], v[172:175], v[180:183], v[2:5]
	global_load_dwordx4 v[172:175], v[18:19], off offset:192
	global_load_dwordx4 v[176:179], v[20:21], off offset:192
	global_load_dwordx4 v[180:183], v[22:23], off offset:192
	v_lshl_add_u64 v[18:19], v[18:19], 0, s[22:23]
	v_lshl_add_u64 v[20:21], v[20:21], 0, s[22:23]
	v_lshl_add_u64 v[22:23], v[22:23], 0, s[22:23]
	s_branch .Lsg3_loop
.Lsg3_tail:
	s_waitcnt vmcnt(21)
	v_mfma_f32_16x16x32_bf16 v[6:9], v[24:27], v[28:31], v[6:9]
	v_mfma_f32_16x16x32_bf16 v[2:5], v[24:27], v[32:35], v[2:5]
	s_waitcnt vmcnt(18)
	v_mfma_f32_16x16x32_bf16 v[6:9], v[96:99], v[100:103], v[6:9]
	v_mfma_f32_16x16x32_bf16 v[2:5], v[96:99], v[104:107], v[2:5]
	s_waitcnt vmcnt(15)
	v_mfma_f32_16x16x32_bf16 v[6:9], v[108:111], v[112:115], v[6:9]
	v_mfma_f32_16x16x32_bf16 v[2:5], v[108:111], v[116:119], v[2:5]
	s_waitcnt vmcnt(12)
	v_mfma_f32_16x16x32_bf16 v[6:9], v[120:123], v[124:127], v[6:9]
	v_mfma_f32_16x16x32_bf16 v[2:5], v[120:123], v[128:131], v[2:5]
	s_waitcnt vmcnt(9)
	v_mfma_f32_16x16x32_bf16 v[6:9], v[132:135], v[136:139], v[6:9]
	v_mfma_f32_16x16x32_bf16 v[2:5], v[132:135], v[140:143], v[2:5]
	s_waitcnt vmcnt(6)
	v_mfma_f32_16x16x32_bf16 v[6:9], v[144:147], v[148:151], v[6:9]
	v_mfma_f32_16x16x32_bf16 v[2:5], v[144:147], v[152:155], v[2:5]
	s_waitcnt vmcnt(3)
	v_mfma_f32_16x16x32_bf16 v[6:9], v[156:159], v[160:163], v[6:9]
	v_mfma_f32_16x16x32_bf16 v[2:5], v[156:159], v[164:167], v[2:5]
	s_waitcnt vmcnt(0)
	v_mfma_f32_16x16x32_bf16 v[6:9], v[172:175], v[176:179], v[6:9]
	v_mfma_f32_16x16x32_bf16 v[2:5], v[172:175], v[180:183], v[2:5]
	s_lshl_b32 s4, s45, 5
	s_and_b32 s4, s4, 0xffffff00
	s_lshl_b32 s0, s45, 4
	v_add_u32_e32 v0, s4, v39
	s_and_b32 s0, s0, 0x70
	v_or_b32_e32 v24, v0, v38
	v_mov_b32_e32 v25, v1
	v_or_b32_e32 v47, s0, v40
	s_movk_i32 s0, 0x1000
	v_add_u32_e32 v30, 0xfffffa00, v24
	v_mov_b32_e32 v31, v1
	v_lshl_add_u64 v[20:21], v[24:25], 1, s[6:7]
	v_ashrrev_i32_e32 v25, 31, v24
	v_or_b32_e32 v46, 0x4000, v47
	v_cmp_gt_i32_e64 s[4:5], s0, v24
	v_and_b32_e32 v45, 0xfffffe00, v0
	v_add_u32_e32 v28, 0xfffff800, v24
	v_mov_b32_e32 v29, v1
	v_lshl_add_u64 v[26:27], v[30:31], 1, s[10:11]
	v_lshl_add_u64 v[22:23], v[24:25], 1, s[6:7]
	s_and_saveexec_b64 s[12:13], s[4:5]
	s_xor_b64 s[12:13], exec, s[12:13]
	s_cbranch_execz .LBB0_1121
	s_movk_i32 s0, 0x5ff
	v_cmp_lt_i32_e32 vcc, s0, v45
	s_mov_b64 s[14:15], 0
	s_mov_b64 s[18:19], 0
	s_and_saveexec_b64 s[16:17], vcc
	s_xor_b64 s[16:17], exec, s[16:17]
	s_cbranch_execz .LBB0_1116
	s_movk_i32 s0, 0x7ff
	v_cmp_lt_i32_e32 vcc, s0, v45
	s_and_saveexec_b64 s[24:25], vcc
	s_xor_b64 s[24:25], exec, s[24:25]
	s_cbranch_execz .LBB0_1109
	s_movk_i32 s0, 0x800
	v_cmp_eq_u32_e32 vcc, s0, v45
	s_mov_b64 s[26:27], -1
	s_and_saveexec_b64 s[18:19], vcc
	s_cbranch_execz .LBB0_1108
	v_readlane_b32 s26, v254, 7
	v_readlane_b32 s27, v254, 8
	s_load_dwordx2 s[26:27], s[26:27], 0x100
	v_lshlrev_b32_e32 v0, 11, v47
	s_waitcnt lgkmcnt(0)
	s_add_u32 s26, s26, s8
	s_addc_u32 s27, s27, s9
	v_lshl_add_u64 v[18:19], s[26:27], 0, v[0:1]
	v_lshl_add_u64 v[18:19], v[28:29], 2, v[18:19]
	v_add_co_u32_e32 v18, vcc, 0x169f0000, v18
	v_cvt_pk_bf16_f32 v0, v6, s0
	s_nop 0
	v_addc_co_u32_e32 v19, vcc, 0, v19, vcc
	global_store_dword v[18:19], v6, off
	v_lshlrev_b32_e32 v18, 5, v47
	v_and_b32_e32 v18, 0xe00, v18
	v_add_u32_e32 v18, v18, v28
	s_movk_i32 s0, 0x1080
	v_mad_u64_u32 v[18:19], s[26:27], v18, s0, v[10:11]
	v_add_co_u32_e32 v18, vcc, 0x1c64e000, v18
	s_xor_b64 s[26:27], exec, -1
	s_nop 0
	v_addc_co_u32_e32 v19, vcc, 0, v19, vcc
	global_store_short v[18:19], v0, off

.LBB0_1121:
	s_or_saveexec_b64 s[12:13], s[12:13]
	v_mul_u32_u24_e32 v36, 0x3800, v46
	s_xor_b64 exec, exec, s[12:13]
	s_cbranch_execz .LBB0_1123
	v_mul_f32_e32 v0, 0xbfb8aa3b, v6
	v_exp_f32_e32 v0, v0
	v_mov_b32_e32 v37, v1
	v_add_f32_e32 v0, 1.0, v0
	v_rcp_f32_e32 v0, v0
	s_nop 0
	v_cvt_pk_bf16_f32 v0, v0, s0
	v_lshl_add_u64 v[18:19], v[20:21], 0, v[36:37]
	global_store_short v[18:19], v0, off

.LBB0_1157:
	v_mul_f32_e32 v7, 0xbfb8aa3b, v7
	v_exp_f32_e32 v7, v7
	s_nop 0
	v_add_f32_e32 v7, 1.0, v7
	v_rcp_f32_e32 v7, v7
	s_nop 0
	v_cvt_pk_bf16_f32 v47, v7, s0
	v_mov_b32_e32 v7, v1
	v_lshl_add_u64 v[36:37], v[20:21], 0, v[6:7]
	global_store_short v[36:37], v47, off
	s_or_b64 exec, exec, s[12:13]
	s_and_saveexec_b64 s[12:13], s[40:41]
	s_xor_b64 s[12:13], exec, s[12:13]
	s_cbranch_execnz .LBB0_1199

.LBB0_1159:
	v_mul_f32_e32 v2, 0xbfb8aa3b, v3
	v_exp_f32_e32 v2, v2
	s_nop 0
	v_add_f32_e32 v2, 1.0, v2
	v_rcp_f32_e32 v2, v2
	s_nop 0
	v_mov_b32_e32 v7, v1
	v_cvt_pk_bf16_f32 v36, v2, s0
	v_lshl_add_u64 v[2:3], s[6:7], 0, v[6:7]
	v_lshl_add_u64 v[2:3], v[18:19], 1, v[2:3]
	global_store_short v[2:3], v36, off

.LBB0_1174:
	v_mul_f32_e32 v3, 0xbfb8aa3b, v8
	v_exp_f32_e32 v3, v3
	s_nop 0
	v_add_f32_e32 v3, 1.0, v3
	v_rcp_f32_e32 v3, v3
	s_nop 0
	v_cvt_pk_bf16_f32 v7, v3, s0
	v_mov_b32_e32 v3, v1
	v_lshl_add_u64 v[36:37], v[20:21], 0, v[2:3]
	global_store_short v[36:37], v7, off
	s_or_b64 exec, exec, s[12:13]
	s_and_saveexec_b64 s[12:13], s[40:41]
	s_xor_b64 s[12:13], exec, s[12:13]
	s_cbranch_execnz .LBB0_1217

.LBB0_1176:
	v_mul_f32_e32 v3, 0xbfb8aa3b, v4
	v_exp_f32_e32 v3, v3
	s_nop 0
	v_add_f32_e32 v3, 1.0, v3
	v_rcp_f32_e32 v3, v3
	s_nop 0
	v_cvt_pk_bf16_f32 v4, v3, s0
	v_mov_b32_e32 v3, v1
	v_lshl_add_u64 v[2:3], s[6:7], 0, v[2:3]
	v_lshl_add_u64 v[2:3], v[18:19], 1, v[2:3]
	global_store_short v[2:3], v4, off

.LBB0_1191:
	v_mul_f32_e32 v3, 0xbfb8aa3b, v9
	v_exp_f32_e32 v3, v3
	s_nop 0
	v_add_f32_e32 v3, 1.0, v3
	v_rcp_f32_e32 v3, v3
	s_nop 0
	v_cvt_pk_bf16_f32 v8, v3, s0
	v_mov_b32_e32 v3, v1
	v_lshl_add_u64 v[6:7], v[20:21], 0, v[2:3]
	global_store_short v[6:7], v8, off
	s_or_b64 exec, exec, s[4:5]
	s_and_saveexec_b64 s[4:5], s[40:41]
	s_xor_b64 s[4:5], exec, s[4:5]
	s_cbranch_execnz .LBB0_1235

.LBB0_1262:
	v_mul_f32_e32 v0, 0xbfb8aa3b, v5
	v_exp_f32_e32 v0, v0
	s_nop 0
	v_add_f32_e32 v0, 1.0, v0
	v_rcp_f32_e32 v0, v0
	s_nop 0
	v_mov_b32_e32 v3, v1
	v_lshl_add_u64 v[2:3], s[6:7], 0, v[2:3]
	v_cvt_pk_bf16_f32 v0, v0, s0
	v_lshl_add_u64 v[2:3], v[18:19], 1, v[2:3]
	global_store_short v[2:3], v0, off
	s_branch .LBB0_1100
